# v77 + byte-phase placement: every 32-MFMA block of the GEMM K-loops starts 8-byte aligned (9 s_nop 0 ahead of section-closing waits)
# speedup vs baseline: 1.0032x; 1.0032x over previous
; #define PG8_STAGE(bufoff, gbase, voff) do { _Pragma("unroll") for (int _i = 0; _i < 2; ++_i) \
;         __builtin_amdgcn_global_load_lds((const unsigned*)((const char*)(gbase) + (voff)[_i]), (LAS unsigned*)(lds + (bufoff) + ldsw + _i * 8192), 16, 0, 0); } while (0)
; #define PG8_LDA(dst, b, h) do { _Pragma("unroll") for (int m = 0; m < 4; ++m) _Pragma("unroll") for (int k = 0; k < 2; ++k) dst[m][k] = *(const LAS bf16x8*)(lds + PG8_SA(b, h) + aoff + m * 2048 + k * 1024); } while (0)
; #define PG8_LDB(dst, b, h) do { _Pragma("unroll") for (int n = 0; n < 2; ++n) _Pragma("unroll") for (int k = 0; k < 2; ++k) dst[n][k] = *(const LAS bf16x8*)(lds + PG8_SB(b, h) + boff + n * 2048 + k * 1024); } while (0)
; #define PG8_MMA(ai, bj, At, Bt) do { __builtin_amdgcn_s_setprio(1); _Pragma("unroll") for (int m = 0; m < 4; ++m) _Pragma("unroll") for (int n = 0; n < 2; ++n) _Pragma("unroll") for (int k = 0; k < 2; ++k) \
;         acc[ai][bj][m][n] = __builtin_amdgcn_mfma_f32_16x16x32_bf16(Bt[n][k], At[m][k], acc[ai][bj][m][n], 0, 0, 0); __builtin_amdgcn_s_setprio(0); } while (0)
; #define PG8_WAIT_V(n) asm volatile("s_waitcnt vmcnt(" #n ")" ::: "memory")
; #define PG8_WAIT_L(n) asm volatile("s_waitcnt lgkmcnt(" #n ")" ::: "memory")
; #define PG8_BAR __builtin_amdgcn_s_barrier()
; #define PG8_SCHED __builtin_amdgcn_sched_barrier(0)
; template <class Epi, bool ALIGN_EPI = PG8_ALIGN, bool SP2 = PG8_SP2>
; __device__ __forceinline__ void gemm_phase(LAS uchar* lds, const Gemm g, const StaticOrder& S, const Epi& E) {
;     ...
;             PG8_WAIT_V(8); PG8_WAIT_L(0); PG8_BAR; PG8_MMA(1, 0, At, B0); PG8_MMA(1, 1, At, B1); PG8_BAR; PG8_SCHED;
;             PG8_LDB(B0, 1, 0); PG8_LDB(B1, 1, 1); PG8_SCHED; PG8_LDA(At, 1, 0); PG8_STAGE(PG8_SA(0, 1), a2 + hstepA, voffA);
;             PG8_WAIT_V(8); PG8_WAIT_L(0); PG8_BAR; PG8_MMA(0, 0, At, B0); PG8_MMA(0, 1, At, B1); PG8_BAR; PG8_SCHED;
.Lrw_done_345_1_pl:
	s_waitcnt lgkmcnt(0)
	s_nop 0
	s_setprio 1
	s_barrier
	v_mfma_f32_16x16x32_bf16 v[62:65], v[164:167], v[204:207], 0
	v_mfma_f32_16x16x32_bf16 v[58:61], v[176:179], v[204:207], 0
	v_mfma_f32_16x16x32_bf16 v[54:57], v[164:167], v[212:215], 0
	v_mfma_f32_16x16x32_bf16 v[46:49], v[176:179], v[212:215], 0
	v_mfma_f32_16x16x32_bf16 v[38:41], v[164:167], v[220:223], 0
	v_mfma_f32_16x16x32_bf16 v[30:33], v[176:179], v[220:223], 0
	v_mfma_f32_16x16x32_bf16 v[22:25], v[164:167], v[228:231], 0
	v_mfma_f32_16x16x32_bf16 v[14:17], v[176:179], v[228:231], 0
	v_mfma_f32_16x16x32_bf16 v[62:65], v[172:175], v[208:211], v[62:65]
	v_mfma_f32_16x16x32_bf16 v[58:61], v[184:187], v[208:211], v[58:61]
	v_mfma_f32_16x16x32_bf16 v[54:57], v[172:175], v[216:219], v[54:57]
	v_mfma_f32_16x16x32_bf16 v[46:49], v[184:187], v[216:219], v[46:49]
	v_mfma_f32_16x16x32_bf16 v[38:41], v[172:175], v[224:227], v[38:41]
	v_mfma_f32_16x16x32_bf16 v[30:33], v[184:187], v[224:227], v[30:33]
	v_mfma_f32_16x16x32_bf16 v[22:25], v[172:175], v[232:235], v[22:25]
	v_mfma_f32_16x16x32_bf16 v[14:17], v[184:187], v[232:235], v[14:17]
	v_mfma_f32_16x16x32_bf16 v[50:53], v[188:191], v[204:207], 0
	v_mfma_f32_16x16x32_bf16 v[42:45], v[196:199], v[204:207], 0
	v_mfma_f32_16x16x32_bf16 v[34:37], v[188:191], v[212:215], 0
	v_mfma_f32_16x16x32_bf16 v[26:29], v[196:199], v[212:215], 0
	v_mfma_f32_16x16x32_bf16 v[18:21], v[188:191], v[220:223], 0
	v_mfma_f32_16x16x32_bf16 v[10:13], v[196:199], v[220:223], 0
	v_mfma_f32_16x16x32_bf16 v[6:9], v[188:191], v[228:231], 0
	v_mfma_f32_16x16x32_bf16 v[2:5], v[196:199], v[228:231], 0
	v_mfma_f32_16x16x32_bf16 v[50:53], v[192:195], v[208:211], v[50:53]
	v_mfma_f32_16x16x32_bf16 v[42:45], v[200:203], v[208:211], v[42:45]
	v_mfma_f32_16x16x32_bf16 v[34:37], v[192:195], v[216:219], v[34:37]
	v_mfma_f32_16x16x32_bf16 v[26:29], v[200:203], v[216:219], v[26:29]
	v_mfma_f32_16x16x32_bf16 v[18:21], v[192:195], v[224:227], v[18:21]
	v_mfma_f32_16x16x32_bf16 v[10:13], v[200:203], v[224:227], v[10:13]
	v_mfma_f32_16x16x32_bf16 v[6:9], v[192:195], v[232:235], v[6:9]
	v_mfma_f32_16x16x32_bf16 v[2:5], v[200:203], v[232:235], v[2:5]
	s_barrier
	s_setprio 0
	s_add_i32 s41, 0, 0x18000
	s_add_i32 s42, 0, 0x1c000
	v_add_u32_e32 v184, s41, v139
	v_add_u32_e32 v200, s42, v139
	ds_read_b128 v[164:167], v184
	ds_read_b128 v[172:175], v184 offset:1024
	ds_read_b128 v[176:179], v184 offset:2048
	ds_read_b128 v[184:187], v184 offset:3072
	ds_read_b128 v[188:191], v200
	ds_read_b128 v[192:195], v200 offset:1024
	ds_read_b128 v[196:199], v200 offset:2048
	ds_read_b128 v[200:203], v200 offset:3072
	s_add_u32 s16, s20, 0x44000
	s_addc_u32 s17, s21, 0
	s_mov_b32 m0, s27
	v_lshl_add_u64 v[240:241], s[16:17], 0, v[156:157]
	ds_read_b128 v[204:207], v171 offset:32768
	ds_read_b128 v[208:211], v171 offset:33792
	ds_read_b128 v[212:215], v171 offset:34816
	ds_read_b128 v[216:219], v171 offset:35840
	ds_read_b128 v[220:223], v171 offset:36864
	ds_read_b128 v[224:227], v171 offset:37888
	ds_read_b128 v[228:231], v171 offset:38912
	ds_read_b128 v[232:235], v171 offset:39936
	global_load_lds_dwordx4 v[240:241], off
	s_mov_b32 m0, s28
	v_lshl_add_u64 v[240:241], s[16:17], 0, v[132:133]
	global_load_lds_dwordx4 v[240:241], off
	s_setprio 1
	s_waitcnt vmcnt(8) lgkmcnt(0)
	s_barrier
	v_mfma_f32_16x16x32_bf16 v[126:129], v[164:167], v[204:207], v[126:129]
	v_mfma_f32_16x16x32_bf16 v[122:125], v[176:179], v[204:207], v[122:125]
	v_mfma_f32_16x16x32_bf16 v[118:121], v[164:167], v[212:215], v[118:121]
	v_mfma_f32_16x16x32_bf16 v[110:113], v[176:179], v[212:215], v[110:113]
	v_mfma_f32_16x16x32_bf16 v[102:105], v[164:167], v[220:223], v[102:105]
	v_mfma_f32_16x16x32_bf16 v[94:97], v[176:179], v[220:223], v[94:97]
	v_mfma_f32_16x16x32_bf16 v[86:89], v[164:167], v[228:231], v[86:89]
	v_mfma_f32_16x16x32_bf16 v[78:81], v[176:179], v[228:231], v[78:81]
	v_mfma_f32_16x16x32_bf16 v[126:129], v[172:175], v[208:211], v[126:129]
	v_mfma_f32_16x16x32_bf16 v[122:125], v[184:187], v[208:211], v[122:125]
	v_mfma_f32_16x16x32_bf16 v[118:121], v[172:175], v[216:219], v[118:121]
	v_mfma_f32_16x16x32_bf16 v[110:113], v[184:187], v[216:219], v[110:113]
	v_mfma_f32_16x16x32_bf16 v[102:105], v[172:175], v[224:227], v[102:105]
	v_mfma_f32_16x16x32_bf16 v[94:97], v[184:187], v[224:227], v[94:97]
	v_mfma_f32_16x16x32_bf16 v[86:89], v[172:175], v[232:235], v[86:89]
	v_mfma_f32_16x16x32_bf16 v[78:81], v[184:187], v[232:235], v[78:81]
	v_mfma_f32_16x16x32_bf16 v[114:117], v[188:191], v[204:207], v[114:117]
	v_mfma_f32_16x16x32_bf16 v[106:109], v[196:199], v[204:207], v[106:109]
	v_mfma_f32_16x16x32_bf16 v[98:101], v[188:191], v[212:215], v[98:101]
	v_mfma_f32_16x16x32_bf16 v[90:93], v[196:199], v[212:215], v[90:93]
	v_mfma_f32_16x16x32_bf16 v[82:85], v[188:191], v[220:223], v[82:85]
	v_mfma_f32_16x16x32_bf16 v[74:77], v[196:199], v[220:223], v[74:77]
	v_mfma_f32_16x16x32_bf16 v[70:73], v[188:191], v[228:231], v[70:73]
	v_mfma_f32_16x16x32_bf16 v[66:69], v[196:199], v[228:231], v[66:69]
	v_mfma_f32_16x16x32_bf16 v[114:117], v[192:195], v[208:211], v[114:117]
	v_mfma_f32_16x16x32_bf16 v[106:109], v[200:203], v[208:211], v[106:109]
	v_mfma_f32_16x16x32_bf16 v[98:101], v[192:195], v[216:219], v[98:101]
	v_mfma_f32_16x16x32_bf16 v[90:93], v[200:203], v[216:219], v[90:93]
	v_mfma_f32_16x16x32_bf16 v[82:85], v[192:195], v[224:227], v[82:85]
	v_mfma_f32_16x16x32_bf16 v[74:77], v[200:203], v[224:227], v[74:77]
	v_mfma_f32_16x16x32_bf16 v[70:73], v[192:195], v[232:235], v[70:73]
	v_mfma_f32_16x16x32_bf16 v[66:69], v[200:203], v[232:235], v[66:69]
	s_barrier
; #define PG8_STAGE(bufoff, gbase, voff) do { _Pragma("unroll") for (int _i = 0; _i < 2; ++_i) \
;         __builtin_amdgcn_global_load_lds((const unsigned*)((const char*)(gbase) + (voff)[_i]), (LAS unsigned*)(lds + (bufoff) + ldsw + _i * 8192), 16, 0, 0); } while (0)
; #define PG8_LDA(dst, b, h) do { _Pragma("unroll") for (int m = 0; m < 4; ++m) _Pragma("unroll") for (int k = 0; k < 2; ++k) dst[m][k] = *(const LAS bf16x8*)(lds + PG8_SA(b, h) + aoff + m * 2048 + k * 1024); } while (0)
; #define PG8_LDB(dst, b, h) do { _Pragma("unroll") for (int n = 0; n < 2; ++n) _Pragma("unroll") for (int k = 0; k < 2; ++k) dst[n][k] = *(const LAS bf16x8*)(lds + PG8_SB(b, h) + boff + n * 2048 + k * 1024); } while (0)
; #define PG8_BAR __builtin_amdgcn_s_barrier()
; template <class Epi, bool ALIGN_EPI = PG8_ALIGN, bool SP2 = PG8_SP2>
; __device__ __forceinline__ void gemm_phase(LAS uchar* lds, const Gemm g, const StaticOrder& S, const Epi& E) {
;     ...
;         for (int t = tb; t < tb + tblk; t += 2) {
;             const bool last = (t == nt - 2);
;             const char* a1 = cA + (size_t)(t + 1) * kstep;
;             const char* a2 = last ? nA : cA + (size_t)(t + 2) * kstep; const char* b2 = last ? nB : cB + (size_t)(t + 2) * kstep;
;             const char* a3 = a2 + kstep; const char* b3 = b2 + kstep;
;             if constexpr (SP2) {
;             PG8_LDB(B0, 0, 0); PG8_LDB(B1, 0, 1); PG8_SCHED; PG8_LDA(At, 0, 0); PG8_STAGE(PG8_SA(1, 1), a1 + hstepA, voffA);
;             PG8_WAIT_V(8); PG8_WAIT_L(0); PG8_BAR; PG8_MMA(0, 0, At, B0); PG8_MMA(0, 1, At, B1); PG8_BAR; PG8_SCHED;
;             PG8_LDA(At, 0, 1); PG8_STAGE(PG8_SB(0, 0), b2, voffB); PG8_STAGE(PG8_SB(0, 1), b2 + hstepB, voffB); PG8_STAGE(PG8_SA(0, 0), a2, voffA);
;             PG8_WAIT_V(8); PG8_WAIT_L(0); PG8_BAR; PG8_MMA(1, 0, At, B0); PG8_MMA(1, 1, At, B1); PG8_BAR; PG8_SCHED;
;             PG8_LDB(B0, 1, 0); PG8_LDB(B1, 1, 1); PG8_SCHED; PG8_LDA(At, 1, 0); PG8_STAGE(PG8_SA(0, 1), a2 + hstepA, voffA);
;             PG8_WAIT_V(8); PG8_WAIT_L(0); PG8_BAR; PG8_MMA(0, 0, At, B0); PG8_MMA(0, 1, At, B1); PG8_BAR; PG8_SCHED;
;             PG8_LDA(At, 1, 1); PG8_STAGE(PG8_SB(1, 0), b3, voffB); PG8_STAGE(PG8_SB(1, 1), b3 + hstepB, voffB); PG8_STAGE(PG8_SA(1, 0), a3, voffA);
;             PG8_WAIT_V(8); PG8_WAIT_L(0); PG8_BAR; PG8_MMA(1, 0, At, B0); PG8_MMA(1, 1, At, B1); PG8_BAR; PG8_SCHED;
	s_setprio 0
	s_add_i32 s16, s41, s23
	v_lshl_add_u64 v[168:169], v[168:169], 0, s[84:85]
	s_mov_b32 m0, s16
	ds_read_b128 v[204:207], v171 offset:49152
	ds_read_b128 v[208:211], v171 offset:50176
	ds_read_b128 v[212:215], v171 offset:51200
	ds_read_b128 v[216:219], v171 offset:52224
	ds_read_b128 v[220:223], v171 offset:53248
	ds_read_b128 v[224:227], v171 offset:54272
	ds_read_b128 v[228:231], v171 offset:55296
	ds_read_b128 v[232:235], v171 offset:56320
	global_load_lds_dwordx4 v[168:169], off
	s_add_i32 m0, s16, 0x2000
	s_add_u32 s4, s4, 0x44080
	v_lshl_add_u64 v[168:169], v[180:181], 0, s[84:85]
	s_addc_u32 s5, s5, 0
	s_add_i32 s16, s42, s23
	global_load_lds_dwordx4 v[168:169], off
	s_mov_b32 m0, s16
	v_lshl_add_u64 v[168:169], s[4:5], 0, v[134:135]
	global_load_lds_dwordx4 v[168:169], off
	s_add_i32 m0, s16, 0x2000
	v_lshl_add_u64 v[168:169], s[4:5], 0, v[130:131]
	global_load_lds_dwordx4 v[168:169], off
	s_mov_b32 m0, s29
	v_lshl_add_u64 v[168:169], v[236:237], 0, s[84:85]
	global_load_lds_dwordx4 v[168:169], off
	s_mov_b32 m0, s30
	v_lshl_add_u64 v[168:169], v[238:239], 0, s[84:85]
	global_load_lds_dwordx4 v[168:169], off
	s_setprio 1
	s_waitcnt vmcnt(8) lgkmcnt(0)
	s_barrier
	v_mfma_f32_16x16x32_bf16 v[62:65], v[164:167], v[204:207], v[62:65]
	v_mfma_f32_16x16x32_bf16 v[58:61], v[176:179], v[204:207], v[58:61]
	v_mfma_f32_16x16x32_bf16 v[54:57], v[164:167], v[212:215], v[54:57]
	v_mfma_f32_16x16x32_bf16 v[46:49], v[176:179], v[212:215], v[46:49]
	v_mfma_f32_16x16x32_bf16 v[38:41], v[164:167], v[220:223], v[38:41]
	v_mfma_f32_16x16x32_bf16 v[30:33], v[176:179], v[220:223], v[30:33]
	v_mfma_f32_16x16x32_bf16 v[22:25], v[164:167], v[228:231], v[22:25]
	v_mfma_f32_16x16x32_bf16 v[14:17], v[176:179], v[228:231], v[14:17]
	v_mfma_f32_16x16x32_bf16 v[62:65], v[172:175], v[208:211], v[62:65]
	v_mfma_f32_16x16x32_bf16 v[58:61], v[184:187], v[208:211], v[58:61]
	v_mfma_f32_16x16x32_bf16 v[54:57], v[172:175], v[216:219], v[54:57]
	v_mfma_f32_16x16x32_bf16 v[46:49], v[184:187], v[216:219], v[46:49]
	v_mfma_f32_16x16x32_bf16 v[38:41], v[172:175], v[224:227], v[38:41]
	v_mfma_f32_16x16x32_bf16 v[30:33], v[184:187], v[224:227], v[30:33]
	v_mfma_f32_16x16x32_bf16 v[22:25], v[172:175], v[232:235], v[22:25]
	v_mfma_f32_16x16x32_bf16 v[14:17], v[184:187], v[232:235], v[14:17]
	v_mfma_f32_16x16x32_bf16 v[50:53], v[188:191], v[204:207], v[50:53]
	v_mfma_f32_16x16x32_bf16 v[42:45], v[196:199], v[204:207], v[42:45]
	v_mfma_f32_16x16x32_bf16 v[34:37], v[188:191], v[212:215], v[34:37]
	v_mfma_f32_16x16x32_bf16 v[26:29], v[196:199], v[212:215], v[26:29]
	v_mfma_f32_16x16x32_bf16 v[18:21], v[188:191], v[220:223], v[18:21]
	v_mfma_f32_16x16x32_bf16 v[10:13], v[196:199], v[220:223], v[10:13]
	v_mfma_f32_16x16x32_bf16 v[6:9], v[188:191], v[228:231], v[6:9]
	v_mfma_f32_16x16x32_bf16 v[2:5], v[196:199], v[228:231], v[2:5]
	v_mfma_f32_16x16x32_bf16 v[50:53], v[192:195], v[208:211], v[50:53]
	v_mfma_f32_16x16x32_bf16 v[42:45], v[200:203], v[208:211], v[42:45]
	v_mfma_f32_16x16x32_bf16 v[34:37], v[192:195], v[216:219], v[34:37]
	v_mfma_f32_16x16x32_bf16 v[26:29], v[200:203], v[216:219], v[26:29]
	v_mfma_f32_16x16x32_bf16 v[18:21], v[192:195], v[224:227], v[18:21]
	v_mfma_f32_16x16x32_bf16 v[10:13], v[200:203], v[224:227], v[10:13]
	v_mfma_f32_16x16x32_bf16 v[6:9], v[192:195], v[232:235], v[6:9]
	v_mfma_f32_16x16x32_bf16 v[2:5], v[200:203], v[232:235], v[2:5]
	s_barrier
	s_setprio 0
	s_add_i32 s40, s40, 2
	s_add_u32 s38, s38, 0x100
	s_addc_u32 s39, s39, 0
	s_cmp_gt_u32 s40, 13
	s_mov_b64 s[16:17], s[18:19]
.LBB0_345:
	s_add_u32 s18, s16, 0x100
	s_addc_u32 s19, s17, 0
	s_add_i32 s41, 0, 0x10000
	s_cmp_eq_u32 s40, 12
	s_cselect_b32 s21, s7, s19
	s_cselect_b32 s20, s6, s18
	v_add_u32_e32 v168, s41, v139
	s_cselect_b32 s5, s15, s39
	s_cselect_b32 s4, s14, s38
	s_add_i32 s42, 0, 0x14000
	ds_read_b128 v[164:167], v168
	ds_read_b128 v[172:175], v168 offset:1024
	ds_read_b128 v[176:179], v168 offset:2048
	ds_read_b128 v[184:187], v168 offset:3072
	v_add_u32_e32 v168, s42, v139
	ds_read_b128 v[188:191], v168
	ds_read_b128 v[192:195], v168 offset:1024
	ds_read_b128 v[196:199], v168 offset:2048
	ds_read_b128 v[200:203], v168 offset:3072
	v_lshl_add_u64 v[168:169], s[16:17], 0, v[160:161]
	s_add_i32 m0, s25, 0xc000
	ds_read_b128 v[204:207], v171
	ds_read_b128 v[208:211], v171 offset:1024
	ds_read_b128 v[212:215], v171 offset:2048
	ds_read_b128 v[216:219], v171 offset:3072
	ds_read_b128 v[220:223], v171 offset:4096
	ds_read_b128 v[224:227], v171 offset:5120
	ds_read_b128 v[228:231], v171 offset:6144
	ds_read_b128 v[232:235], v171 offset:7168
	global_load_lds_dwordx4 v[168:169], off
	s_add_i32 m0, s25, 0xe000
	v_lshl_add_u64 v[168:169], s[16:17], 0, v[162:163]
	global_load_lds_dwordx4 v[168:169], off
	s_nop 0
	s_setprio 1
	s_waitcnt vmcnt(8) lgkmcnt(0)
	s_barrier
; #define PG8_STAGE(bufoff, gbase, voff) do { _Pragma("unroll") for (int _i = 0; _i < 2; ++_i) \
;         __builtin_amdgcn_global_load_lds((const unsigned*)((const char*)(gbase) + (voff)[_i]), (LAS unsigned*)(lds + (bufoff) + ldsw + _i * 8192), 16, 0, 0); } while (0)
; #define PG8_LDA(dst, b, h) do { _Pragma("unroll") for (int m = 0; m < 4; ++m) _Pragma("unroll") for (int k = 0; k < 2; ++k) dst[m][k] = *(const LAS bf16x8*)(lds + PG8_SA(b, h) + aoff + m * 2048 + k * 1024); } while (0)
; #define PG8_LDB(dst, b, h) do { _Pragma("unroll") for (int n = 0; n < 2; ++n) _Pragma("unroll") for (int k = 0; k < 2; ++k) dst[n][k] = *(const LAS bf16x8*)(lds + PG8_SB(b, h) + boff + n * 2048 + k * 1024); } while (0)
; #define PG8_MMA(ai, bj, At, Bt) do { __builtin_amdgcn_s_setprio(1); _Pragma("unroll") for (int m = 0; m < 4; ++m) _Pragma("unroll") for (int n = 0; n < 2; ++n) _Pragma("unroll") for (int k = 0; k < 2; ++k) \
;         acc[ai][bj][m][n] = __builtin_amdgcn_mfma_f32_16x16x32_bf16(Bt[n][k], At[m][k], acc[ai][bj][m][n], 0, 0, 0); __builtin_amdgcn_s_setprio(0); } while (0)
; #define PG8_WAIT_V(n) asm volatile("s_waitcnt vmcnt(" #n ")" ::: "memory")
; template <class Epi, bool ALIGN_EPI = PG8_ALIGN, bool SP2 = PG8_SP2>
; __device__ __forceinline__ void gemm_phase(LAS uchar* lds, const Gemm g, const StaticOrder& S, const Epi& E) {
;     ...
;             PG8_LDB(B0, 0, 0); PG8_LDB(B1, 0, 1); PG8_SCHED; PG8_LDA(At, 0, 0); PG8_STAGE(PG8_SA(1, 1), a1 + hstepA, voffA);
;             PG8_WAIT_V(8); PG8_WAIT_L(0); PG8_BAR; PG8_MMA(0, 0, At, B0); PG8_MMA(0, 1, At, B1); PG8_BAR; PG8_SCHED;
;             PG8_LDA(At, 0, 1); PG8_STAGE(PG8_SB(0, 0), b2, voffB); PG8_STAGE(PG8_SB(0, 1), b2 + hstepB, voffB); PG8_STAGE(PG8_SA(0, 0), a2, voffA);
;             PG8_WAIT_V(8); PG8_WAIT_L(0); PG8_BAR; PG8_MMA(1, 0, At, B0); PG8_MMA(1, 1, At, B1); PG8_BAR; PG8_SCHED;
;             PG8_LDB(B0, 1, 0); PG8_LDB(B1, 1, 1); PG8_SCHED; PG8_LDA(At, 1, 0); PG8_STAGE(PG8_SA(0, 1), a2 + hstepA, voffA);
;             PG8_WAIT_V(8); PG8_WAIT_L(0); PG8_BAR; PG8_MMA(0, 0, At, B0); PG8_MMA(0, 1, At, B1); PG8_BAR; PG8_SCHED;
;             PG8_LDA(At, 1, 1); PG8_STAGE(PG8_SB(1, 0), b3, voffB); PG8_STAGE(PG8_SB(1, 1), b3 + hstepB, voffB); PG8_STAGE(PG8_SA(1, 0), a3, voffA);
;             PG8_WAIT_V(8); PG8_WAIT_L(0); PG8_BAR; PG8_MMA(1, 0, At, B0); PG8_MMA(1, 1, At, B1); PG8_BAR; PG8_SCHED;
	v_mfma_f32_16x16x32_bf16 v[126:129], v[164:167], v[204:207], v[126:129]
	v_mfma_f32_16x16x32_bf16 v[122:125], v[176:179], v[204:207], v[122:125]
	v_mfma_f32_16x16x32_bf16 v[118:121], v[164:167], v[212:215], v[118:121]
	v_mfma_f32_16x16x32_bf16 v[110:113], v[176:179], v[212:215], v[110:113]
	v_mfma_f32_16x16x32_bf16 v[102:105], v[164:167], v[220:223], v[102:105]
	v_mfma_f32_16x16x32_bf16 v[94:97], v[176:179], v[220:223], v[94:97]
	v_mfma_f32_16x16x32_bf16 v[86:89], v[164:167], v[228:231], v[86:89]
	v_mfma_f32_16x16x32_bf16 v[78:81], v[176:179], v[228:231], v[78:81]
	v_mfma_f32_16x16x32_bf16 v[126:129], v[172:175], v[208:211], v[126:129]
	v_mfma_f32_16x16x32_bf16 v[122:125], v[184:187], v[208:211], v[122:125]
	v_mfma_f32_16x16x32_bf16 v[118:121], v[172:175], v[216:219], v[118:121]
	v_mfma_f32_16x16x32_bf16 v[110:113], v[184:187], v[216:219], v[110:113]
	v_mfma_f32_16x16x32_bf16 v[102:105], v[172:175], v[224:227], v[102:105]
	v_mfma_f32_16x16x32_bf16 v[94:97], v[184:187], v[224:227], v[94:97]
	v_mfma_f32_16x16x32_bf16 v[86:89], v[172:175], v[232:235], v[86:89]
	v_mfma_f32_16x16x32_bf16 v[78:81], v[184:187], v[232:235], v[78:81]
	v_mfma_f32_16x16x32_bf16 v[114:117], v[188:191], v[204:207], v[114:117]
	v_mfma_f32_16x16x32_bf16 v[106:109], v[196:199], v[204:207], v[106:109]
	v_mfma_f32_16x16x32_bf16 v[98:101], v[188:191], v[212:215], v[98:101]
	v_mfma_f32_16x16x32_bf16 v[90:93], v[196:199], v[212:215], v[90:93]
	v_mfma_f32_16x16x32_bf16 v[82:85], v[188:191], v[220:223], v[82:85]
	v_mfma_f32_16x16x32_bf16 v[74:77], v[196:199], v[220:223], v[74:77]
	v_mfma_f32_16x16x32_bf16 v[70:73], v[188:191], v[228:231], v[70:73]
	v_mfma_f32_16x16x32_bf16 v[66:69], v[196:199], v[228:231], v[66:69]
	v_mfma_f32_16x16x32_bf16 v[114:117], v[192:195], v[208:211], v[114:117]
	v_mfma_f32_16x16x32_bf16 v[106:109], v[200:203], v[208:211], v[106:109]
	v_mfma_f32_16x16x32_bf16 v[98:101], v[192:195], v[216:219], v[98:101]
	v_mfma_f32_16x16x32_bf16 v[90:93], v[200:203], v[216:219], v[90:93]
	v_mfma_f32_16x16x32_bf16 v[82:85], v[192:195], v[224:227], v[82:85]
	v_mfma_f32_16x16x32_bf16 v[74:77], v[200:203], v[224:227], v[74:77]
	v_mfma_f32_16x16x32_bf16 v[70:73], v[192:195], v[232:235], v[70:73]
	v_mfma_f32_16x16x32_bf16 v[66:69], v[200:203], v[232:235], v[66:69]
	s_barrier
	s_setprio 0
	s_add_i32 s16, s41, s23
	v_lshl_add_u64 v[168:169], s[4:5], 0, v[134:135]
	s_mov_b32 m0, s16
	ds_read_b128 v[204:207], v171 offset:16384
	ds_read_b128 v[208:211], v171 offset:17408
	ds_read_b128 v[212:215], v171 offset:18432
	ds_read_b128 v[216:219], v171 offset:19456
	ds_read_b128 v[220:223], v171 offset:20480
	ds_read_b128 v[224:227], v171 offset:21504
	ds_read_b128 v[228:231], v171 offset:22528
	ds_read_b128 v[232:235], v171 offset:23552
	global_load_lds_dwordx4 v[168:169], off
	s_add_i32 m0, s16, 0x2000
	s_add_u32 s16, s4, 0x44000
	v_lshl_add_u64 v[180:181], s[4:5], 0, v[130:131]
	s_addc_u32 s17, s5, 0
	s_add_i32 s41, s42, s23
	global_load_lds_dwordx4 v[180:181], off
	v_lshl_add_u64 v[236:237], s[16:17], 0, v[134:135]
	s_mov_b32 m0, s41
	global_load_lds_dwordx4 v[236:237], off
	s_add_i32 m0, s41, 0x2000
	v_lshl_add_u64 v[236:237], s[16:17], 0, v[130:131]
	global_load_lds_dwordx4 v[236:237], off
	s_mov_b32 m0, s25
	v_lshl_add_u64 v[236:237], s[20:21], 0, v[156:157]
	global_load_lds_dwordx4 v[236:237], off
	s_mov_b32 m0, s26
	v_lshl_add_u64 v[238:239], s[20:21], 0, v[132:133]
	global_load_lds_dwordx4 v[238:239], off
	s_setprio 1
	s_waitcnt vmcnt(8) lgkmcnt(0)
	s_barrier
	v_mfma_f32_16x16x32_bf16 v[62:65], v[164:167], v[204:207], v[62:65]
	v_mfma_f32_16x16x32_bf16 v[58:61], v[176:179], v[204:207], v[58:61]
	v_mfma_f32_16x16x32_bf16 v[54:57], v[164:167], v[212:215], v[54:57]
	v_mfma_f32_16x16x32_bf16 v[46:49], v[176:179], v[212:215], v[46:49]
	v_mfma_f32_16x16x32_bf16 v[38:41], v[164:167], v[220:223], v[38:41]
	v_mfma_f32_16x16x32_bf16 v[30:33], v[176:179], v[220:223], v[30:33]
	v_mfma_f32_16x16x32_bf16 v[22:25], v[164:167], v[228:231], v[22:25]
	v_mfma_f32_16x16x32_bf16 v[14:17], v[176:179], v[228:231], v[14:17]
	v_mfma_f32_16x16x32_bf16 v[62:65], v[172:175], v[208:211], v[62:65]
	v_mfma_f32_16x16x32_bf16 v[58:61], v[184:187], v[208:211], v[58:61]
	v_mfma_f32_16x16x32_bf16 v[54:57], v[172:175], v[216:219], v[54:57]
	v_mfma_f32_16x16x32_bf16 v[46:49], v[184:187], v[216:219], v[46:49]
	v_mfma_f32_16x16x32_bf16 v[38:41], v[172:175], v[224:227], v[38:41]
	v_mfma_f32_16x16x32_bf16 v[30:33], v[184:187], v[224:227], v[30:33]
	v_mfma_f32_16x16x32_bf16 v[22:25], v[172:175], v[232:235], v[22:25]
	v_mfma_f32_16x16x32_bf16 v[14:17], v[184:187], v[232:235], v[14:17]
	v_mfma_f32_16x16x32_bf16 v[50:53], v[188:191], v[204:207], v[50:53]
	v_mfma_f32_16x16x32_bf16 v[42:45], v[196:199], v[204:207], v[42:45]
	v_mfma_f32_16x16x32_bf16 v[34:37], v[188:191], v[212:215], v[34:37]
	v_mfma_f32_16x16x32_bf16 v[26:29], v[196:199], v[212:215], v[26:29]
	v_mfma_f32_16x16x32_bf16 v[18:21], v[188:191], v[220:223], v[18:21]
	v_mfma_f32_16x16x32_bf16 v[10:13], v[196:199], v[220:223], v[10:13]
	v_mfma_f32_16x16x32_bf16 v[6:9], v[188:191], v[228:231], v[6:9]
	v_mfma_f32_16x16x32_bf16 v[2:5], v[196:199], v[228:231], v[2:5]
	v_mfma_f32_16x16x32_bf16 v[50:53], v[192:195], v[208:211], v[50:53]
	v_mfma_f32_16x16x32_bf16 v[42:45], v[200:203], v[208:211], v[42:45]
	v_mfma_f32_16x16x32_bf16 v[34:37], v[192:195], v[216:219], v[34:37]
	v_mfma_f32_16x16x32_bf16 v[26:29], v[200:203], v[216:219], v[26:29]
	v_mfma_f32_16x16x32_bf16 v[18:21], v[192:195], v[224:227], v[18:21]
	v_mfma_f32_16x16x32_bf16 v[10:13], v[200:203], v[224:227], v[10:13]
	v_mfma_f32_16x16x32_bf16 v[6:9], v[192:195], v[232:235], v[6:9]
	v_mfma_f32_16x16x32_bf16 v[2:5], v[200:203], v[232:235], v[2:5]
	s_barrier
; #define PG8_STAGE(bufoff, gbase, voff) do { _Pragma("unroll") for (int _i = 0; _i < 2; ++_i) \
;         __builtin_amdgcn_global_load_lds((const unsigned*)((const char*)(gbase) + (voff)[_i]), (LAS unsigned*)(lds + (bufoff) + ldsw + _i * 8192), 16, 0, 0); } while (0)
; #define PG8_LDA(dst, b, h) do { _Pragma("unroll") for (int m = 0; m < 4; ++m) _Pragma("unroll") for (int k = 0; k < 2; ++k) dst[m][k] = *(const LAS bf16x8*)(lds + PG8_SA(b, h) + aoff + m * 2048 + k * 1024); } while (0)
; #define PG8_LDB(dst, b, h) do { _Pragma("unroll") for (int n = 0; n < 2; ++n) _Pragma("unroll") for (int k = 0; k < 2; ++k) dst[n][k] = *(const LAS bf16x8*)(lds + PG8_SB(b, h) + boff + n * 2048 + k * 1024); } while (0)
; #define PG8_MMA(ai, bj, At, Bt) do { __builtin_amdgcn_s_setprio(1); _Pragma("unroll") for (int m = 0; m < 4; ++m) _Pragma("unroll") for (int n = 0; n < 2; ++n) _Pragma("unroll") for (int k = 0; k < 2; ++k) \
;         acc[ai][bj][m][n] = __builtin_amdgcn_mfma_f32_16x16x32_bf16(Bt[n][k], At[m][k], acc[ai][bj][m][n], 0, 0, 0); __builtin_amdgcn_s_setprio(0); } while (0)
; #define PG8_WAIT_V(n) asm volatile("s_waitcnt vmcnt(" #n ")" ::: "memory")
; template <class Epi, bool ALIGN_EPI = PG8_ALIGN, bool SP2 = PG8_SP2>
; __device__ __forceinline__ void gemm_phase(LAS uchar* lds, const Gemm g, const StaticOrder& S, const Epi& E) {
;     ...
;             PG8_LDB(B0, 0, 0); PG8_LDB(B1, 0, 1); PG8_SCHED; PG8_LDA(At, 0, 0); PG8_STAGE(PG8_SA(1, 1), a1 + hstepA, voffA);
;             PG8_WAIT_V(8); PG8_WAIT_L(0); PG8_BAR; PG8_MMA(0, 0, At, B0); PG8_MMA(0, 1, At, B1); PG8_BAR; PG8_SCHED;
;             PG8_LDA(At, 0, 1); PG8_STAGE(PG8_SB(0, 0), b2, voffB); PG8_STAGE(PG8_SB(0, 1), b2 + hstepB, voffB); PG8_STAGE(PG8_SA(0, 0), a2, voffA);
;             PG8_WAIT_V(8); PG8_WAIT_L(0); PG8_BAR; PG8_MMA(1, 0, At, B0); PG8_MMA(1, 1, At, B1); PG8_BAR; PG8_SCHED;
;             PG8_LDB(B0, 1, 0); PG8_LDB(B1, 1, 1); PG8_SCHED; PG8_LDA(At, 1, 0); PG8_STAGE(PG8_SA(0, 1), a2 + hstepA, voffA);
;             PG8_WAIT_V(8); PG8_WAIT_L(0); PG8_BAR; PG8_MMA(0, 0, At, B0); PG8_MMA(0, 1, At, B1); PG8_BAR; PG8_SCHED;
;             PG8_LDA(At, 1, 1); PG8_STAGE(PG8_SB(1, 0), b3, voffB); PG8_STAGE(PG8_SB(1, 1), b3 + hstepB, voffB); PG8_STAGE(PG8_SA(1, 0), a3, voffA);
;             PG8_WAIT_V(8); PG8_WAIT_L(0); PG8_BAR; PG8_MMA(1, 0, At, B0); PG8_MMA(1, 1, At, B1); PG8_BAR; PG8_SCHED;
	s_setprio 0
	s_add_i32 s41, 0, 0x18000
	s_add_i32 s42, 0, 0x1c000
	v_add_u32_e32 v184, s41, v139
	v_add_u32_e32 v200, s42, v139
	ds_read_b128 v[164:167], v184
	ds_read_b128 v[172:175], v184 offset:1024
	ds_read_b128 v[176:179], v184 offset:2048
	ds_read_b128 v[184:187], v184 offset:3072
	ds_read_b128 v[188:191], v200
	ds_read_b128 v[192:195], v200 offset:1024
	ds_read_b128 v[196:199], v200 offset:2048
	ds_read_b128 v[200:203], v200 offset:3072
	s_add_u32 s16, s20, 0x44000
	s_addc_u32 s17, s21, 0
	s_mov_b32 m0, s27
	v_lshl_add_u64 v[240:241], s[16:17], 0, v[156:157]
	ds_read_b128 v[204:207], v171 offset:32768
	ds_read_b128 v[208:211], v171 offset:33792
	ds_read_b128 v[212:215], v171 offset:34816
	ds_read_b128 v[216:219], v171 offset:35840
	ds_read_b128 v[220:223], v171 offset:36864
	ds_read_b128 v[224:227], v171 offset:37888
	ds_read_b128 v[228:231], v171 offset:38912
	ds_read_b128 v[232:235], v171 offset:39936
	global_load_lds_dwordx4 v[240:241], off
	s_mov_b32 m0, s28
	v_lshl_add_u64 v[240:241], s[16:17], 0, v[132:133]
	global_load_lds_dwordx4 v[240:241], off
	s_setprio 1
	s_waitcnt vmcnt(8) lgkmcnt(0)
	s_barrier
	v_mfma_f32_16x16x32_bf16 v[126:129], v[164:167], v[204:207], v[126:129]
	v_mfma_f32_16x16x32_bf16 v[122:125], v[176:179], v[204:207], v[122:125]
	v_mfma_f32_16x16x32_bf16 v[118:121], v[164:167], v[212:215], v[118:121]
	v_mfma_f32_16x16x32_bf16 v[110:113], v[176:179], v[212:215], v[110:113]
	v_mfma_f32_16x16x32_bf16 v[102:105], v[164:167], v[220:223], v[102:105]
	v_mfma_f32_16x16x32_bf16 v[94:97], v[176:179], v[220:223], v[94:97]
	v_mfma_f32_16x16x32_bf16 v[86:89], v[164:167], v[228:231], v[86:89]
	v_mfma_f32_16x16x32_bf16 v[78:81], v[176:179], v[228:231], v[78:81]
	v_mfma_f32_16x16x32_bf16 v[126:129], v[172:175], v[208:211], v[126:129]
	v_mfma_f32_16x16x32_bf16 v[122:125], v[184:187], v[208:211], v[122:125]
	v_mfma_f32_16x16x32_bf16 v[118:121], v[172:175], v[216:219], v[118:121]
	v_mfma_f32_16x16x32_bf16 v[110:113], v[184:187], v[216:219], v[110:113]
	v_mfma_f32_16x16x32_bf16 v[102:105], v[172:175], v[224:227], v[102:105]
	v_mfma_f32_16x16x32_bf16 v[94:97], v[184:187], v[224:227], v[94:97]
	v_mfma_f32_16x16x32_bf16 v[86:89], v[172:175], v[232:235], v[86:89]
	v_mfma_f32_16x16x32_bf16 v[78:81], v[184:187], v[232:235], v[78:81]
	v_mfma_f32_16x16x32_bf16 v[114:117], v[188:191], v[204:207], v[114:117]
	v_mfma_f32_16x16x32_bf16 v[106:109], v[196:199], v[204:207], v[106:109]
	v_mfma_f32_16x16x32_bf16 v[98:101], v[188:191], v[212:215], v[98:101]
	v_mfma_f32_16x16x32_bf16 v[90:93], v[196:199], v[212:215], v[90:93]
	v_mfma_f32_16x16x32_bf16 v[82:85], v[188:191], v[220:223], v[82:85]
	v_mfma_f32_16x16x32_bf16 v[74:77], v[196:199], v[220:223], v[74:77]
	v_mfma_f32_16x16x32_bf16 v[70:73], v[188:191], v[228:231], v[70:73]
	v_mfma_f32_16x16x32_bf16 v[66:69], v[196:199], v[228:231], v[66:69]
	v_mfma_f32_16x16x32_bf16 v[114:117], v[192:195], v[208:211], v[114:117]
	v_mfma_f32_16x16x32_bf16 v[106:109], v[200:203], v[208:211], v[106:109]
	v_mfma_f32_16x16x32_bf16 v[98:101], v[192:195], v[216:219], v[98:101]
	v_mfma_f32_16x16x32_bf16 v[90:93], v[200:203], v[216:219], v[90:93]
	v_mfma_f32_16x16x32_bf16 v[82:85], v[192:195], v[224:227], v[82:85]
	v_mfma_f32_16x16x32_bf16 v[74:77], v[200:203], v[224:227], v[74:77]
	v_mfma_f32_16x16x32_bf16 v[70:73], v[192:195], v[232:235], v[70:73]
	v_mfma_f32_16x16x32_bf16 v[66:69], v[200:203], v[232:235], v[66:69]
	s_barrier
; #define PG8_STAGE(bufoff, gbase, voff) do { _Pragma("unroll") for (int _i = 0; _i < 2; ++_i) \
;         __builtin_amdgcn_global_load_lds((const unsigned*)((const char*)(gbase) + (voff)[_i]), (LAS unsigned*)(lds + (bufoff) + ldsw + _i * 8192), 16, 0, 0); } while (0)
; #define PG8_LDA(dst, b, h) do { _Pragma("unroll") for (int m = 0; m < 4; ++m) _Pragma("unroll") for (int k = 0; k < 2; ++k) dst[m][k] = *(const LAS bf16x8*)(lds + PG8_SA(b, h) + aoff + m * 2048 + k * 1024); } while (0)
; #define PG8_LDB(dst, b, h) do { _Pragma("unroll") for (int n = 0; n < 2; ++n) _Pragma("unroll") for (int k = 0; k < 2; ++k) dst[n][k] = *(const LAS bf16x8*)(lds + PG8_SB(b, h) + boff + n * 2048 + k * 1024); } while (0)
; #define PG8_MMA(ai, bj, At, Bt) do { __builtin_amdgcn_s_setprio(1); _Pragma("unroll") for (int m = 0; m < 4; ++m) _Pragma("unroll") for (int n = 0; n < 2; ++n) _Pragma("unroll") for (int k = 0; k < 2; ++k) \
;         acc[ai][bj][m][n] = __builtin_amdgcn_mfma_f32_16x16x32_bf16(Bt[n][k], At[m][k], acc[ai][bj][m][n], 0, 0, 0); __builtin_amdgcn_s_setprio(0); } while (0)
; #define PG8_WAIT_V(n) asm volatile("s_waitcnt vmcnt(" #n ")" ::: "memory")
; template <class Epi, bool ALIGN_EPI = PG8_ALIGN, bool SP2 = PG8_SP2>
; __device__ __forceinline__ void gemm_phase(LAS uchar* lds, const Gemm g, const StaticOrder& S, const Epi& E) {
;     ...
;             PG8_LDB(B0, 0, 0); PG8_LDB(B1, 0, 1); PG8_SCHED; PG8_LDA(At, 0, 0); PG8_STAGE(PG8_SA(1, 1), a1 + hstepA, voffA);
;             PG8_WAIT_V(8); PG8_WAIT_L(0); PG8_BAR; PG8_MMA(0, 0, At, B0); PG8_MMA(0, 1, At, B1); PG8_BAR; PG8_SCHED;
;             PG8_LDA(At, 0, 1); PG8_STAGE(PG8_SB(0, 0), b2, voffB); PG8_STAGE(PG8_SB(0, 1), b2 + hstepB, voffB); PG8_STAGE(PG8_SA(0, 0), a2, voffA);
;             PG8_WAIT_V(8); PG8_WAIT_L(0); PG8_BAR; PG8_MMA(1, 0, At, B0); PG8_MMA(1, 1, At, B1); PG8_BAR; PG8_SCHED;
;             PG8_LDB(B0, 1, 0); PG8_LDB(B1, 1, 1); PG8_SCHED; PG8_LDA(At, 1, 0); PG8_STAGE(PG8_SA(0, 1), a2 + hstepA, voffA);
;             PG8_WAIT_V(8); PG8_WAIT_L(0); PG8_BAR; PG8_MMA(0, 0, At, B0); PG8_MMA(0, 1, At, B1); PG8_BAR; PG8_SCHED;
;             PG8_LDA(At, 1, 1); PG8_STAGE(PG8_SB(1, 0), b3, voffB); PG8_STAGE(PG8_SB(1, 1), b3 + hstepB, voffB); PG8_STAGE(PG8_SA(1, 0), a3, voffA);
;             PG8_WAIT_V(8); PG8_WAIT_L(0); PG8_BAR; PG8_MMA(1, 0, At, B0); PG8_MMA(1, 1, At, B1); PG8_BAR; PG8_SCHED;
	s_setprio 0
	s_add_i32 s16, s41, s23
	v_lshl_add_u64 v[168:169], v[168:169], 0, s[84:85]
	s_mov_b32 m0, s16
	ds_read_b128 v[204:207], v171 offset:49152
	ds_read_b128 v[208:211], v171 offset:50176
	ds_read_b128 v[212:215], v171 offset:51200
	ds_read_b128 v[216:219], v171 offset:52224
	ds_read_b128 v[220:223], v171 offset:53248
	ds_read_b128 v[224:227], v171 offset:54272
	ds_read_b128 v[228:231], v171 offset:55296
	ds_read_b128 v[232:235], v171 offset:56320
	global_load_lds_dwordx4 v[168:169], off
	s_add_i32 m0, s16, 0x2000
	s_add_u32 s4, s4, 0x44080
	v_lshl_add_u64 v[168:169], v[180:181], 0, s[84:85]
	s_addc_u32 s5, s5, 0
	s_add_i32 s16, s42, s23
	global_load_lds_dwordx4 v[168:169], off
	s_mov_b32 m0, s16
	v_lshl_add_u64 v[168:169], s[4:5], 0, v[134:135]
	global_load_lds_dwordx4 v[168:169], off
	s_add_i32 m0, s16, 0x2000
	v_lshl_add_u64 v[168:169], s[4:5], 0, v[130:131]
	global_load_lds_dwordx4 v[168:169], off
	s_mov_b32 m0, s29
	v_lshl_add_u64 v[168:169], v[236:237], 0, s[84:85]
	global_load_lds_dwordx4 v[168:169], off
	s_mov_b32 m0, s30
	v_lshl_add_u64 v[168:169], v[238:239], 0, s[84:85]
	global_load_lds_dwordx4 v[168:169], off
	s_setprio 1
	s_waitcnt vmcnt(8) lgkmcnt(0)
	s_barrier
	v_mfma_f32_16x16x32_bf16 v[62:65], v[164:167], v[204:207], v[62:65]
	v_mfma_f32_16x16x32_bf16 v[58:61], v[176:179], v[204:207], v[58:61]
	v_mfma_f32_16x16x32_bf16 v[54:57], v[164:167], v[212:215], v[54:57]
	v_mfma_f32_16x16x32_bf16 v[46:49], v[176:179], v[212:215], v[46:49]
	v_mfma_f32_16x16x32_bf16 v[38:41], v[164:167], v[220:223], v[38:41]
	v_mfma_f32_16x16x32_bf16 v[30:33], v[176:179], v[220:223], v[30:33]
	v_mfma_f32_16x16x32_bf16 v[22:25], v[164:167], v[228:231], v[22:25]
	v_mfma_f32_16x16x32_bf16 v[14:17], v[176:179], v[228:231], v[14:17]
	v_mfma_f32_16x16x32_bf16 v[62:65], v[172:175], v[208:211], v[62:65]
	v_mfma_f32_16x16x32_bf16 v[58:61], v[184:187], v[208:211], v[58:61]
	v_mfma_f32_16x16x32_bf16 v[54:57], v[172:175], v[216:219], v[54:57]
	v_mfma_f32_16x16x32_bf16 v[46:49], v[184:187], v[216:219], v[46:49]
	v_mfma_f32_16x16x32_bf16 v[38:41], v[172:175], v[224:227], v[38:41]
	v_mfma_f32_16x16x32_bf16 v[30:33], v[184:187], v[224:227], v[30:33]
	v_mfma_f32_16x16x32_bf16 v[22:25], v[172:175], v[232:235], v[22:25]
	v_mfma_f32_16x16x32_bf16 v[14:17], v[184:187], v[232:235], v[14:17]
	v_mfma_f32_16x16x32_bf16 v[50:53], v[188:191], v[204:207], v[50:53]
	v_mfma_f32_16x16x32_bf16 v[42:45], v[196:199], v[204:207], v[42:45]
	v_mfma_f32_16x16x32_bf16 v[34:37], v[188:191], v[212:215], v[34:37]
	v_mfma_f32_16x16x32_bf16 v[26:29], v[196:199], v[212:215], v[26:29]
	v_mfma_f32_16x16x32_bf16 v[18:21], v[188:191], v[220:223], v[18:21]
	v_mfma_f32_16x16x32_bf16 v[10:13], v[196:199], v[220:223], v[10:13]
	v_mfma_f32_16x16x32_bf16 v[6:9], v[188:191], v[228:231], v[6:9]
	v_mfma_f32_16x16x32_bf16 v[2:5], v[196:199], v[228:231], v[2:5]
	v_mfma_f32_16x16x32_bf16 v[50:53], v[192:195], v[208:211], v[50:53]
	v_mfma_f32_16x16x32_bf16 v[42:45], v[200:203], v[208:211], v[42:45]
	v_mfma_f32_16x16x32_bf16 v[34:37], v[192:195], v[216:219], v[34:37]
	v_mfma_f32_16x16x32_bf16 v[26:29], v[200:203], v[216:219], v[26:29]
	v_mfma_f32_16x16x32_bf16 v[18:21], v[192:195], v[224:227], v[18:21]
	v_mfma_f32_16x16x32_bf16 v[10:13], v[200:203], v[224:227], v[10:13]
	v_mfma_f32_16x16x32_bf16 v[6:9], v[192:195], v[232:235], v[6:9]
	v_mfma_f32_16x16x32_bf16 v[2:5], v[200:203], v[232:235], v[2:5]
	s_barrier
	s_setprio 0
	s_add_i32 s40, s40, 2
	s_add_u32 s38, s38, 0x100
	s_addc_u32 s39, s39, 0
	s_cmp_gt_u32 s40, 13
	s_mov_b64 s[16:17], s[18:19]
	s_cbranch_scc0 .LBB0_345
	s_mov_b32 s97, 0
	s_and_b64 vcc, exec, s[10:11]
	s_cbranch_vccnz .LBB0_350
	v_lshl_add_u32 v164, s37, 8, v1
	s_cmp_gt_i32 s36, 23
	s_mov_b64 s[4:5], -1
	s_cbranch_scc1 .LBB0_351

; #define LAS __attribute__((address_space(3)))
; #define PG8_WAIT_V(n) asm volatile("s_waitcnt vmcnt(" #n ")" ::: "memory")
; #define PG8_BAR __builtin_amdgcn_s_barrier()
; template <class Epi, bool ALIGN_EPI = PG8_ALIGN, bool SP2 = PG8_SP2>
; __device__ __forceinline__ void gemm_phase(LAS uchar* lds, const Gemm g, const StaticOrder& S, const Epi& E) {
;     ...
; #pragma unroll 1
;         for (int tb = 0; tb < nt; tb += tblk) {
;         if constexpr (Epi::GROUPS) { if (tb > 0) {
;             const LAS float* rt = (const LAS float*)(lds + LDS_RT) + ((ui & 1) * 256 + wr * 64 + fr) * 8 + ((tb >> 2) - 1);
; #pragma unroll
;             for (int a = 0; a < 2; ++a)
; #pragma unroll
;                 for (int m = 0; m < 4; ++m) { const float f = rt[(a * 128 + m * 16) * 8];
; #pragma unroll
;                     for (int b = 0; b < 2; ++b)
; #pragma unroll
;                         for (int n = 0; n < 2; ++n) acc[a][b][m][n] *= f; } } }
; #pragma unroll 1
;         for (int t = tb; t < tb + tblk; t += 2) {
;             const bool last = (t == nt - 2);
;             const char* a1 = cA + (size_t)(t + 1) * kstep;
;             const char* a2 = last ? nA : cA + (size_t)(t + 2) * kstep; const char* b2 = last ? nB : cB + (size_t)(t + 2) * kstep;
;             const char* a3 = a2 + kstep; const char* b3 = b2 + kstep;
;             if constexpr (SP2) {
;             PG8_LDB(B0, 0, 0); PG8_LDB(B1, 0, 1); PG8_SCHED; PG8_LDA(At, 0, 0); PG8_STAGE(PG8_SA(1, 1), a1 + hstepA, voffA);
;             PG8_WAIT_V(8); PG8_WAIT_L(0); PG8_BAR; PG8_MMA(0, 0, At, B0); PG8_MMA(0, 1, At, B1); PG8_BAR; PG8_SCHED;
;             PG8_LDA(At, 0, 1); PG8_STAGE(PG8_SB(0, 0), b2, voffB); PG8_STAGE(PG8_SB(0, 1), b2 + hstepB, voffB); PG8_STAGE(PG8_SA(0, 0), a2, voffA);
;             PG8_WAIT_V(8); PG8_WAIT_L(0); PG8_BAR; PG8_MMA(1, 0, At, B0); PG8_MMA(1, 1, At, B1); PG8_BAR; PG8_SCHED;
;             PG8_LDB(B0, 1, 0); PG8_LDB(B1, 1, 1); PG8_SCHED; PG8_LDA(At, 1, 0); PG8_STAGE(PG8_SA(0, 1), a2 + hstepA, voffA);
;             PG8_WAIT_V(8); PG8_WAIT_L(0); PG8_BAR; PG8_MMA(0, 0, At, B0); PG8_MMA(0, 1, At, B1); PG8_BAR; PG8_SCHED;
;             PG8_LDA(At, 1, 1); PG8_STAGE(PG8_SB(1, 0), b3, voffB); PG8_STAGE(PG8_SB(1, 1), b3 + hstepB, voffB); PG8_STAGE(PG8_SA(1, 0), a3, voffA);
;             PG8_WAIT_V(8); PG8_WAIT_L(0); PG8_BAR; PG8_MMA(1, 0, At, B0); PG8_MMA(1, 1, At, B1); PG8_BAR; PG8_SCHED;
.LBB0_580:
	s_add_i32 s42, s42, 2
	s_add_u32 s4, s14, s18
	s_addc_u32 s5, s15, s19
	s_add_u32 s4, s4, 0x100
	s_addc_u32 s5, s5, 0
	s_add_u32 s43, s38, s18
	s_addc_u32 s44, s39, s19
	s_add_i32 s45, 0, 0x10000
	s_cmpk_eq_i32 s18, 0xf00
	s_cselect_b32 s21, s1, s5
	s_cselect_b32 s20, s0, s4
	v_add_u32_e32 v1, s45, v168
	s_cselect_b32 s5, s13, s44
	s_cselect_b32 s4, s12, s43
	s_add_i32 s43, 0, 0x14000
	ds_read_b128 v[174:177], v1
	ds_read_b128 v[178:181], v1 offset:1024
	ds_read_b128 v[184:187], v1 offset:2048
	ds_read_b128 v[188:191], v1 offset:3072
	v_add_u32_e32 v1, s43, v168
	ds_read_b128 v[192:195], v1
	ds_read_b128 v[196:199], v1 offset:1024
	ds_read_b128 v[200:203], v1 offset:2048
	ds_read_b128 v[204:207], v1 offset:3072
	v_lshl_add_u64 v[2:3], v[164:165], 0, s[18:19]
	s_add_i32 m0, s25, 0xc000
	ds_read_b128 v[208:211], v170
	ds_read_b128 v[212:215], v170 offset:1024
	ds_read_b128 v[216:219], v170 offset:2048
	ds_read_b128 v[220:223], v170 offset:3072
	ds_read_b128 v[224:227], v170 offset:4096
	ds_read_b128 v[228:231], v170 offset:5120
	ds_read_b128 v[232:235], v170 offset:6144
	ds_read_b128 v[236:239], v170 offset:7168
	global_load_lds_dwordx4 v[2:3], off
	s_add_i32 m0, s25, 0xe000
	v_lshl_add_u64 v[2:3], v[166:167], 0, s[18:19]
	global_load_lds_dwordx4 v[2:3], off
	s_nop 0
	s_setprio 1
	s_waitcnt vmcnt(8) lgkmcnt(0)
	s_barrier
	v_mfma_f32_16x16x32_bf16 v[128:131], v[174:177], v[208:211], v[128:131]
	v_mfma_f32_16x16x32_bf16 v[124:127], v[184:187], v[208:211], v[124:127]
	v_mfma_f32_16x16x32_bf16 v[112:115], v[174:177], v[216:219], v[112:115]
	v_mfma_f32_16x16x32_bf16 v[108:111], v[184:187], v[216:219], v[108:111]
	v_mfma_f32_16x16x32_bf16 v[96:99], v[174:177], v[224:227], v[96:99]
	v_mfma_f32_16x16x32_bf16 v[92:95], v[184:187], v[224:227], v[92:95]
	v_mfma_f32_16x16x32_bf16 v[80:83], v[174:177], v[232:235], v[80:83]
	v_mfma_f32_16x16x32_bf16 v[76:79], v[184:187], v[232:235], v[76:79]
	v_mfma_f32_16x16x32_bf16 v[128:131], v[178:181], v[212:215], v[128:131]
	v_mfma_f32_16x16x32_bf16 v[124:127], v[188:191], v[212:215], v[124:127]
	v_mfma_f32_16x16x32_bf16 v[112:115], v[178:181], v[220:223], v[112:115]
	v_mfma_f32_16x16x32_bf16 v[108:111], v[188:191], v[220:223], v[108:111]
	v_mfma_f32_16x16x32_bf16 v[96:99], v[178:181], v[228:231], v[96:99]
	v_mfma_f32_16x16x32_bf16 v[92:95], v[188:191], v[228:231], v[92:95]
	v_mfma_f32_16x16x32_bf16 v[80:83], v[178:181], v[236:239], v[80:83]
	v_mfma_f32_16x16x32_bf16 v[76:79], v[188:191], v[236:239], v[76:79]
	v_mfma_f32_16x16x32_bf16 v[120:123], v[192:195], v[208:211], v[120:123]
	v_mfma_f32_16x16x32_bf16 v[116:119], v[200:203], v[208:211], v[116:119]
	v_mfma_f32_16x16x32_bf16 v[104:107], v[192:195], v[216:219], v[104:107]
	v_mfma_f32_16x16x32_bf16 v[100:103], v[200:203], v[216:219], v[100:103]
	v_mfma_f32_16x16x32_bf16 v[88:91], v[192:195], v[224:227], v[88:91]
	v_mfma_f32_16x16x32_bf16 v[84:87], v[200:203], v[224:227], v[84:87]
	v_mfma_f32_16x16x32_bf16 v[72:75], v[192:195], v[232:235], v[72:75]
	v_mfma_f32_16x16x32_bf16 v[68:71], v[200:203], v[232:235], v[68:71]
	v_mfma_f32_16x16x32_bf16 v[120:123], v[196:199], v[212:215], v[120:123]
	v_mfma_f32_16x16x32_bf16 v[116:119], v[204:207], v[212:215], v[116:119]
	v_mfma_f32_16x16x32_bf16 v[104:107], v[196:199], v[220:223], v[104:107]
	v_mfma_f32_16x16x32_bf16 v[100:103], v[204:207], v[220:223], v[100:103]
	v_mfma_f32_16x16x32_bf16 v[88:91], v[196:199], v[228:231], v[88:91]
	v_mfma_f32_16x16x32_bf16 v[84:87], v[204:207], v[228:231], v[84:87]
	v_mfma_f32_16x16x32_bf16 v[72:75], v[196:199], v[236:239], v[72:75]
	v_mfma_f32_16x16x32_bf16 v[68:71], v[204:207], v[236:239], v[68:71]
	s_barrier
	s_setprio 0
	s_add_i32 s44, s45, s24
	v_lshl_add_u64 v[240:241], s[4:5], 0, v[134:135]
	s_mov_b32 m0, s44
	ds_read_b128 v[208:211], v170 offset:16384
	ds_read_b128 v[212:215], v170 offset:17408
	ds_read_b128 v[216:219], v170 offset:18432
	ds_read_b128 v[220:223], v170 offset:19456
	ds_read_b128 v[224:227], v170 offset:20480
	ds_read_b128 v[228:231], v170 offset:21504
	ds_read_b128 v[232:235], v170 offset:22528
	ds_read_b128 v[236:239], v170 offset:23552
	global_load_lds_dwordx4 v[240:241], off
	s_add_i32 m0, s44, 0x2000
	s_add_u32 s44, s4, 0x84000
	v_lshl_add_u64 v[242:243], s[4:5], 0, v[158:159]
	s_addc_u32 s45, s5, 0
	s_add_i32 s43, s43, s24
	global_load_lds_dwordx4 v[242:243], off
	v_lshl_add_u64 v[2:3], s[44:45], 0, v[134:135]
	s_mov_b32 m0, s43
	global_load_lds_dwordx4 v[2:3], off
	v_lshl_add_u64 v[2:3], s[44:45], 0, v[158:159]
	s_add_i32 m0, s43, 0x2000
	global_load_lds_dwordx4 v[2:3], off
	s_mov_b32 m0, s25
	v_lshl_add_u64 v[244:245], s[20:21], 0, v[132:133]
	global_load_lds_dwordx4 v[244:245], off
	s_mov_b32 m0, s26
	v_lshl_add_u64 v[246:247], s[20:21], 0, v[156:157]
	global_load_lds_dwordx4 v[246:247], off
	s_setprio 1
	s_waitcnt vmcnt(8) lgkmcnt(0)
	s_barrier
; #define PG8_STAGE(bufoff, gbase, voff) do { _Pragma("unroll") for (int _i = 0; _i < 2; ++_i) \
;         __builtin_amdgcn_global_load_lds((const unsigned*)((const char*)(gbase) + (voff)[_i]), (LAS unsigned*)(lds + (bufoff) + ldsw + _i * 8192), 16, 0, 0); } while (0)
; #define PG8_LDA(dst, b, h) do { _Pragma("unroll") for (int m = 0; m < 4; ++m) _Pragma("unroll") for (int k = 0; k < 2; ++k) dst[m][k] = *(const LAS bf16x8*)(lds + PG8_SA(b, h) + aoff + m * 2048 + k * 1024); } while (0)
; #define PG8_LDB(dst, b, h) do { _Pragma("unroll") for (int n = 0; n < 2; ++n) _Pragma("unroll") for (int k = 0; k < 2; ++k) dst[n][k] = *(const LAS bf16x8*)(lds + PG8_SB(b, h) + boff + n * 2048 + k * 1024); } while (0)
; #define PG8_MMA(ai, bj, At, Bt) do { __builtin_amdgcn_s_setprio(1); _Pragma("unroll") for (int m = 0; m < 4; ++m) _Pragma("unroll") for (int n = 0; n < 2; ++n) _Pragma("unroll") for (int k = 0; k < 2; ++k) \
;         acc[ai][bj][m][n] = __builtin_amdgcn_mfma_f32_16x16x32_bf16(Bt[n][k], At[m][k], acc[ai][bj][m][n], 0, 0, 0); __builtin_amdgcn_s_setprio(0); } while (0)
; #define PG8_WAIT_V(n) asm volatile("s_waitcnt vmcnt(" #n ")" ::: "memory")
; template <class Epi, bool ALIGN_EPI = PG8_ALIGN, bool SP2 = PG8_SP2>
; __device__ __forceinline__ void gemm_phase(LAS uchar* lds, const Gemm g, const StaticOrder& S, const Epi& E) {
;     ...
;             PG8_LDB(B0, 0, 0); PG8_LDB(B1, 0, 1); PG8_SCHED; PG8_LDA(At, 0, 0); PG8_STAGE(PG8_SA(1, 1), a1 + hstepA, voffA);
;             PG8_WAIT_V(8); PG8_WAIT_L(0); PG8_BAR; PG8_MMA(0, 0, At, B0); PG8_MMA(0, 1, At, B1); PG8_BAR; PG8_SCHED;
;             PG8_LDA(At, 0, 1); PG8_STAGE(PG8_SB(0, 0), b2, voffB); PG8_STAGE(PG8_SB(0, 1), b2 + hstepB, voffB); PG8_STAGE(PG8_SA(0, 0), a2, voffA);
;             PG8_WAIT_V(8); PG8_WAIT_L(0); PG8_BAR; PG8_MMA(1, 0, At, B0); PG8_MMA(1, 1, At, B1); PG8_BAR; PG8_SCHED;
;             PG8_LDB(B0, 1, 0); PG8_LDB(B1, 1, 1); PG8_SCHED; PG8_LDA(At, 1, 0); PG8_STAGE(PG8_SA(0, 1), a2 + hstepA, voffA);
;             PG8_WAIT_V(8); PG8_WAIT_L(0); PG8_BAR; PG8_MMA(0, 0, At, B0); PG8_MMA(0, 1, At, B1); PG8_BAR; PG8_SCHED;
;             PG8_LDA(At, 1, 1); PG8_STAGE(PG8_SB(1, 0), b3, voffB); PG8_STAGE(PG8_SB(1, 1), b3 + hstepB, voffB); PG8_STAGE(PG8_SA(1, 0), a3, voffA);
;             PG8_WAIT_V(8); PG8_WAIT_L(0); PG8_BAR; PG8_MMA(1, 0, At, B0); PG8_MMA(1, 1, At, B1); PG8_BAR; PG8_SCHED;
	v_mfma_f32_16x16x32_bf16 v[64:67], v[174:177], v[208:211], v[64:67]
	v_mfma_f32_16x16x32_bf16 v[60:63], v[184:187], v[208:211], v[60:63]
	v_mfma_f32_16x16x32_bf16 v[48:51], v[174:177], v[216:219], v[48:51]
	v_mfma_f32_16x16x32_bf16 v[44:47], v[184:187], v[216:219], v[44:47]
	v_mfma_f32_16x16x32_bf16 v[32:35], v[174:177], v[224:227], v[32:35]
	v_mfma_f32_16x16x32_bf16 v[28:31], v[184:187], v[224:227], v[28:31]
	v_mfma_f32_16x16x32_bf16 v[16:19], v[174:177], v[232:235], v[16:19]
	v_mfma_f32_16x16x32_bf16 v[12:15], v[184:187], v[232:235], v[12:15]
	v_mfma_f32_16x16x32_bf16 v[64:67], v[178:181], v[212:215], v[64:67]
	v_mfma_f32_16x16x32_bf16 v[60:63], v[188:191], v[212:215], v[60:63]
	v_mfma_f32_16x16x32_bf16 v[48:51], v[178:181], v[220:223], v[48:51]
	v_mfma_f32_16x16x32_bf16 v[44:47], v[188:191], v[220:223], v[44:47]
	v_mfma_f32_16x16x32_bf16 v[32:35], v[178:181], v[228:231], v[32:35]
	v_mfma_f32_16x16x32_bf16 v[28:31], v[188:191], v[228:231], v[28:31]
	v_mfma_f32_16x16x32_bf16 v[16:19], v[178:181], v[236:239], v[16:19]
	v_mfma_f32_16x16x32_bf16 v[12:15], v[188:191], v[236:239], v[12:15]
	v_mfma_f32_16x16x32_bf16 v[56:59], v[192:195], v[208:211], v[56:59]
	v_mfma_f32_16x16x32_bf16 v[52:55], v[200:203], v[208:211], v[52:55]
	v_mfma_f32_16x16x32_bf16 v[40:43], v[192:195], v[216:219], v[40:43]
	v_mfma_f32_16x16x32_bf16 v[36:39], v[200:203], v[216:219], v[36:39]
	v_mfma_f32_16x16x32_bf16 v[24:27], v[192:195], v[224:227], v[24:27]
	v_mfma_f32_16x16x32_bf16 v[20:23], v[200:203], v[224:227], v[20:23]
	v_mfma_f32_16x16x32_bf16 v[8:11], v[192:195], v[232:235], v[8:11]
	v_mfma_f32_16x16x32_bf16 v[2:5], v[200:203], v[232:235], v[4:7]
	v_mfma_f32_16x16x32_bf16 v[56:59], v[196:199], v[212:215], v[56:59]
	v_mfma_f32_16x16x32_bf16 v[52:55], v[204:207], v[212:215], v[52:55]
	v_mfma_f32_16x16x32_bf16 v[40:43], v[196:199], v[220:223], v[40:43]
	v_mfma_f32_16x16x32_bf16 v[36:39], v[204:207], v[220:223], v[36:39]
	v_mfma_f32_16x16x32_bf16 v[24:27], v[196:199], v[228:231], v[24:27]
	v_mfma_f32_16x16x32_bf16 v[20:23], v[204:207], v[228:231], v[20:23]
	v_mfma_f32_16x16x32_bf16 v[8:11], v[196:199], v[236:239], v[8:11]
	v_mfma_f32_16x16x32_bf16 v[2:5], v[204:207], v[236:239], v[2:5]
	s_barrier
	s_setprio 0
	s_add_i32 s43, 0, 0x18000
	v_add_u32_e32 v1, s43, v168
	s_add_i32 s44, 0, 0x1c000
	ds_read_b128 v[174:177], v1
	ds_read_b128 v[178:181], v1 offset:1024
	ds_read_b128 v[184:187], v1 offset:2048
	ds_read_b128 v[188:191], v1 offset:3072
	v_add_u32_e32 v1, s44, v168
	ds_read_b128 v[192:195], v1
	ds_read_b128 v[196:199], v1 offset:1024
	ds_read_b128 v[200:203], v1 offset:2048
	ds_read_b128 v[204:207], v1 offset:3072
	s_add_u32 s20, s20, 0x184000
	s_addc_u32 s21, s21, 0
	s_mov_b32 m0, s27
	v_lshl_add_u64 v[6:7], s[20:21], 0, v[132:133]
	ds_read_b128 v[208:211], v170 offset:32768
	ds_read_b128 v[212:215], v170 offset:33792
	ds_read_b128 v[216:219], v170 offset:34816
	ds_read_b128 v[220:223], v170 offset:35840
	ds_read_b128 v[224:227], v170 offset:36864
	ds_read_b128 v[228:231], v170 offset:37888
	ds_read_b128 v[232:235], v170 offset:38912
	ds_read_b128 v[236:239], v170 offset:39936
	global_load_lds_dwordx4 v[6:7], off
	s_mov_b32 m0, s28
	v_lshl_add_u64 v[6:7], s[20:21], 0, v[156:157]
	global_load_lds_dwordx4 v[6:7], off
	s_setprio 1
	s_waitcnt vmcnt(8) lgkmcnt(0)
	s_barrier
	v_mfma_f32_16x16x32_bf16 v[128:131], v[174:177], v[208:211], v[128:131]
	v_mfma_f32_16x16x32_bf16 v[124:127], v[184:187], v[208:211], v[124:127]
	v_mfma_f32_16x16x32_bf16 v[112:115], v[174:177], v[216:219], v[112:115]
	v_mfma_f32_16x16x32_bf16 v[108:111], v[184:187], v[216:219], v[108:111]
	v_mfma_f32_16x16x32_bf16 v[96:99], v[174:177], v[224:227], v[96:99]
	v_mfma_f32_16x16x32_bf16 v[92:95], v[184:187], v[224:227], v[92:95]
	v_mfma_f32_16x16x32_bf16 v[80:83], v[174:177], v[232:235], v[80:83]
	v_mfma_f32_16x16x32_bf16 v[76:79], v[184:187], v[232:235], v[76:79]
	v_mfma_f32_16x16x32_bf16 v[128:131], v[178:181], v[212:215], v[128:131]
	v_mfma_f32_16x16x32_bf16 v[124:127], v[188:191], v[212:215], v[124:127]
	v_mfma_f32_16x16x32_bf16 v[112:115], v[178:181], v[220:223], v[112:115]
	v_mfma_f32_16x16x32_bf16 v[108:111], v[188:191], v[220:223], v[108:111]
	v_mfma_f32_16x16x32_bf16 v[96:99], v[178:181], v[228:231], v[96:99]
	v_mfma_f32_16x16x32_bf16 v[92:95], v[188:191], v[228:231], v[92:95]
	v_mfma_f32_16x16x32_bf16 v[80:83], v[178:181], v[236:239], v[80:83]
	v_mfma_f32_16x16x32_bf16 v[76:79], v[188:191], v[236:239], v[76:79]
	v_mfma_f32_16x16x32_bf16 v[120:123], v[192:195], v[208:211], v[120:123]
	v_mfma_f32_16x16x32_bf16 v[116:119], v[200:203], v[208:211], v[116:119]
	v_mfma_f32_16x16x32_bf16 v[104:107], v[192:195], v[216:219], v[104:107]
	v_mfma_f32_16x16x32_bf16 v[100:103], v[200:203], v[216:219], v[100:103]
	v_mfma_f32_16x16x32_bf16 v[88:91], v[192:195], v[224:227], v[88:91]
	v_mfma_f32_16x16x32_bf16 v[84:87], v[200:203], v[224:227], v[84:87]
	v_mfma_f32_16x16x32_bf16 v[72:75], v[192:195], v[232:235], v[72:75]
	v_mfma_f32_16x16x32_bf16 v[68:71], v[200:203], v[232:235], v[68:71]
	v_mfma_f32_16x16x32_bf16 v[120:123], v[196:199], v[212:215], v[120:123]
	v_mfma_f32_16x16x32_bf16 v[116:119], v[204:207], v[212:215], v[116:119]
	v_mfma_f32_16x16x32_bf16 v[104:107], v[196:199], v[220:223], v[104:107]
	v_mfma_f32_16x16x32_bf16 v[100:103], v[204:207], v[220:223], v[100:103]
	v_mfma_f32_16x16x32_bf16 v[88:91], v[196:199], v[228:231], v[88:91]
	v_mfma_f32_16x16x32_bf16 v[84:87], v[204:207], v[228:231], v[84:87]
	v_mfma_f32_16x16x32_bf16 v[72:75], v[196:199], v[236:239], v[72:75]
	v_mfma_f32_16x16x32_bf16 v[68:71], v[204:207], v[236:239], v[68:71]
	s_barrier
; #define LAS __attribute__((address_space(3)))
; #define PG8_WAIT_V(n) asm volatile("s_waitcnt vmcnt(" #n ")" ::: "memory")
; #define PG8_BAR __builtin_amdgcn_s_barrier()
; template <class Epi, bool ALIGN_EPI = PG8_ALIGN, bool SP2 = PG8_SP2>
; __device__ __forceinline__ void gemm_phase(LAS uchar* lds, const Gemm g, const StaticOrder& S, const Epi& E) {
;     ...
; #pragma unroll 1
;         for (int tb = 0; tb < nt; tb += tblk) {
;         if constexpr (Epi::GROUPS) { if (tb > 0) {
;             const LAS float* rt = (const LAS float*)(lds + LDS_RT) + ((ui & 1) * 256 + wr * 64 + fr) * 8 + ((tb >> 2) - 1);
; #pragma unroll
;             for (int a = 0; a < 2; ++a)
; #pragma unroll
;                 for (int m = 0; m < 4; ++m) { const float f = rt[(a * 128 + m * 16) * 8];
; #pragma unroll
;                     for (int b = 0; b < 2; ++b)
; #pragma unroll
;                         for (int n = 0; n < 2; ++n) acc[a][b][m][n] *= f; } } }
; #pragma unroll 1
;         for (int t = tb; t < tb + tblk; t += 2) {
;             const bool last = (t == nt - 2);
;             const char* a1 = cA + (size_t)(t + 1) * kstep;
;             const char* a2 = last ? nA : cA + (size_t)(t + 2) * kstep; const char* b2 = last ? nB : cB + (size_t)(t + 2) * kstep;
;             const char* a3 = a2 + kstep; const char* b3 = b2 + kstep;
;             if constexpr (SP2) {
;             PG8_LDB(B0, 0, 0); PG8_LDB(B1, 0, 1); PG8_SCHED; PG8_LDA(At, 0, 0); PG8_STAGE(PG8_SA(1, 1), a1 + hstepA, voffA);
;             PG8_WAIT_V(8); PG8_WAIT_L(0); PG8_BAR; PG8_MMA(0, 0, At, B0); PG8_MMA(0, 1, At, B1); PG8_BAR; PG8_SCHED;
;             PG8_LDA(At, 0, 1); PG8_STAGE(PG8_SB(0, 0), b2, voffB); PG8_STAGE(PG8_SB(0, 1), b2 + hstepB, voffB); PG8_STAGE(PG8_SA(0, 0), a2, voffA);
;             PG8_WAIT_V(8); PG8_WAIT_L(0); PG8_BAR; PG8_MMA(1, 0, At, B0); PG8_MMA(1, 1, At, B1); PG8_BAR; PG8_SCHED;
;             PG8_LDB(B0, 1, 0); PG8_LDB(B1, 1, 1); PG8_SCHED; PG8_LDA(At, 1, 0); PG8_STAGE(PG8_SA(0, 1), a2 + hstepA, voffA);
;             PG8_WAIT_V(8); PG8_WAIT_L(0); PG8_BAR; PG8_MMA(0, 0, At, B0); PG8_MMA(0, 1, At, B1); PG8_BAR; PG8_SCHED;
;             PG8_LDA(At, 1, 1); PG8_STAGE(PG8_SB(1, 0), b3, voffB); PG8_STAGE(PG8_SB(1, 1), b3 + hstepB, voffB); PG8_STAGE(PG8_SA(1, 0), a3, voffA);
;             PG8_WAIT_V(8); PG8_WAIT_L(0); PG8_BAR; PG8_MMA(1, 0, At, B0); PG8_MMA(1, 1, At, B1); PG8_BAR; PG8_SCHED;
	s_setprio 0
	s_add_i32 s20, s43, s24
	v_lshl_add_u64 v[6:7], v[240:241], 0, s[84:85]
	s_mov_b32 m0, s20
	ds_read_b128 v[208:211], v170 offset:49152
	ds_read_b128 v[212:215], v170 offset:50176
	ds_read_b128 v[216:219], v170 offset:51200
	ds_read_b128 v[220:223], v170 offset:52224
	ds_read_b128 v[224:227], v170 offset:53248
	ds_read_b128 v[228:231], v170 offset:54272
	ds_read_b128 v[232:235], v170 offset:55296
	ds_read_b128 v[236:239], v170 offset:56320
	global_load_lds_dwordx4 v[6:7], off
	s_add_i32 m0, s20, 0x2000
	s_add_u32 s4, s4, 0x84080
	v_lshl_add_u64 v[6:7], v[242:243], 0, s[84:85]
	s_addc_u32 s5, s5, 0
	s_add_i32 s20, s44, s24
	global_load_lds_dwordx4 v[6:7], off
	s_mov_b32 m0, s20
	v_lshl_add_u64 v[6:7], s[4:5], 0, v[134:135]
	global_load_lds_dwordx4 v[6:7], off
	s_add_i32 m0, s20, 0x2000
	v_lshl_add_u64 v[6:7], s[4:5], 0, v[158:159]
	global_load_lds_dwordx4 v[6:7], off
	s_mov_b32 m0, s29
	v_lshl_add_u64 v[6:7], v[244:245], 0, s[84:85]
	global_load_lds_dwordx4 v[6:7], off
	s_mov_b32 m0, s30
	v_lshl_add_u64 v[6:7], v[246:247], 0, s[84:85]
	global_load_lds_dwordx4 v[6:7], off
	s_setprio 1
	s_waitcnt vmcnt(8) lgkmcnt(0)
	s_barrier
	v_mfma_f32_16x16x32_bf16 v[64:67], v[174:177], v[208:211], v[64:67]
	v_mfma_f32_16x16x32_bf16 v[60:63], v[184:187], v[208:211], v[60:63]
	v_mfma_f32_16x16x32_bf16 v[48:51], v[174:177], v[216:219], v[48:51]
	v_mfma_f32_16x16x32_bf16 v[44:47], v[184:187], v[216:219], v[44:47]
	v_mfma_f32_16x16x32_bf16 v[32:35], v[174:177], v[224:227], v[32:35]
	v_mfma_f32_16x16x32_bf16 v[28:31], v[184:187], v[224:227], v[28:31]
	v_mfma_f32_16x16x32_bf16 v[16:19], v[174:177], v[232:235], v[16:19]
	v_mfma_f32_16x16x32_bf16 v[12:15], v[184:187], v[232:235], v[12:15]
	v_mfma_f32_16x16x32_bf16 v[64:67], v[178:181], v[212:215], v[64:67]
	v_mfma_f32_16x16x32_bf16 v[60:63], v[188:191], v[212:215], v[60:63]
	v_mfma_f32_16x16x32_bf16 v[48:51], v[178:181], v[220:223], v[48:51]
	v_mfma_f32_16x16x32_bf16 v[44:47], v[188:191], v[220:223], v[44:47]
	v_mfma_f32_16x16x32_bf16 v[32:35], v[178:181], v[228:231], v[32:35]
	v_mfma_f32_16x16x32_bf16 v[28:31], v[188:191], v[228:231], v[28:31]
	v_mfma_f32_16x16x32_bf16 v[16:19], v[178:181], v[236:239], v[16:19]
	v_mfma_f32_16x16x32_bf16 v[12:15], v[188:191], v[236:239], v[12:15]
	v_mfma_f32_16x16x32_bf16 v[56:59], v[192:195], v[208:211], v[56:59]
	v_mfma_f32_16x16x32_bf16 v[52:55], v[200:203], v[208:211], v[52:55]
	v_mfma_f32_16x16x32_bf16 v[40:43], v[192:195], v[216:219], v[40:43]
	v_mfma_f32_16x16x32_bf16 v[36:39], v[200:203], v[216:219], v[36:39]
	v_mfma_f32_16x16x32_bf16 v[24:27], v[192:195], v[224:227], v[24:27]
	v_mfma_f32_16x16x32_bf16 v[20:23], v[200:203], v[224:227], v[20:23]
	v_mfma_f32_16x16x32_bf16 v[6:9], v[192:195], v[232:235], v[8:11]
	v_mfma_f32_16x16x32_bf16 v[2:5], v[200:203], v[232:235], v[2:5]
	v_mfma_f32_16x16x32_bf16 v[56:59], v[196:199], v[212:215], v[56:59]
	v_mfma_f32_16x16x32_bf16 v[52:55], v[204:207], v[212:215], v[52:55]
	v_mfma_f32_16x16x32_bf16 v[40:43], v[196:199], v[220:223], v[40:43]
	v_mfma_f32_16x16x32_bf16 v[36:39], v[204:207], v[220:223], v[36:39]
	v_mfma_f32_16x16x32_bf16 v[24:27], v[196:199], v[228:231], v[24:27]
	v_mfma_f32_16x16x32_bf16 v[20:23], v[204:207], v[228:231], v[20:23]
	v_mfma_f32_16x16x32_bf16 v[8:11], v[196:199], v[236:239], v[6:9]
	v_mfma_f32_16x16x32_bf16 v[4:7], v[204:207], v[236:239], v[2:5]
	s_barrier
	s_setprio 0
	s_add_u32 s18, s18, 0x100
	s_addc_u32 s19, s19, 0
	s_cmp_ge_u32 s42, s41
	s_cbranch_scc0 .LBB0_580
	s_add_u32 s16, s16, 0x200
	s_addc_u32 s17, s17, 0
	s_cmp_lt_u32 s40, 28
	s_cbranch_scc0 .LBB0_583
	s_mov_b32 s40, s41
	s_cmp_eq_u32 s40, 0
	s_cbranch_scc0 .LBB0_578
	s_branch .LBB0_579

; #define PG8_STAGE(bufoff, gbase, voff) do { _Pragma("unroll") for (int _i = 0; _i < 2; ++_i) \
;         __builtin_amdgcn_global_load_lds((const unsigned*)((const char*)(gbase) + (voff)[_i]), (LAS unsigned*)(lds + (bufoff) + ldsw + _i * 8192), 16, 0, 0); } while (0)
; #define PG8_LDA(dst, b, h) do { _Pragma("unroll") for (int m = 0; m < 4; ++m) _Pragma("unroll") for (int k = 0; k < 2; ++k) dst[m][k] = *(const LAS bf16x8*)(lds + PG8_SA(b, h) + aoff + m * 2048 + k * 1024); } while (0)
; #define PG8_LDB(dst, b, h) do { _Pragma("unroll") for (int n = 0; n < 2; ++n) _Pragma("unroll") for (int k = 0; k < 2; ++k) dst[n][k] = *(const LAS bf16x8*)(lds + PG8_SB(b, h) + boff + n * 2048 + k * 1024); } while (0)
; #define PG8_MMA(ai, bj, At, Bt) do { __builtin_amdgcn_s_setprio(1); _Pragma("unroll") for (int m = 0; m < 4; ++m) _Pragma("unroll") for (int n = 0; n < 2; ++n) _Pragma("unroll") for (int k = 0; k < 2; ++k) \
;         acc[ai][bj][m][n] = __builtin_amdgcn_mfma_f32_16x16x32_bf16(Bt[n][k], At[m][k], acc[ai][bj][m][n], 0, 0, 0); __builtin_amdgcn_s_setprio(0); } while (0)
; #define PG8_WAIT_V(n) asm volatile("s_waitcnt vmcnt(" #n ")" ::: "memory")
; template <class Epi, bool ALIGN_EPI = PG8_ALIGN, bool SP2 = PG8_SP2>
; __device__ __forceinline__ void gemm_phase(LAS uchar* lds, const Gemm g, const StaticOrder& S, const Epi& E) {
;     ...
;             PG8_LDB(B0, 0, 0); PG8_LDB(B1, 0, 1); PG8_SCHED; PG8_LDA(At, 0, 0); PG8_STAGE(PG8_SA(1, 1), a1 + hstepA, voffA);
;             PG8_WAIT_V(8); PG8_WAIT_L(0); PG8_BAR; PG8_MMA(0, 0, At, B0); PG8_MMA(0, 1, At, B1); PG8_BAR; PG8_SCHED;
;             PG8_LDA(At, 0, 1); PG8_STAGE(PG8_SB(0, 0), b2, voffB); PG8_STAGE(PG8_SB(0, 1), b2 + hstepB, voffB); PG8_STAGE(PG8_SA(0, 0), a2, voffA);
;             PG8_WAIT_V(8); PG8_WAIT_L(0); PG8_BAR; PG8_MMA(1, 0, At, B0); PG8_MMA(1, 1, At, B1); PG8_BAR; PG8_SCHED;
;             PG8_LDB(B0, 1, 0); PG8_LDB(B1, 1, 1); PG8_SCHED; PG8_LDA(At, 1, 0); PG8_STAGE(PG8_SA(0, 1), a2 + hstepA, voffA);
;             PG8_WAIT_V(8); PG8_WAIT_L(0); PG8_BAR; PG8_MMA(0, 0, At, B0); PG8_MMA(0, 1, At, B1); PG8_BAR; PG8_SCHED;
;             PG8_LDA(At, 1, 1); PG8_STAGE(PG8_SB(1, 0), b3, voffB); PG8_STAGE(PG8_SB(1, 1), b3 + hstepB, voffB); PG8_STAGE(PG8_SA(1, 0), a3, voffA);
;             PG8_WAIT_V(8); PG8_WAIT_L(0); PG8_BAR; PG8_MMA(1, 0, At, B0); PG8_MMA(1, 1, At, B1); PG8_BAR; PG8_SCHED;
.LBB0_669:
	s_add_u32 s14, s12, 0x100
	s_addc_u32 s15, s13, 0
	s_add_i32 s39, 0, 0x10000
	s_cmp_eq_u32 s38, 12
	s_cselect_b32 s19, s5, s15
	s_cselect_b32 s18, s4, s14
	s_cselect_b32 s17, s11, s37
	s_cselect_b32 s16, s10, s36
	s_add_i32 s40, 0, 0x14000
	v_add_u32_e32 v174, s39, v139
	v_add_u32_e32 v192, s40, v139
	ds_read_b128 v[160:163], v174
	ds_read_b128 v[164:167], v174 offset:1024
	ds_read_b128 v[168:171], v174 offset:2048
	ds_read_b128 v[174:177], v174 offset:3072
	ds_read_b128 v[178:181], v192
	ds_read_b128 v[184:187], v192 offset:1024
	ds_read_b128 v[188:191], v192 offset:2048
	ds_read_b128 v[192:195], v192 offset:3072
	v_lshl_add_u64 v[228:229], s[12:13], 0, v[156:157]
	s_add_i32 m0, s23, 0xc000
	ds_read_b128 v[196:199], v173
	ds_read_b128 v[200:203], v173 offset:1024
	ds_read_b128 v[204:207], v173 offset:2048
	ds_read_b128 v[208:211], v173 offset:3072
	ds_read_b128 v[212:215], v173 offset:4096
	ds_read_b128 v[216:219], v173 offset:5120
	ds_read_b128 v[220:223], v173 offset:6144
	ds_read_b128 v[224:227], v173 offset:7168
	global_load_lds_dwordx4 v[228:229], off
	s_add_i32 m0, s23, 0xe000
	v_lshl_add_u64 v[228:229], s[12:13], 0, v[158:159]
	global_load_lds_dwordx4 v[228:229], off
	s_nop 0
	s_setprio 1
	s_waitcnt vmcnt(8) lgkmcnt(0)
	s_barrier
	v_mfma_f32_16x16x32_bf16 v[126:129], v[160:163], v[196:199], v[126:129]
	v_mfma_f32_16x16x32_bf16 v[122:125], v[168:171], v[196:199], v[122:125]
	v_mfma_f32_16x16x32_bf16 v[118:121], v[160:163], v[204:207], v[118:121]
	v_mfma_f32_16x16x32_bf16 v[110:113], v[168:171], v[204:207], v[110:113]
	v_mfma_f32_16x16x32_bf16 v[102:105], v[160:163], v[212:215], v[102:105]
	v_mfma_f32_16x16x32_bf16 v[94:97], v[168:171], v[212:215], v[94:97]
	v_mfma_f32_16x16x32_bf16 v[86:89], v[160:163], v[220:223], v[86:89]
	v_mfma_f32_16x16x32_bf16 v[78:81], v[168:171], v[220:223], v[78:81]
	v_mfma_f32_16x16x32_bf16 v[126:129], v[164:167], v[200:203], v[126:129]
	v_mfma_f32_16x16x32_bf16 v[122:125], v[174:177], v[200:203], v[122:125]
	v_mfma_f32_16x16x32_bf16 v[118:121], v[164:167], v[208:211], v[118:121]
	v_mfma_f32_16x16x32_bf16 v[110:113], v[174:177], v[208:211], v[110:113]
	v_mfma_f32_16x16x32_bf16 v[102:105], v[164:167], v[216:219], v[102:105]
	v_mfma_f32_16x16x32_bf16 v[94:97], v[174:177], v[216:219], v[94:97]
	v_mfma_f32_16x16x32_bf16 v[86:89], v[164:167], v[224:227], v[86:89]
	v_mfma_f32_16x16x32_bf16 v[78:81], v[174:177], v[224:227], v[78:81]
	v_mfma_f32_16x16x32_bf16 v[114:117], v[178:181], v[196:199], v[114:117]
	v_mfma_f32_16x16x32_bf16 v[106:109], v[188:191], v[196:199], v[106:109]
	v_mfma_f32_16x16x32_bf16 v[98:101], v[178:181], v[204:207], v[98:101]
	v_mfma_f32_16x16x32_bf16 v[90:93], v[188:191], v[204:207], v[90:93]
	v_mfma_f32_16x16x32_bf16 v[82:85], v[178:181], v[212:215], v[82:85]
	v_mfma_f32_16x16x32_bf16 v[74:77], v[188:191], v[212:215], v[74:77]
	v_mfma_f32_16x16x32_bf16 v[70:73], v[178:181], v[220:223], v[70:73]
	v_mfma_f32_16x16x32_bf16 v[66:69], v[188:191], v[220:223], v[66:69]
	v_mfma_f32_16x16x32_bf16 v[114:117], v[184:187], v[200:203], v[114:117]
	v_mfma_f32_16x16x32_bf16 v[106:109], v[192:195], v[200:203], v[106:109]
	v_mfma_f32_16x16x32_bf16 v[98:101], v[184:187], v[208:211], v[98:101]
	v_mfma_f32_16x16x32_bf16 v[90:93], v[192:195], v[208:211], v[90:93]
	v_mfma_f32_16x16x32_bf16 v[82:85], v[184:187], v[216:219], v[82:85]
	v_mfma_f32_16x16x32_bf16 v[74:77], v[192:195], v[216:219], v[74:77]
	v_mfma_f32_16x16x32_bf16 v[70:73], v[184:187], v[224:227], v[70:73]
	v_mfma_f32_16x16x32_bf16 v[66:69], v[192:195], v[224:227], v[66:69]
	s_barrier
	s_setprio 0
	s_add_i32 s12, s39, s21
	v_lshl_add_u64 v[228:229], s[16:17], 0, v[134:135]
	s_mov_b32 m0, s12
	ds_read_b128 v[196:199], v173 offset:16384
	ds_read_b128 v[200:203], v173 offset:17408
	ds_read_b128 v[204:207], v173 offset:18432
	ds_read_b128 v[208:211], v173 offset:19456
	ds_read_b128 v[212:215], v173 offset:20480
	ds_read_b128 v[216:219], v173 offset:21504
	ds_read_b128 v[220:223], v173 offset:22528
	ds_read_b128 v[224:227], v173 offset:23552
	global_load_lds_dwordx4 v[228:229], off
	s_add_i32 m0, s12, 0x2000
	s_add_u32 s12, s16, 0x44000
	v_lshl_add_u64 v[230:231], s[16:17], 0, v[130:131]
	s_addc_u32 s13, s17, 0
	s_add_i32 s39, s40, s21
	global_load_lds_dwordx4 v[230:231], off
	v_lshl_add_u64 v[232:233], s[12:13], 0, v[134:135]
	s_mov_b32 m0, s39
	global_load_lds_dwordx4 v[232:233], off
	s_add_i32 m0, s39, 0x2000
	v_lshl_add_u64 v[232:233], s[12:13], 0, v[130:131]
	global_load_lds_dwordx4 v[232:233], off
	s_mov_b32 m0, s23
	v_lshl_add_u64 v[232:233], s[18:19], 0, v[152:153]
	global_load_lds_dwordx4 v[232:233], off
	s_mov_b32 m0, s24
	v_lshl_add_u64 v[234:235], s[18:19], 0, v[132:133]
	global_load_lds_dwordx4 v[234:235], off
	s_setprio 1
	s_waitcnt vmcnt(8) lgkmcnt(0)
	s_barrier
; #define PG8_STAGE(bufoff, gbase, voff) do { _Pragma("unroll") for (int _i = 0; _i < 2; ++_i) \
;         __builtin_amdgcn_global_load_lds((const unsigned*)((const char*)(gbase) + (voff)[_i]), (LAS unsigned*)(lds + (bufoff) + ldsw + _i * 8192), 16, 0, 0); } while (0)
; #define PG8_LDA(dst, b, h) do { _Pragma("unroll") for (int m = 0; m < 4; ++m) _Pragma("unroll") for (int k = 0; k < 2; ++k) dst[m][k] = *(const LAS bf16x8*)(lds + PG8_SA(b, h) + aoff + m * 2048 + k * 1024); } while (0)
; #define PG8_LDB(dst, b, h) do { _Pragma("unroll") for (int n = 0; n < 2; ++n) _Pragma("unroll") for (int k = 0; k < 2; ++k) dst[n][k] = *(const LAS bf16x8*)(lds + PG8_SB(b, h) + boff + n * 2048 + k * 1024); } while (0)
; #define PG8_MMA(ai, bj, At, Bt) do { __builtin_amdgcn_s_setprio(1); _Pragma("unroll") for (int m = 0; m < 4; ++m) _Pragma("unroll") for (int n = 0; n < 2; ++n) _Pragma("unroll") for (int k = 0; k < 2; ++k) \
;         acc[ai][bj][m][n] = __builtin_amdgcn_mfma_f32_16x16x32_bf16(Bt[n][k], At[m][k], acc[ai][bj][m][n], 0, 0, 0); __builtin_amdgcn_s_setprio(0); } while (0)
; #define PG8_WAIT_V(n) asm volatile("s_waitcnt vmcnt(" #n ")" ::: "memory")
; template <class Epi, bool ALIGN_EPI = PG8_ALIGN, bool SP2 = PG8_SP2>
; __device__ __forceinline__ void gemm_phase(LAS uchar* lds, const Gemm g, const StaticOrder& S, const Epi& E) {
;     ...
;             PG8_LDB(B0, 0, 0); PG8_LDB(B1, 0, 1); PG8_SCHED; PG8_LDA(At, 0, 0); PG8_STAGE(PG8_SA(1, 1), a1 + hstepA, voffA);
;             PG8_WAIT_V(8); PG8_WAIT_L(0); PG8_BAR; PG8_MMA(0, 0, At, B0); PG8_MMA(0, 1, At, B1); PG8_BAR; PG8_SCHED;
;             PG8_LDA(At, 0, 1); PG8_STAGE(PG8_SB(0, 0), b2, voffB); PG8_STAGE(PG8_SB(0, 1), b2 + hstepB, voffB); PG8_STAGE(PG8_SA(0, 0), a2, voffA);
;             PG8_WAIT_V(8); PG8_WAIT_L(0); PG8_BAR; PG8_MMA(1, 0, At, B0); PG8_MMA(1, 1, At, B1); PG8_BAR; PG8_SCHED;
;             PG8_LDB(B0, 1, 0); PG8_LDB(B1, 1, 1); PG8_SCHED; PG8_LDA(At, 1, 0); PG8_STAGE(PG8_SA(0, 1), a2 + hstepA, voffA);
;             PG8_WAIT_V(8); PG8_WAIT_L(0); PG8_BAR; PG8_MMA(0, 0, At, B0); PG8_MMA(0, 1, At, B1); PG8_BAR; PG8_SCHED;
;             PG8_LDA(At, 1, 1); PG8_STAGE(PG8_SB(1, 0), b3, voffB); PG8_STAGE(PG8_SB(1, 1), b3 + hstepB, voffB); PG8_STAGE(PG8_SA(1, 0), a3, voffA);
;             PG8_WAIT_V(8); PG8_WAIT_L(0); PG8_BAR; PG8_MMA(1, 0, At, B0); PG8_MMA(1, 1, At, B1); PG8_BAR; PG8_SCHED;
	v_mfma_f32_16x16x32_bf16 v[62:65], v[160:163], v[196:199], v[62:65]
	v_mfma_f32_16x16x32_bf16 v[58:61], v[168:171], v[196:199], v[58:61]
	v_mfma_f32_16x16x32_bf16 v[54:57], v[160:163], v[204:207], v[54:57]
	v_mfma_f32_16x16x32_bf16 v[46:49], v[168:171], v[204:207], v[46:49]
	v_mfma_f32_16x16x32_bf16 v[38:41], v[160:163], v[212:215], v[38:41]
	v_mfma_f32_16x16x32_bf16 v[30:33], v[168:171], v[212:215], v[30:33]
	v_mfma_f32_16x16x32_bf16 v[22:25], v[160:163], v[220:223], v[22:25]
	v_mfma_f32_16x16x32_bf16 v[14:17], v[168:171], v[220:223], v[14:17]
	v_mfma_f32_16x16x32_bf16 v[62:65], v[164:167], v[200:203], v[62:65]
	v_mfma_f32_16x16x32_bf16 v[58:61], v[174:177], v[200:203], v[58:61]
	v_mfma_f32_16x16x32_bf16 v[54:57], v[164:167], v[208:211], v[54:57]
	v_mfma_f32_16x16x32_bf16 v[46:49], v[174:177], v[208:211], v[46:49]
	v_mfma_f32_16x16x32_bf16 v[38:41], v[164:167], v[216:219], v[38:41]
	v_mfma_f32_16x16x32_bf16 v[30:33], v[174:177], v[216:219], v[30:33]
	v_mfma_f32_16x16x32_bf16 v[22:25], v[164:167], v[224:227], v[22:25]
	v_mfma_f32_16x16x32_bf16 v[14:17], v[174:177], v[224:227], v[14:17]
	v_mfma_f32_16x16x32_bf16 v[50:53], v[178:181], v[196:199], v[50:53]
	v_mfma_f32_16x16x32_bf16 v[42:45], v[188:191], v[196:199], v[42:45]
	v_mfma_f32_16x16x32_bf16 v[34:37], v[178:181], v[204:207], v[34:37]
	v_mfma_f32_16x16x32_bf16 v[26:29], v[188:191], v[204:207], v[26:29]
	v_mfma_f32_16x16x32_bf16 v[18:21], v[178:181], v[212:215], v[18:21]
	v_mfma_f32_16x16x32_bf16 v[10:13], v[188:191], v[212:215], v[10:13]
	v_mfma_f32_16x16x32_bf16 v[6:9], v[178:181], v[220:223], v[6:9]
	v_mfma_f32_16x16x32_bf16 v[2:5], v[188:191], v[220:223], v[2:5]
	v_mfma_f32_16x16x32_bf16 v[50:53], v[184:187], v[200:203], v[50:53]
	v_mfma_f32_16x16x32_bf16 v[42:45], v[192:195], v[200:203], v[42:45]
	v_mfma_f32_16x16x32_bf16 v[34:37], v[184:187], v[208:211], v[34:37]
	v_mfma_f32_16x16x32_bf16 v[26:29], v[192:195], v[208:211], v[26:29]
	v_mfma_f32_16x16x32_bf16 v[18:21], v[184:187], v[216:219], v[18:21]
	v_mfma_f32_16x16x32_bf16 v[10:13], v[192:195], v[216:219], v[10:13]
	v_mfma_f32_16x16x32_bf16 v[6:9], v[184:187], v[224:227], v[6:9]
	v_mfma_f32_16x16x32_bf16 v[2:5], v[192:195], v[224:227], v[2:5]
	s_barrier
	s_setprio 0
	s_add_i32 s39, 0, 0x18000
	s_add_i32 s40, 0, 0x1c000
	v_add_u32_e32 v174, s39, v139
	v_add_u32_e32 v192, s40, v139
	ds_read_b128 v[160:163], v174
	ds_read_b128 v[164:167], v174 offset:1024
	ds_read_b128 v[168:171], v174 offset:2048
	ds_read_b128 v[174:177], v174 offset:3072
	ds_read_b128 v[178:181], v192
	ds_read_b128 v[184:187], v192 offset:1024
	ds_read_b128 v[188:191], v192 offset:2048
	ds_read_b128 v[192:195], v192 offset:3072
	s_add_u32 s12, s18, 0x44000
	s_addc_u32 s13, s19, 0
	s_mov_b32 m0, s25
	v_lshl_add_u64 v[236:237], s[12:13], 0, v[152:153]
	ds_read_b128 v[196:199], v173 offset:32768
	ds_read_b128 v[200:203], v173 offset:33792
	ds_read_b128 v[204:207], v173 offset:34816
	ds_read_b128 v[208:211], v173 offset:35840
	ds_read_b128 v[212:215], v173 offset:36864
	ds_read_b128 v[216:219], v173 offset:37888
	ds_read_b128 v[220:223], v173 offset:38912
	ds_read_b128 v[224:227], v173 offset:39936
	global_load_lds_dwordx4 v[236:237], off
	s_mov_b32 m0, s26
	v_lshl_add_u64 v[236:237], s[12:13], 0, v[132:133]
	global_load_lds_dwordx4 v[236:237], off
	s_setprio 1
	s_waitcnt vmcnt(8) lgkmcnt(0)
	s_barrier
	v_mfma_f32_16x16x32_bf16 v[126:129], v[160:163], v[196:199], v[126:129]
	v_mfma_f32_16x16x32_bf16 v[122:125], v[168:171], v[196:199], v[122:125]
	v_mfma_f32_16x16x32_bf16 v[118:121], v[160:163], v[204:207], v[118:121]
	v_mfma_f32_16x16x32_bf16 v[110:113], v[168:171], v[204:207], v[110:113]
	v_mfma_f32_16x16x32_bf16 v[102:105], v[160:163], v[212:215], v[102:105]
	v_mfma_f32_16x16x32_bf16 v[94:97], v[168:171], v[212:215], v[94:97]
	v_mfma_f32_16x16x32_bf16 v[86:89], v[160:163], v[220:223], v[86:89]
	v_mfma_f32_16x16x32_bf16 v[78:81], v[168:171], v[220:223], v[78:81]
	v_mfma_f32_16x16x32_bf16 v[126:129], v[164:167], v[200:203], v[126:129]
	v_mfma_f32_16x16x32_bf16 v[122:125], v[174:177], v[200:203], v[122:125]
	v_mfma_f32_16x16x32_bf16 v[118:121], v[164:167], v[208:211], v[118:121]
	v_mfma_f32_16x16x32_bf16 v[110:113], v[174:177], v[208:211], v[110:113]
	v_mfma_f32_16x16x32_bf16 v[102:105], v[164:167], v[216:219], v[102:105]
	v_mfma_f32_16x16x32_bf16 v[94:97], v[174:177], v[216:219], v[94:97]
	v_mfma_f32_16x16x32_bf16 v[86:89], v[164:167], v[224:227], v[86:89]
	v_mfma_f32_16x16x32_bf16 v[78:81], v[174:177], v[224:227], v[78:81]
	v_mfma_f32_16x16x32_bf16 v[114:117], v[178:181], v[196:199], v[114:117]
	v_mfma_f32_16x16x32_bf16 v[106:109], v[188:191], v[196:199], v[106:109]
	v_mfma_f32_16x16x32_bf16 v[98:101], v[178:181], v[204:207], v[98:101]
	v_mfma_f32_16x16x32_bf16 v[90:93], v[188:191], v[204:207], v[90:93]
	v_mfma_f32_16x16x32_bf16 v[82:85], v[178:181], v[212:215], v[82:85]
	v_mfma_f32_16x16x32_bf16 v[74:77], v[188:191], v[212:215], v[74:77]
	v_mfma_f32_16x16x32_bf16 v[70:73], v[178:181], v[220:223], v[70:73]
	v_mfma_f32_16x16x32_bf16 v[66:69], v[188:191], v[220:223], v[66:69]
	v_mfma_f32_16x16x32_bf16 v[114:117], v[184:187], v[200:203], v[114:117]
	v_mfma_f32_16x16x32_bf16 v[106:109], v[192:195], v[200:203], v[106:109]
	v_mfma_f32_16x16x32_bf16 v[98:101], v[184:187], v[208:211], v[98:101]
	v_mfma_f32_16x16x32_bf16 v[90:93], v[192:195], v[208:211], v[90:93]
	v_mfma_f32_16x16x32_bf16 v[82:85], v[184:187], v[216:219], v[82:85]
	v_mfma_f32_16x16x32_bf16 v[74:77], v[192:195], v[216:219], v[74:77]
	v_mfma_f32_16x16x32_bf16 v[70:73], v[184:187], v[224:227], v[70:73]
	v_mfma_f32_16x16x32_bf16 v[66:69], v[192:195], v[224:227], v[66:69]
	s_barrier
; #define PG8_STAGE(bufoff, gbase, voff) do { _Pragma("unroll") for (int _i = 0; _i < 2; ++_i) \
;         __builtin_amdgcn_global_load_lds((const unsigned*)((const char*)(gbase) + (voff)[_i]), (LAS unsigned*)(lds + (bufoff) + ldsw + _i * 8192), 16, 0, 0); } while (0)
; #define PG8_LDA(dst, b, h) do { _Pragma("unroll") for (int m = 0; m < 4; ++m) _Pragma("unroll") for (int k = 0; k < 2; ++k) dst[m][k] = *(const LAS bf16x8*)(lds + PG8_SA(b, h) + aoff + m * 2048 + k * 1024); } while (0)
; #define PG8_LDB(dst, b, h) do { _Pragma("unroll") for (int n = 0; n < 2; ++n) _Pragma("unroll") for (int k = 0; k < 2; ++k) dst[n][k] = *(const LAS bf16x8*)(lds + PG8_SB(b, h) + boff + n * 2048 + k * 1024); } while (0)
; #define PG8_MMA(ai, bj, At, Bt) do { __builtin_amdgcn_s_setprio(1); _Pragma("unroll") for (int m = 0; m < 4; ++m) _Pragma("unroll") for (int n = 0; n < 2; ++n) _Pragma("unroll") for (int k = 0; k < 2; ++k) \
;         acc[ai][bj][m][n] = __builtin_amdgcn_mfma_f32_16x16x32_bf16(Bt[n][k], At[m][k], acc[ai][bj][m][n], 0, 0, 0); __builtin_amdgcn_s_setprio(0); } while (0)
; template <class Epi, bool ALIGN_EPI = PG8_ALIGN, bool SP2 = PG8_SP2>
; __device__ __forceinline__ void gemm_phase(LAS uchar* lds, const Gemm g, const StaticOrder& S, const Epi& E) {
;     ...
;             PG8_LDB(B0, 0, 0); PG8_LDB(B1, 0, 1); PG8_SCHED; PG8_LDA(At, 0, 0); PG8_STAGE(PG8_SA(1, 1), a1 + hstepA, voffA);
;             PG8_WAIT_V(8); PG8_WAIT_L(0); PG8_BAR; PG8_MMA(0, 0, At, B0); PG8_MMA(0, 1, At, B1); PG8_BAR; PG8_SCHED;
;             PG8_LDA(At, 0, 1); PG8_STAGE(PG8_SB(0, 0), b2, voffB); PG8_STAGE(PG8_SB(0, 1), b2 + hstepB, voffB); PG8_STAGE(PG8_SA(0, 0), a2, voffA);
;             PG8_WAIT_V(8); PG8_WAIT_L(0); PG8_BAR; PG8_MMA(1, 0, At, B0); PG8_MMA(1, 1, At, B1); PG8_BAR; PG8_SCHED;
;             PG8_LDB(B0, 1, 0); PG8_LDB(B1, 1, 1); PG8_SCHED; PG8_LDA(At, 1, 0); PG8_STAGE(PG8_SA(0, 1), a2 + hstepA, voffA);
;             PG8_WAIT_V(8); PG8_WAIT_L(0); PG8_BAR; PG8_MMA(0, 0, At, B0); PG8_MMA(0, 1, At, B1); PG8_BAR; PG8_SCHED;
;             PG8_LDA(At, 1, 1); PG8_STAGE(PG8_SB(1, 0), b3, voffB); PG8_STAGE(PG8_SB(1, 1), b3 + hstepB, voffB); PG8_STAGE(PG8_SA(1, 0), a3, voffA);
;             PG8_WAIT_V(8); PG8_WAIT_L(0); PG8_BAR; PG8_MMA(1, 0, At, B0); PG8_MMA(1, 1, At, B1); PG8_BAR; PG8_SCHED;
;     ...
;         if constexpr (ALIGN_EPI) { if (wr == 0) PG8_BAR; }
	s_setprio 0
	s_add_i32 s12, s39, s21
	v_lshl_add_u64 v[228:229], v[228:229], 0, s[84:85]
	s_mov_b32 m0, s12
	ds_read_b128 v[196:199], v173 offset:49152
	ds_read_b128 v[200:203], v173 offset:50176
	ds_read_b128 v[204:207], v173 offset:51200
	ds_read_b128 v[208:211], v173 offset:52224
	ds_read_b128 v[212:215], v173 offset:53248
	ds_read_b128 v[216:219], v173 offset:54272
	ds_read_b128 v[220:223], v173 offset:55296
	ds_read_b128 v[224:227], v173 offset:56320
	global_load_lds_dwordx4 v[228:229], off
	s_add_i32 m0, s12, 0x2000
	s_add_u32 s12, s16, 0x44080
	v_lshl_add_u64 v[228:229], v[230:231], 0, s[84:85]
	s_addc_u32 s13, s17, 0
	s_add_i32 s16, s40, s21
	global_load_lds_dwordx4 v[228:229], off
	s_mov_b32 m0, s16
	v_lshl_add_u64 v[228:229], s[12:13], 0, v[134:135]
	global_load_lds_dwordx4 v[228:229], off
	s_add_i32 m0, s16, 0x2000
	v_lshl_add_u64 v[228:229], s[12:13], 0, v[130:131]
	global_load_lds_dwordx4 v[228:229], off
	s_mov_b32 m0, s27
	v_lshl_add_u64 v[228:229], v[232:233], 0, s[84:85]
	global_load_lds_dwordx4 v[228:229], off
	s_mov_b32 m0, s28
	v_lshl_add_u64 v[228:229], v[234:235], 0, s[84:85]
	global_load_lds_dwordx4 v[228:229], off
	s_setprio 1
	s_waitcnt vmcnt(8) lgkmcnt(0)
	s_barrier
	v_mfma_f32_16x16x32_bf16 v[62:65], v[160:163], v[196:199], v[62:65]
	v_mfma_f32_16x16x32_bf16 v[58:61], v[168:171], v[196:199], v[58:61]
	v_mfma_f32_16x16x32_bf16 v[54:57], v[160:163], v[204:207], v[54:57]
	v_mfma_f32_16x16x32_bf16 v[46:49], v[168:171], v[204:207], v[46:49]
	v_mfma_f32_16x16x32_bf16 v[38:41], v[160:163], v[212:215], v[38:41]
	v_mfma_f32_16x16x32_bf16 v[30:33], v[168:171], v[212:215], v[30:33]
	v_mfma_f32_16x16x32_bf16 v[22:25], v[160:163], v[220:223], v[22:25]
	v_mfma_f32_16x16x32_bf16 v[14:17], v[168:171], v[220:223], v[14:17]
	v_mfma_f32_16x16x32_bf16 v[62:65], v[164:167], v[200:203], v[62:65]
	v_mfma_f32_16x16x32_bf16 v[58:61], v[174:177], v[200:203], v[58:61]
	v_mfma_f32_16x16x32_bf16 v[54:57], v[164:167], v[208:211], v[54:57]
	v_mfma_f32_16x16x32_bf16 v[46:49], v[174:177], v[208:211], v[46:49]
	v_mfma_f32_16x16x32_bf16 v[38:41], v[164:167], v[216:219], v[38:41]
	v_mfma_f32_16x16x32_bf16 v[30:33], v[174:177], v[216:219], v[30:33]
	v_mfma_f32_16x16x32_bf16 v[22:25], v[164:167], v[224:227], v[22:25]
	v_mfma_f32_16x16x32_bf16 v[14:17], v[174:177], v[224:227], v[14:17]
	v_mfma_f32_16x16x32_bf16 v[50:53], v[178:181], v[196:199], v[50:53]
	v_mfma_f32_16x16x32_bf16 v[42:45], v[188:191], v[196:199], v[42:45]
	v_mfma_f32_16x16x32_bf16 v[34:37], v[178:181], v[204:207], v[34:37]
	v_mfma_f32_16x16x32_bf16 v[26:29], v[188:191], v[204:207], v[26:29]
	v_mfma_f32_16x16x32_bf16 v[18:21], v[178:181], v[212:215], v[18:21]
	v_mfma_f32_16x16x32_bf16 v[10:13], v[188:191], v[212:215], v[10:13]
	v_mfma_f32_16x16x32_bf16 v[6:9], v[178:181], v[220:223], v[6:9]
	v_mfma_f32_16x16x32_bf16 v[2:5], v[188:191], v[220:223], v[2:5]
	v_mfma_f32_16x16x32_bf16 v[50:53], v[184:187], v[200:203], v[50:53]
	v_mfma_f32_16x16x32_bf16 v[42:45], v[192:195], v[200:203], v[42:45]
	v_mfma_f32_16x16x32_bf16 v[34:37], v[184:187], v[208:211], v[34:37]
	v_mfma_f32_16x16x32_bf16 v[26:29], v[192:195], v[208:211], v[26:29]
	v_mfma_f32_16x16x32_bf16 v[18:21], v[184:187], v[216:219], v[18:21]
	v_mfma_f32_16x16x32_bf16 v[10:13], v[192:195], v[216:219], v[10:13]
	v_mfma_f32_16x16x32_bf16 v[6:9], v[184:187], v[224:227], v[6:9]
	v_mfma_f32_16x16x32_bf16 v[2:5], v[192:195], v[224:227], v[2:5]
	s_barrier
	s_setprio 0
	s_add_i32 s38, s38, 2
	s_add_u32 s36, s36, 0x100
	s_addc_u32 s37, s37, 0
	s_cmp_gt_u32 s38, 13
	s_mov_b64 s[12:13], s[14:15]
	s_cbranch_scc0 .LBB0_669
	s_and_b64 vcc, exec, s[8:9]
	s_cbranch_vccz .LBB0_672
	s_barrier

; #define PG8_STAGE(bufoff, gbase, voff) do { _Pragma("unroll") for (int _i = 0; _i < 2; ++_i) \
;         __builtin_amdgcn_global_load_lds((const unsigned*)((const char*)(gbase) + (voff)[_i]), (LAS unsigned*)(lds + (bufoff) + ldsw + _i * 8192), 16, 0, 0); } while (0)
; #define PG8_LDA(dst, b, h) do { _Pragma("unroll") for (int m = 0; m < 4; ++m) _Pragma("unroll") for (int k = 0; k < 2; ++k) dst[m][k] = *(const LAS bf16x8*)(lds + PG8_SA(b, h) + aoff + m * 2048 + k * 1024); } while (0)
; #define PG8_LDB(dst, b, h) do { _Pragma("unroll") for (int n = 0; n < 2; ++n) _Pragma("unroll") for (int k = 0; k < 2; ++k) dst[n][k] = *(const LAS bf16x8*)(lds + PG8_SB(b, h) + boff + n * 2048 + k * 1024); } while (0)
; #define PG8_MMA(ai, bj, At, Bt) do { __builtin_amdgcn_s_setprio(1); _Pragma("unroll") for (int m = 0; m < 4; ++m) _Pragma("unroll") for (int n = 0; n < 2; ++n) _Pragma("unroll") for (int k = 0; k < 2; ++k) \
;         acc[ai][bj][m][n] = __builtin_amdgcn_mfma_f32_16x16x32_bf16(Bt[n][k], At[m][k], acc[ai][bj][m][n], 0, 0, 0); __builtin_amdgcn_s_setprio(0); } while (0)
; #define PG8_WAIT_V(n) asm volatile("s_waitcnt vmcnt(" #n ")" ::: "memory")
; template <class Epi, bool ALIGN_EPI = PG8_ALIGN, bool SP2 = PG8_SP2>
; __device__ __forceinline__ void gemm_phase(LAS uchar* lds, const Gemm g, const StaticOrder& S, const Epi& E) {
;     ...
;             PG8_LDB(B0, 0, 0); PG8_LDB(B1, 0, 1); PG8_SCHED; PG8_LDA(At, 0, 0); PG8_STAGE(PG8_SA(1, 1), a1 + hstepA, voffA);
;             PG8_WAIT_V(8); PG8_WAIT_L(0); PG8_BAR; PG8_MMA(0, 0, At, B0); PG8_MMA(0, 1, At, B1); PG8_BAR; PG8_SCHED;
;             PG8_LDA(At, 0, 1); PG8_STAGE(PG8_SB(0, 0), b2, voffB); PG8_STAGE(PG8_SB(0, 1), b2 + hstepB, voffB); PG8_STAGE(PG8_SA(0, 0), a2, voffA);
;             PG8_WAIT_V(8); PG8_WAIT_L(0); PG8_BAR; PG8_MMA(1, 0, At, B0); PG8_MMA(1, 1, At, B1); PG8_BAR; PG8_SCHED;
;             PG8_LDB(B0, 1, 0); PG8_LDB(B1, 1, 1); PG8_SCHED; PG8_LDA(At, 1, 0); PG8_STAGE(PG8_SA(0, 1), a2 + hstepA, voffA);
;             PG8_WAIT_V(8); PG8_WAIT_L(0); PG8_BAR; PG8_MMA(0, 0, At, B0); PG8_MMA(0, 1, At, B1); PG8_BAR; PG8_SCHED;
;             PG8_LDA(At, 1, 1); PG8_STAGE(PG8_SB(1, 0), b3, voffB); PG8_STAGE(PG8_SB(1, 1), b3 + hstepB, voffB); PG8_STAGE(PG8_SA(1, 0), a3, voffA);
;             PG8_WAIT_V(8); PG8_WAIT_L(0); PG8_BAR; PG8_MMA(1, 0, At, B0); PG8_MMA(1, 1, At, B1); PG8_BAR; PG8_SCHED;
.LBB0_837:
	s_add_u32 s14, s12, 0x100
	s_addc_u32 s15, s13, 0
	s_add_i32 s39, 0, 0x10000
	s_cmp_eq_u32 s38, 12
	s_cselect_b32 s19, s5, s15
	s_cselect_b32 s18, s4, s14
	s_cselect_b32 s17, s11, s37
	s_cselect_b32 s16, s10, s36
	s_add_i32 s40, 0, 0x14000
	v_add_u32_e32 v174, s39, v139
	v_add_u32_e32 v192, s40, v139
	ds_read_b128 v[160:163], v174
	ds_read_b128 v[166:169], v174 offset:1024
	ds_read_b128 v[170:173], v174 offset:2048
	ds_read_b128 v[174:177], v174 offset:3072
	ds_read_b128 v[178:181], v192
	ds_read_b128 v[184:187], v192 offset:1024
	ds_read_b128 v[188:191], v192 offset:2048
	ds_read_b128 v[192:195], v192 offset:3072
	v_lshl_add_u64 v[228:229], s[12:13], 0, v[156:157]
	s_add_i32 m0, s23, 0xc000
	ds_read_b128 v[196:199], v165
	ds_read_b128 v[200:203], v165 offset:1024
	ds_read_b128 v[204:207], v165 offset:2048
	ds_read_b128 v[208:211], v165 offset:3072
	ds_read_b128 v[212:215], v165 offset:4096
	ds_read_b128 v[216:219], v165 offset:5120
	ds_read_b128 v[220:223], v165 offset:6144
	ds_read_b128 v[224:227], v165 offset:7168
	global_load_lds_dwordx4 v[228:229], off
	s_add_i32 m0, s23, 0xe000
	v_lshl_add_u64 v[228:229], s[12:13], 0, v[158:159]
	global_load_lds_dwordx4 v[228:229], off
	s_nop 0
	s_setprio 1
	s_waitcnt vmcnt(8) lgkmcnt(0)
	s_barrier
	v_mfma_f32_16x16x32_bf16 v[126:129], v[160:163], v[196:199], v[126:129]
	v_mfma_f32_16x16x32_bf16 v[122:125], v[170:173], v[196:199], v[122:125]
	v_mfma_f32_16x16x32_bf16 v[118:121], v[160:163], v[204:207], v[118:121]
	v_mfma_f32_16x16x32_bf16 v[110:113], v[170:173], v[204:207], v[110:113]
	v_mfma_f32_16x16x32_bf16 v[102:105], v[160:163], v[212:215], v[102:105]
	v_mfma_f32_16x16x32_bf16 v[94:97], v[170:173], v[212:215], v[94:97]
	v_mfma_f32_16x16x32_bf16 v[86:89], v[160:163], v[220:223], v[86:89]
	v_mfma_f32_16x16x32_bf16 v[78:81], v[170:173], v[220:223], v[78:81]
	v_mfma_f32_16x16x32_bf16 v[126:129], v[166:169], v[200:203], v[126:129]
	v_mfma_f32_16x16x32_bf16 v[122:125], v[174:177], v[200:203], v[122:125]
	v_mfma_f32_16x16x32_bf16 v[118:121], v[166:169], v[208:211], v[118:121]
	v_mfma_f32_16x16x32_bf16 v[110:113], v[174:177], v[208:211], v[110:113]
	v_mfma_f32_16x16x32_bf16 v[102:105], v[166:169], v[216:219], v[102:105]
	v_mfma_f32_16x16x32_bf16 v[94:97], v[174:177], v[216:219], v[94:97]
	v_mfma_f32_16x16x32_bf16 v[86:89], v[166:169], v[224:227], v[86:89]
	v_mfma_f32_16x16x32_bf16 v[78:81], v[174:177], v[224:227], v[78:81]
	v_mfma_f32_16x16x32_bf16 v[114:117], v[178:181], v[196:199], v[114:117]
	v_mfma_f32_16x16x32_bf16 v[106:109], v[188:191], v[196:199], v[106:109]
	v_mfma_f32_16x16x32_bf16 v[98:101], v[178:181], v[204:207], v[98:101]
	v_mfma_f32_16x16x32_bf16 v[90:93], v[188:191], v[204:207], v[90:93]
	v_mfma_f32_16x16x32_bf16 v[82:85], v[178:181], v[212:215], v[82:85]
	v_mfma_f32_16x16x32_bf16 v[74:77], v[188:191], v[212:215], v[74:77]
	v_mfma_f32_16x16x32_bf16 v[70:73], v[178:181], v[220:223], v[70:73]
	v_mfma_f32_16x16x32_bf16 v[66:69], v[188:191], v[220:223], v[66:69]
	v_mfma_f32_16x16x32_bf16 v[114:117], v[184:187], v[200:203], v[114:117]
	v_mfma_f32_16x16x32_bf16 v[106:109], v[192:195], v[200:203], v[106:109]
	v_mfma_f32_16x16x32_bf16 v[98:101], v[184:187], v[208:211], v[98:101]
	v_mfma_f32_16x16x32_bf16 v[90:93], v[192:195], v[208:211], v[90:93]
	v_mfma_f32_16x16x32_bf16 v[82:85], v[184:187], v[216:219], v[82:85]
	v_mfma_f32_16x16x32_bf16 v[74:77], v[192:195], v[216:219], v[74:77]
	v_mfma_f32_16x16x32_bf16 v[70:73], v[184:187], v[224:227], v[70:73]
	v_mfma_f32_16x16x32_bf16 v[66:69], v[192:195], v[224:227], v[66:69]
	s_barrier
	s_setprio 0
	s_add_i32 s12, s39, s22
	v_lshl_add_u64 v[228:229], s[16:17], 0, v[132:133]
	s_mov_b32 m0, s12
	ds_read_b128 v[196:199], v165 offset:16384
	ds_read_b128 v[200:203], v165 offset:17408
	ds_read_b128 v[204:207], v165 offset:18432
	ds_read_b128 v[208:211], v165 offset:19456
	ds_read_b128 v[212:215], v165 offset:20480
	ds_read_b128 v[216:219], v165 offset:21504
	ds_read_b128 v[220:223], v165 offset:22528
	ds_read_b128 v[224:227], v165 offset:23552
	global_load_lds_dwordx4 v[228:229], off
	s_add_i32 m0, s12, 0x2000
	s_add_u32 s12, s16, 0x44000
	v_lshl_add_u64 v[230:231], s[16:17], 0, v[152:153]
	s_addc_u32 s13, s17, 0
	s_add_i32 s39, s40, s22
	global_load_lds_dwordx4 v[230:231], off
	v_lshl_add_u64 v[232:233], s[12:13], 0, v[132:133]
	s_mov_b32 m0, s39
	global_load_lds_dwordx4 v[232:233], off
	s_add_i32 m0, s39, 0x2000
	v_lshl_add_u64 v[232:233], s[12:13], 0, v[152:153]
	global_load_lds_dwordx4 v[232:233], off
	s_mov_b32 m0, s23
	v_lshl_add_u64 v[232:233], s[18:19], 0, v[130:131]
	global_load_lds_dwordx4 v[232:233], off
	s_mov_b32 m0, s24
	v_lshl_add_u64 v[234:235], s[18:19], 0, v[134:135]
	global_load_lds_dwordx4 v[234:235], off
	s_setprio 1
	s_waitcnt vmcnt(8) lgkmcnt(0)
	s_barrier
; #define PG8_STAGE(bufoff, gbase, voff) do { _Pragma("unroll") for (int _i = 0; _i < 2; ++_i) \
;         __builtin_amdgcn_global_load_lds((const unsigned*)((const char*)(gbase) + (voff)[_i]), (LAS unsigned*)(lds + (bufoff) + ldsw + _i * 8192), 16, 0, 0); } while (0)
; #define PG8_LDA(dst, b, h) do { _Pragma("unroll") for (int m = 0; m < 4; ++m) _Pragma("unroll") for (int k = 0; k < 2; ++k) dst[m][k] = *(const LAS bf16x8*)(lds + PG8_SA(b, h) + aoff + m * 2048 + k * 1024); } while (0)
; #define PG8_LDB(dst, b, h) do { _Pragma("unroll") for (int n = 0; n < 2; ++n) _Pragma("unroll") for (int k = 0; k < 2; ++k) dst[n][k] = *(const LAS bf16x8*)(lds + PG8_SB(b, h) + boff + n * 2048 + k * 1024); } while (0)
; #define PG8_MMA(ai, bj, At, Bt) do { __builtin_amdgcn_s_setprio(1); _Pragma("unroll") for (int m = 0; m < 4; ++m) _Pragma("unroll") for (int n = 0; n < 2; ++n) _Pragma("unroll") for (int k = 0; k < 2; ++k) \
;         acc[ai][bj][m][n] = __builtin_amdgcn_mfma_f32_16x16x32_bf16(Bt[n][k], At[m][k], acc[ai][bj][m][n], 0, 0, 0); __builtin_amdgcn_s_setprio(0); } while (0)
; #define PG8_WAIT_V(n) asm volatile("s_waitcnt vmcnt(" #n ")" ::: "memory")
; template <class Epi, bool ALIGN_EPI = PG8_ALIGN, bool SP2 = PG8_SP2>
; __device__ __forceinline__ void gemm_phase(LAS uchar* lds, const Gemm g, const StaticOrder& S, const Epi& E) {
;     ...
;             PG8_LDB(B0, 0, 0); PG8_LDB(B1, 0, 1); PG8_SCHED; PG8_LDA(At, 0, 0); PG8_STAGE(PG8_SA(1, 1), a1 + hstepA, voffA);
;             PG8_WAIT_V(8); PG8_WAIT_L(0); PG8_BAR; PG8_MMA(0, 0, At, B0); PG8_MMA(0, 1, At, B1); PG8_BAR; PG8_SCHED;
;             PG8_LDA(At, 0, 1); PG8_STAGE(PG8_SB(0, 0), b2, voffB); PG8_STAGE(PG8_SB(0, 1), b2 + hstepB, voffB); PG8_STAGE(PG8_SA(0, 0), a2, voffA);
;             PG8_WAIT_V(8); PG8_WAIT_L(0); PG8_BAR; PG8_MMA(1, 0, At, B0); PG8_MMA(1, 1, At, B1); PG8_BAR; PG8_SCHED;
;             PG8_LDB(B0, 1, 0); PG8_LDB(B1, 1, 1); PG8_SCHED; PG8_LDA(At, 1, 0); PG8_STAGE(PG8_SA(0, 1), a2 + hstepA, voffA);
;             PG8_WAIT_V(8); PG8_WAIT_L(0); PG8_BAR; PG8_MMA(0, 0, At, B0); PG8_MMA(0, 1, At, B1); PG8_BAR; PG8_SCHED;
;             PG8_LDA(At, 1, 1); PG8_STAGE(PG8_SB(1, 0), b3, voffB); PG8_STAGE(PG8_SB(1, 1), b3 + hstepB, voffB); PG8_STAGE(PG8_SA(1, 0), a3, voffA);
;             PG8_WAIT_V(8); PG8_WAIT_L(0); PG8_BAR; PG8_MMA(1, 0, At, B0); PG8_MMA(1, 1, At, B1); PG8_BAR; PG8_SCHED;
	v_mfma_f32_16x16x32_bf16 v[62:65], v[160:163], v[196:199], v[62:65]
	v_mfma_f32_16x16x32_bf16 v[58:61], v[170:173], v[196:199], v[58:61]
	v_mfma_f32_16x16x32_bf16 v[54:57], v[160:163], v[204:207], v[54:57]
	v_mfma_f32_16x16x32_bf16 v[46:49], v[170:173], v[204:207], v[46:49]
	v_mfma_f32_16x16x32_bf16 v[38:41], v[160:163], v[212:215], v[38:41]
	v_mfma_f32_16x16x32_bf16 v[30:33], v[170:173], v[212:215], v[30:33]
	v_mfma_f32_16x16x32_bf16 v[22:25], v[160:163], v[220:223], v[22:25]
	v_mfma_f32_16x16x32_bf16 v[14:17], v[170:173], v[220:223], v[14:17]
	v_mfma_f32_16x16x32_bf16 v[62:65], v[166:169], v[200:203], v[62:65]
	v_mfma_f32_16x16x32_bf16 v[58:61], v[174:177], v[200:203], v[58:61]
	v_mfma_f32_16x16x32_bf16 v[54:57], v[166:169], v[208:211], v[54:57]
	v_mfma_f32_16x16x32_bf16 v[46:49], v[174:177], v[208:211], v[46:49]
	v_mfma_f32_16x16x32_bf16 v[38:41], v[166:169], v[216:219], v[38:41]
	v_mfma_f32_16x16x32_bf16 v[30:33], v[174:177], v[216:219], v[30:33]
	v_mfma_f32_16x16x32_bf16 v[22:25], v[166:169], v[224:227], v[22:25]
	v_mfma_f32_16x16x32_bf16 v[14:17], v[174:177], v[224:227], v[14:17]
	v_mfma_f32_16x16x32_bf16 v[50:53], v[178:181], v[196:199], v[50:53]
	v_mfma_f32_16x16x32_bf16 v[42:45], v[188:191], v[196:199], v[42:45]
	v_mfma_f32_16x16x32_bf16 v[34:37], v[178:181], v[204:207], v[34:37]
	v_mfma_f32_16x16x32_bf16 v[26:29], v[188:191], v[204:207], v[26:29]
	v_mfma_f32_16x16x32_bf16 v[18:21], v[178:181], v[212:215], v[18:21]
	v_mfma_f32_16x16x32_bf16 v[10:13], v[188:191], v[212:215], v[10:13]
	v_mfma_f32_16x16x32_bf16 v[6:9], v[178:181], v[220:223], v[6:9]
	v_mfma_f32_16x16x32_bf16 v[2:5], v[188:191], v[220:223], v[2:5]
	v_mfma_f32_16x16x32_bf16 v[50:53], v[184:187], v[200:203], v[50:53]
	v_mfma_f32_16x16x32_bf16 v[42:45], v[192:195], v[200:203], v[42:45]
	v_mfma_f32_16x16x32_bf16 v[34:37], v[184:187], v[208:211], v[34:37]
	v_mfma_f32_16x16x32_bf16 v[26:29], v[192:195], v[208:211], v[26:29]
	v_mfma_f32_16x16x32_bf16 v[18:21], v[184:187], v[216:219], v[18:21]
	v_mfma_f32_16x16x32_bf16 v[10:13], v[192:195], v[216:219], v[10:13]
	v_mfma_f32_16x16x32_bf16 v[6:9], v[184:187], v[224:227], v[6:9]
	v_mfma_f32_16x16x32_bf16 v[2:5], v[192:195], v[224:227], v[2:5]
	s_barrier
	s_setprio 0
	s_add_i32 s39, 0, 0x18000
	s_add_i32 s40, 0, 0x1c000
	v_add_u32_e32 v174, s39, v139
	v_add_u32_e32 v192, s40, v139
	ds_read_b128 v[160:163], v174
	ds_read_b128 v[166:169], v174 offset:1024
	ds_read_b128 v[170:173], v174 offset:2048
	ds_read_b128 v[174:177], v174 offset:3072
	ds_read_b128 v[178:181], v192
	ds_read_b128 v[184:187], v192 offset:1024
	ds_read_b128 v[188:191], v192 offset:2048
	ds_read_b128 v[192:195], v192 offset:3072
	s_add_u32 s12, s18, 0x44000
	s_addc_u32 s13, s19, 0
	s_mov_b32 m0, s25
	v_lshl_add_u64 v[236:237], s[12:13], 0, v[130:131]
	ds_read_b128 v[196:199], v165 offset:32768
	ds_read_b128 v[200:203], v165 offset:33792
	ds_read_b128 v[204:207], v165 offset:34816
	ds_read_b128 v[208:211], v165 offset:35840
	ds_read_b128 v[212:215], v165 offset:36864
	ds_read_b128 v[216:219], v165 offset:37888
	ds_read_b128 v[220:223], v165 offset:38912
	ds_read_b128 v[224:227], v165 offset:39936
	global_load_lds_dwordx4 v[236:237], off
	s_mov_b32 m0, s26
	v_lshl_add_u64 v[236:237], s[12:13], 0, v[134:135]
	global_load_lds_dwordx4 v[236:237], off
	s_setprio 1
	s_waitcnt vmcnt(8) lgkmcnt(0)
	s_barrier
	v_mfma_f32_16x16x32_bf16 v[126:129], v[160:163], v[196:199], v[126:129]
	v_mfma_f32_16x16x32_bf16 v[122:125], v[170:173], v[196:199], v[122:125]
	v_mfma_f32_16x16x32_bf16 v[118:121], v[160:163], v[204:207], v[118:121]
	v_mfma_f32_16x16x32_bf16 v[110:113], v[170:173], v[204:207], v[110:113]
	v_mfma_f32_16x16x32_bf16 v[102:105], v[160:163], v[212:215], v[102:105]
	v_mfma_f32_16x16x32_bf16 v[94:97], v[170:173], v[212:215], v[94:97]
	v_mfma_f32_16x16x32_bf16 v[86:89], v[160:163], v[220:223], v[86:89]
	v_mfma_f32_16x16x32_bf16 v[78:81], v[170:173], v[220:223], v[78:81]
	v_mfma_f32_16x16x32_bf16 v[126:129], v[166:169], v[200:203], v[126:129]
	v_mfma_f32_16x16x32_bf16 v[122:125], v[174:177], v[200:203], v[122:125]
	v_mfma_f32_16x16x32_bf16 v[118:121], v[166:169], v[208:211], v[118:121]
	v_mfma_f32_16x16x32_bf16 v[110:113], v[174:177], v[208:211], v[110:113]
	v_mfma_f32_16x16x32_bf16 v[102:105], v[166:169], v[216:219], v[102:105]
	v_mfma_f32_16x16x32_bf16 v[94:97], v[174:177], v[216:219], v[94:97]
	v_mfma_f32_16x16x32_bf16 v[86:89], v[166:169], v[224:227], v[86:89]
	v_mfma_f32_16x16x32_bf16 v[78:81], v[174:177], v[224:227], v[78:81]
	v_mfma_f32_16x16x32_bf16 v[114:117], v[178:181], v[196:199], v[114:117]
	v_mfma_f32_16x16x32_bf16 v[106:109], v[188:191], v[196:199], v[106:109]
	v_mfma_f32_16x16x32_bf16 v[98:101], v[178:181], v[204:207], v[98:101]
	v_mfma_f32_16x16x32_bf16 v[90:93], v[188:191], v[204:207], v[90:93]
	v_mfma_f32_16x16x32_bf16 v[82:85], v[178:181], v[212:215], v[82:85]
	v_mfma_f32_16x16x32_bf16 v[74:77], v[188:191], v[212:215], v[74:77]
	v_mfma_f32_16x16x32_bf16 v[70:73], v[178:181], v[220:223], v[70:73]
	v_mfma_f32_16x16x32_bf16 v[66:69], v[188:191], v[220:223], v[66:69]
	v_mfma_f32_16x16x32_bf16 v[114:117], v[184:187], v[200:203], v[114:117]
	v_mfma_f32_16x16x32_bf16 v[106:109], v[192:195], v[200:203], v[106:109]
	v_mfma_f32_16x16x32_bf16 v[98:101], v[184:187], v[208:211], v[98:101]
	v_mfma_f32_16x16x32_bf16 v[90:93], v[192:195], v[208:211], v[90:93]
	v_mfma_f32_16x16x32_bf16 v[82:85], v[184:187], v[216:219], v[82:85]
	v_mfma_f32_16x16x32_bf16 v[74:77], v[192:195], v[216:219], v[74:77]
	v_mfma_f32_16x16x32_bf16 v[70:73], v[184:187], v[224:227], v[70:73]
	v_mfma_f32_16x16x32_bf16 v[66:69], v[192:195], v[224:227], v[66:69]
	s_barrier
; #define PG8_STAGE(bufoff, gbase, voff) do { _Pragma("unroll") for (int _i = 0; _i < 2; ++_i) \
;         __builtin_amdgcn_global_load_lds((const unsigned*)((const char*)(gbase) + (voff)[_i]), (LAS unsigned*)(lds + (bufoff) + ldsw + _i * 8192), 16, 0, 0); } while (0)
; #define PG8_LDA(dst, b, h) do { _Pragma("unroll") for (int m = 0; m < 4; ++m) _Pragma("unroll") for (int k = 0; k < 2; ++k) dst[m][k] = *(const LAS bf16x8*)(lds + PG8_SA(b, h) + aoff + m * 2048 + k * 1024); } while (0)
; #define PG8_LDB(dst, b, h) do { _Pragma("unroll") for (int n = 0; n < 2; ++n) _Pragma("unroll") for (int k = 0; k < 2; ++k) dst[n][k] = *(const LAS bf16x8*)(lds + PG8_SB(b, h) + boff + n * 2048 + k * 1024); } while (0)
; #define PG8_MMA(ai, bj, At, Bt) do { __builtin_amdgcn_s_setprio(1); _Pragma("unroll") for (int m = 0; m < 4; ++m) _Pragma("unroll") for (int n = 0; n < 2; ++n) _Pragma("unroll") for (int k = 0; k < 2; ++k) \
;         acc[ai][bj][m][n] = __builtin_amdgcn_mfma_f32_16x16x32_bf16(Bt[n][k], At[m][k], acc[ai][bj][m][n], 0, 0, 0); __builtin_amdgcn_s_setprio(0); } while (0)
; template <class Epi, bool ALIGN_EPI = PG8_ALIGN, bool SP2 = PG8_SP2>
; __device__ __forceinline__ void gemm_phase(LAS uchar* lds, const Gemm g, const StaticOrder& S, const Epi& E) {
;     ...
;             PG8_LDB(B0, 0, 0); PG8_LDB(B1, 0, 1); PG8_SCHED; PG8_LDA(At, 0, 0); PG8_STAGE(PG8_SA(1, 1), a1 + hstepA, voffA);
;             PG8_WAIT_V(8); PG8_WAIT_L(0); PG8_BAR; PG8_MMA(0, 0, At, B0); PG8_MMA(0, 1, At, B1); PG8_BAR; PG8_SCHED;
;             PG8_LDA(At, 0, 1); PG8_STAGE(PG8_SB(0, 0), b2, voffB); PG8_STAGE(PG8_SB(0, 1), b2 + hstepB, voffB); PG8_STAGE(PG8_SA(0, 0), a2, voffA);
;             PG8_WAIT_V(8); PG8_WAIT_L(0); PG8_BAR; PG8_MMA(1, 0, At, B0); PG8_MMA(1, 1, At, B1); PG8_BAR; PG8_SCHED;
;             PG8_LDB(B0, 1, 0); PG8_LDB(B1, 1, 1); PG8_SCHED; PG8_LDA(At, 1, 0); PG8_STAGE(PG8_SA(0, 1), a2 + hstepA, voffA);
;             PG8_WAIT_V(8); PG8_WAIT_L(0); PG8_BAR; PG8_MMA(0, 0, At, B0); PG8_MMA(0, 1, At, B1); PG8_BAR; PG8_SCHED;
;             PG8_LDA(At, 1, 1); PG8_STAGE(PG8_SB(1, 0), b3, voffB); PG8_STAGE(PG8_SB(1, 1), b3 + hstepB, voffB); PG8_STAGE(PG8_SA(1, 0), a3, voffA);
;             PG8_WAIT_V(8); PG8_WAIT_L(0); PG8_BAR; PG8_MMA(1, 0, At, B0); PG8_MMA(1, 1, At, B1); PG8_BAR; PG8_SCHED;
;     ...
;         if constexpr (ALIGN_EPI) { if (wr == 0) PG8_BAR; }
	s_setprio 0
	s_add_i32 s12, s39, s22
	v_lshl_add_u64 v[228:229], v[228:229], 0, s[84:85]
	s_mov_b32 m0, s12
	ds_read_b128 v[196:199], v165 offset:49152
	ds_read_b128 v[200:203], v165 offset:50176
	ds_read_b128 v[204:207], v165 offset:51200
	ds_read_b128 v[208:211], v165 offset:52224
	ds_read_b128 v[212:215], v165 offset:53248
	ds_read_b128 v[216:219], v165 offset:54272
	ds_read_b128 v[220:223], v165 offset:55296
	ds_read_b128 v[224:227], v165 offset:56320
	global_load_lds_dwordx4 v[228:229], off
	s_add_i32 m0, s12, 0x2000
	s_add_u32 s12, s16, 0x44080
	v_lshl_add_u64 v[228:229], v[230:231], 0, s[84:85]
	s_addc_u32 s13, s17, 0
	s_add_i32 s16, s40, s22
	global_load_lds_dwordx4 v[228:229], off
	s_mov_b32 m0, s16
	v_lshl_add_u64 v[228:229], s[12:13], 0, v[132:133]
	global_load_lds_dwordx4 v[228:229], off
	s_add_i32 m0, s16, 0x2000
	v_lshl_add_u64 v[228:229], s[12:13], 0, v[152:153]
	global_load_lds_dwordx4 v[228:229], off
	s_mov_b32 m0, s27
	v_lshl_add_u64 v[228:229], v[232:233], 0, s[84:85]
	global_load_lds_dwordx4 v[228:229], off
	s_mov_b32 m0, s28
	v_lshl_add_u64 v[228:229], v[234:235], 0, s[84:85]
	global_load_lds_dwordx4 v[228:229], off
	s_setprio 1
	s_waitcnt vmcnt(8) lgkmcnt(0)
	s_barrier
	v_mfma_f32_16x16x32_bf16 v[62:65], v[160:163], v[196:199], v[62:65]
	v_mfma_f32_16x16x32_bf16 v[58:61], v[170:173], v[196:199], v[58:61]
	v_mfma_f32_16x16x32_bf16 v[54:57], v[160:163], v[204:207], v[54:57]
	v_mfma_f32_16x16x32_bf16 v[46:49], v[170:173], v[204:207], v[46:49]
	v_mfma_f32_16x16x32_bf16 v[38:41], v[160:163], v[212:215], v[38:41]
	v_mfma_f32_16x16x32_bf16 v[30:33], v[170:173], v[212:215], v[30:33]
	v_mfma_f32_16x16x32_bf16 v[22:25], v[160:163], v[220:223], v[22:25]
	v_mfma_f32_16x16x32_bf16 v[14:17], v[170:173], v[220:223], v[14:17]
	v_mfma_f32_16x16x32_bf16 v[62:65], v[166:169], v[200:203], v[62:65]
	v_mfma_f32_16x16x32_bf16 v[58:61], v[174:177], v[200:203], v[58:61]
	v_mfma_f32_16x16x32_bf16 v[54:57], v[166:169], v[208:211], v[54:57]
	v_mfma_f32_16x16x32_bf16 v[46:49], v[174:177], v[208:211], v[46:49]
	v_mfma_f32_16x16x32_bf16 v[38:41], v[166:169], v[216:219], v[38:41]
	v_mfma_f32_16x16x32_bf16 v[30:33], v[174:177], v[216:219], v[30:33]
	v_mfma_f32_16x16x32_bf16 v[22:25], v[166:169], v[224:227], v[22:25]
	v_mfma_f32_16x16x32_bf16 v[14:17], v[174:177], v[224:227], v[14:17]
	v_mfma_f32_16x16x32_bf16 v[50:53], v[178:181], v[196:199], v[50:53]
	v_mfma_f32_16x16x32_bf16 v[42:45], v[188:191], v[196:199], v[42:45]
	v_mfma_f32_16x16x32_bf16 v[34:37], v[178:181], v[204:207], v[34:37]
	v_mfma_f32_16x16x32_bf16 v[26:29], v[188:191], v[204:207], v[26:29]
	v_mfma_f32_16x16x32_bf16 v[18:21], v[178:181], v[212:215], v[18:21]
	v_mfma_f32_16x16x32_bf16 v[10:13], v[188:191], v[212:215], v[10:13]
	v_mfma_f32_16x16x32_bf16 v[6:9], v[178:181], v[220:223], v[6:9]
	v_mfma_f32_16x16x32_bf16 v[2:5], v[188:191], v[220:223], v[2:5]
	v_mfma_f32_16x16x32_bf16 v[50:53], v[184:187], v[200:203], v[50:53]
	v_mfma_f32_16x16x32_bf16 v[42:45], v[192:195], v[200:203], v[42:45]
	v_mfma_f32_16x16x32_bf16 v[34:37], v[184:187], v[208:211], v[34:37]
	v_mfma_f32_16x16x32_bf16 v[26:29], v[192:195], v[208:211], v[26:29]
	v_mfma_f32_16x16x32_bf16 v[18:21], v[184:187], v[216:219], v[18:21]
	v_mfma_f32_16x16x32_bf16 v[10:13], v[192:195], v[216:219], v[10:13]
	v_mfma_f32_16x16x32_bf16 v[6:9], v[184:187], v[224:227], v[6:9]
	v_mfma_f32_16x16x32_bf16 v[2:5], v[192:195], v[224:227], v[2:5]
	s_barrier
	s_setprio 0
	s_add_i32 s38, s38, 2
	s_add_u32 s36, s36, 0x100
	s_addc_u32 s37, s37, 0
	s_cmp_gt_u32 s38, 13
	s_mov_b64 s[12:13], s[14:15]
	s_cbranch_scc0 .LBB0_837
	s_and_b64 vcc, exec, s[8:9]
	s_cbranch_vccz .LBB0_840
	s_barrier

; #define PG8_STAGE(bufoff, gbase, voff) do { _Pragma("unroll") for (int _i = 0; _i < 2; ++_i) \
;         __builtin_amdgcn_global_load_lds((const unsigned*)((const char*)(gbase) + (voff)[_i]), (LAS unsigned*)(lds + (bufoff) + ldsw + _i * 8192), 16, 0, 0); } while (0)
; #define PG8_LDA(dst, b, h) do { _Pragma("unroll") for (int m = 0; m < 4; ++m) _Pragma("unroll") for (int k = 0; k < 2; ++k) dst[m][k] = *(const LAS bf16x8*)(lds + PG8_SA(b, h) + aoff + m * 2048 + k * 1024); } while (0)
; #define PG8_LDB(dst, b, h) do { _Pragma("unroll") for (int n = 0; n < 2; ++n) _Pragma("unroll") for (int k = 0; k < 2; ++k) dst[n][k] = *(const LAS bf16x8*)(lds + PG8_SB(b, h) + boff + n * 2048 + k * 1024); } while (0)
; #define PG8_MMA(ai, bj, At, Bt) do { __builtin_amdgcn_s_setprio(1); _Pragma("unroll") for (int m = 0; m < 4; ++m) _Pragma("unroll") for (int n = 0; n < 2; ++n) _Pragma("unroll") for (int k = 0; k < 2; ++k) \
;         acc[ai][bj][m][n] = __builtin_amdgcn_mfma_f32_16x16x32_bf16(Bt[n][k], At[m][k], acc[ai][bj][m][n], 0, 0, 0); __builtin_amdgcn_s_setprio(0); } while (0)
; #define PG8_WAIT_V(n) asm volatile("s_waitcnt vmcnt(" #n ")" ::: "memory")
; template <class Epi, bool ALIGN_EPI = PG8_ALIGN, bool SP2 = PG8_SP2>
; __device__ __forceinline__ void gemm_phase(LAS uchar* lds, const Gemm g, const StaticOrder& S, const Epi& E) {
;     ...
;             PG8_LDB(B0, 0, 0); PG8_LDB(B1, 0, 1); PG8_SCHED; PG8_LDA(At, 0, 0); PG8_STAGE(PG8_SA(1, 1), a1 + hstepA, voffA);
;             PG8_WAIT_V(8); PG8_WAIT_L(0); PG8_BAR; PG8_MMA(0, 0, At, B0); PG8_MMA(0, 1, At, B1); PG8_BAR; PG8_SCHED;
;             PG8_LDA(At, 0, 1); PG8_STAGE(PG8_SB(0, 0), b2, voffB); PG8_STAGE(PG8_SB(0, 1), b2 + hstepB, voffB); PG8_STAGE(PG8_SA(0, 0), a2, voffA);
;             PG8_WAIT_V(8); PG8_WAIT_L(0); PG8_BAR; PG8_MMA(1, 0, At, B0); PG8_MMA(1, 1, At, B1); PG8_BAR; PG8_SCHED;
;             PG8_LDB(B0, 1, 0); PG8_LDB(B1, 1, 1); PG8_SCHED; PG8_LDA(At, 1, 0); PG8_STAGE(PG8_SA(0, 1), a2 + hstepA, voffA);
;             PG8_WAIT_V(8); PG8_WAIT_L(0); PG8_BAR; PG8_MMA(0, 0, At, B0); PG8_MMA(0, 1, At, B1); PG8_BAR; PG8_SCHED;
;             PG8_LDA(At, 1, 1); PG8_STAGE(PG8_SB(1, 0), b3, voffB); PG8_STAGE(PG8_SB(1, 1), b3 + hstepB, voffB); PG8_STAGE(PG8_SA(1, 0), a3, voffA);
;             PG8_WAIT_V(8); PG8_WAIT_L(0); PG8_BAR; PG8_MMA(1, 0, At, B0); PG8_MMA(1, 1, At, B1); PG8_BAR; PG8_SCHED;
.Lrw_done_1050_0_pl:
	s_waitcnt lgkmcnt(0)
	s_nop 0
	s_setprio 1
	s_barrier
	v_mfma_f32_16x16x32_bf16 v[126:129], v[164:167], v[200:203], 0
	v_mfma_f32_16x16x32_bf16 v[118:121], v[172:175], v[200:203], 0
	v_mfma_f32_16x16x32_bf16 v[110:113], v[164:167], v[208:211], 0
	v_mfma_f32_16x16x32_bf16 v[102:105], v[172:175], v[208:211], 0
	v_mfma_f32_16x16x32_bf16 v[94:97], v[164:167], v[216:219], 0
	v_mfma_f32_16x16x32_bf16 v[86:89], v[172:175], v[216:219], 0
	v_mfma_f32_16x16x32_bf16 v[78:81], v[164:167], v[224:227], 0
	v_mfma_f32_16x16x32_bf16 v[70:73], v[172:175], v[224:227], 0
	v_mfma_f32_16x16x32_bf16 v[126:129], v[168:171], v[204:207], v[126:129]
	v_mfma_f32_16x16x32_bf16 v[118:121], v[176:179], v[204:207], v[118:121]
	v_mfma_f32_16x16x32_bf16 v[110:113], v[168:171], v[212:215], v[110:113]
	v_mfma_f32_16x16x32_bf16 v[102:105], v[176:179], v[212:215], v[102:105]
	v_mfma_f32_16x16x32_bf16 v[94:97], v[168:171], v[220:223], v[94:97]
	v_mfma_f32_16x16x32_bf16 v[86:89], v[176:179], v[220:223], v[86:89]
	v_mfma_f32_16x16x32_bf16 v[78:81], v[168:171], v[228:231], v[78:81]
	v_mfma_f32_16x16x32_bf16 v[70:73], v[176:179], v[228:231], v[70:73]
	v_mfma_f32_16x16x32_bf16 v[122:125], v[184:187], v[200:203], 0
	v_mfma_f32_16x16x32_bf16 v[114:117], v[192:195], v[200:203], 0
	v_mfma_f32_16x16x32_bf16 v[106:109], v[184:187], v[208:211], 0
	v_mfma_f32_16x16x32_bf16 v[98:101], v[192:195], v[208:211], 0
	v_mfma_f32_16x16x32_bf16 v[90:93], v[184:187], v[216:219], 0
	v_mfma_f32_16x16x32_bf16 v[82:85], v[192:195], v[216:219], 0
	v_mfma_f32_16x16x32_bf16 v[74:77], v[184:187], v[224:227], 0
	v_mfma_f32_16x16x32_bf16 v[66:69], v[192:195], v[224:227], 0
	v_mfma_f32_16x16x32_bf16 v[122:125], v[188:191], v[204:207], v[122:125]
	v_mfma_f32_16x16x32_bf16 v[114:117], v[196:199], v[204:207], v[114:117]
	v_mfma_f32_16x16x32_bf16 v[106:109], v[188:191], v[212:215], v[106:109]
	v_mfma_f32_16x16x32_bf16 v[98:101], v[196:199], v[212:215], v[98:101]
	v_mfma_f32_16x16x32_bf16 v[90:93], v[188:191], v[220:223], v[90:93]
	v_mfma_f32_16x16x32_bf16 v[82:85], v[196:199], v[220:223], v[82:85]
	v_mfma_f32_16x16x32_bf16 v[74:77], v[188:191], v[228:231], v[74:77]
	v_mfma_f32_16x16x32_bf16 v[66:69], v[196:199], v[228:231], v[66:69]
	s_barrier
	s_setprio 0
	s_add_i32 s12, s39, s21
	v_lshl_add_u64 v[160:161], s[16:17], 0, v[134:135]
	s_mov_b32 m0, s12
	ds_read_b128 v[200:203], v163 offset:16384
	ds_read_b128 v[204:207], v163 offset:17408
	ds_read_b128 v[208:211], v163 offset:18432
	ds_read_b128 v[212:215], v163 offset:19456
	ds_read_b128 v[216:219], v163 offset:20480
	ds_read_b128 v[220:223], v163 offset:21504
	ds_read_b128 v[224:227], v163 offset:22528
	ds_read_b128 v[228:231], v163 offset:23552
	global_load_lds_dwordx4 v[160:161], off
	s_add_i32 m0, s12, 0x2000
	s_add_u32 s12, s16, 0x44000
	v_lshl_add_u64 v[180:181], s[16:17], 0, v[130:131]
	s_addc_u32 s13, s17, 0
	s_add_i32 s39, s40, s21
	global_load_lds_dwordx4 v[180:181], off
	v_lshl_add_u64 v[232:233], s[12:13], 0, v[134:135]
	s_mov_b32 m0, s39
	global_load_lds_dwordx4 v[232:233], off
	s_add_i32 m0, s39, 0x2000
	v_lshl_add_u64 v[232:233], s[12:13], 0, v[130:131]
	global_load_lds_dwordx4 v[232:233], off
	s_mov_b32 m0, s23
	v_lshl_add_u64 v[232:233], s[18:19], 0, v[154:155]
	global_load_lds_dwordx4 v[232:233], off
	s_mov_b32 m0, s24
	v_lshl_add_u64 v[234:235], s[18:19], 0, v[132:133]
	global_load_lds_dwordx4 v[234:235], off
	s_cmp_lt_u32 s29, 2
	s_cbranch_scc1 .Lrw_std_1050_1_pl
	s_waitcnt vmcnt(16)
	s_branch .Lrw_done_1050_1_pl

; #define PG8_STAGE(bufoff, gbase, voff) do { _Pragma("unroll") for (int _i = 0; _i < 2; ++_i) \
;         __builtin_amdgcn_global_load_lds((const unsigned*)((const char*)(gbase) + (voff)[_i]), (LAS unsigned*)(lds + (bufoff) + ldsw + _i * 8192), 16, 0, 0); } while (0)
; #define PG8_LDA(dst, b, h) do { _Pragma("unroll") for (int m = 0; m < 4; ++m) _Pragma("unroll") for (int k = 0; k < 2; ++k) dst[m][k] = *(const LAS bf16x8*)(lds + PG8_SA(b, h) + aoff + m * 2048 + k * 1024); } while (0)
; #define PG8_LDB(dst, b, h) do { _Pragma("unroll") for (int n = 0; n < 2; ++n) _Pragma("unroll") for (int k = 0; k < 2; ++k) dst[n][k] = *(const LAS bf16x8*)(lds + PG8_SB(b, h) + boff + n * 2048 + k * 1024); } while (0)
; #define PG8_MMA(ai, bj, At, Bt) do { __builtin_amdgcn_s_setprio(1); _Pragma("unroll") for (int m = 0; m < 4; ++m) _Pragma("unroll") for (int n = 0; n < 2; ++n) _Pragma("unroll") for (int k = 0; k < 2; ++k) \
;         acc[ai][bj][m][n] = __builtin_amdgcn_mfma_f32_16x16x32_bf16(Bt[n][k], At[m][k], acc[ai][bj][m][n], 0, 0, 0); __builtin_amdgcn_s_setprio(0); } while (0)
; #define PG8_WAIT_V(n) asm volatile("s_waitcnt vmcnt(" #n ")" ::: "memory")
; template <class Epi, bool ALIGN_EPI = PG8_ALIGN, bool SP2 = PG8_SP2>
; __device__ __forceinline__ void gemm_phase(LAS uchar* lds, const Gemm g, const StaticOrder& S, const Epi& E) {
;     ...
;             PG8_LDB(B0, 0, 0); PG8_LDB(B1, 0, 1); PG8_SCHED; PG8_LDA(At, 0, 0); PG8_STAGE(PG8_SA(1, 1), a1 + hstepA, voffA);
;             PG8_WAIT_V(8); PG8_WAIT_L(0); PG8_BAR; PG8_MMA(0, 0, At, B0); PG8_MMA(0, 1, At, B1); PG8_BAR; PG8_SCHED;
;             PG8_LDA(At, 0, 1); PG8_STAGE(PG8_SB(0, 0), b2, voffB); PG8_STAGE(PG8_SB(0, 1), b2 + hstepB, voffB); PG8_STAGE(PG8_SA(0, 0), a2, voffA);
;             PG8_WAIT_V(8); PG8_WAIT_L(0); PG8_BAR; PG8_MMA(1, 0, At, B0); PG8_MMA(1, 1, At, B1); PG8_BAR; PG8_SCHED;
;             PG8_LDB(B0, 1, 0); PG8_LDB(B1, 1, 1); PG8_SCHED; PG8_LDA(At, 1, 0); PG8_STAGE(PG8_SA(0, 1), a2 + hstepA, voffA);
;             PG8_WAIT_V(8); PG8_WAIT_L(0); PG8_BAR; PG8_MMA(0, 0, At, B0); PG8_MMA(0, 1, At, B1); PG8_BAR; PG8_SCHED;
;             PG8_LDA(At, 1, 1); PG8_STAGE(PG8_SB(1, 0), b3, voffB); PG8_STAGE(PG8_SB(1, 1), b3 + hstepB, voffB); PG8_STAGE(PG8_SA(1, 0), a3, voffA);
;             PG8_WAIT_V(8); PG8_WAIT_L(0); PG8_BAR; PG8_MMA(1, 0, At, B0); PG8_MMA(1, 1, At, B1); PG8_BAR; PG8_SCHED;
.Lrw_done_1050_1_pl:
	s_waitcnt lgkmcnt(0)
	s_nop 0
	s_setprio 1
	s_barrier
	v_mfma_f32_16x16x32_bf16 v[62:65], v[164:167], v[200:203], 0
	v_mfma_f32_16x16x32_bf16 v[54:57], v[172:175], v[200:203], 0
	v_mfma_f32_16x16x32_bf16 v[46:49], v[164:167], v[208:211], 0
	v_mfma_f32_16x16x32_bf16 v[38:41], v[172:175], v[208:211], 0
	v_mfma_f32_16x16x32_bf16 v[30:33], v[164:167], v[216:219], 0
	v_mfma_f32_16x16x32_bf16 v[22:25], v[172:175], v[216:219], 0
	v_mfma_f32_16x16x32_bf16 v[14:17], v[164:167], v[224:227], 0
	v_mfma_f32_16x16x32_bf16 v[6:9], v[172:175], v[224:227], 0
	v_mfma_f32_16x16x32_bf16 v[62:65], v[168:171], v[204:207], v[62:65]
	v_mfma_f32_16x16x32_bf16 v[54:57], v[176:179], v[204:207], v[54:57]
	v_mfma_f32_16x16x32_bf16 v[46:49], v[168:171], v[212:215], v[46:49]
	v_mfma_f32_16x16x32_bf16 v[38:41], v[176:179], v[212:215], v[38:41]
	v_mfma_f32_16x16x32_bf16 v[30:33], v[168:171], v[220:223], v[30:33]
	v_mfma_f32_16x16x32_bf16 v[22:25], v[176:179], v[220:223], v[22:25]
	v_mfma_f32_16x16x32_bf16 v[14:17], v[168:171], v[228:231], v[14:17]
	v_mfma_f32_16x16x32_bf16 v[6:9], v[176:179], v[228:231], v[6:9]
	v_mfma_f32_16x16x32_bf16 v[58:61], v[184:187], v[200:203], 0
	v_mfma_f32_16x16x32_bf16 v[50:53], v[192:195], v[200:203], 0
	v_mfma_f32_16x16x32_bf16 v[42:45], v[184:187], v[208:211], 0
	v_mfma_f32_16x16x32_bf16 v[34:37], v[192:195], v[208:211], 0
	v_mfma_f32_16x16x32_bf16 v[26:29], v[184:187], v[216:219], 0
	v_mfma_f32_16x16x32_bf16 v[18:21], v[192:195], v[216:219], 0
	v_mfma_f32_16x16x32_bf16 v[10:13], v[184:187], v[224:227], 0
	v_mfma_f32_16x16x32_bf16 v[2:5], v[192:195], v[224:227], 0
	v_mfma_f32_16x16x32_bf16 v[58:61], v[188:191], v[204:207], v[58:61]
	v_mfma_f32_16x16x32_bf16 v[50:53], v[196:199], v[204:207], v[50:53]
	v_mfma_f32_16x16x32_bf16 v[42:45], v[188:191], v[212:215], v[42:45]
	v_mfma_f32_16x16x32_bf16 v[34:37], v[196:199], v[212:215], v[34:37]
	v_mfma_f32_16x16x32_bf16 v[26:29], v[188:191], v[220:223], v[26:29]
	v_mfma_f32_16x16x32_bf16 v[18:21], v[196:199], v[220:223], v[18:21]
	v_mfma_f32_16x16x32_bf16 v[10:13], v[188:191], v[228:231], v[10:13]
	v_mfma_f32_16x16x32_bf16 v[2:5], v[196:199], v[228:231], v[2:5]
	s_barrier
	s_setprio 0
	s_add_i32 s39, 0, 0x18000
	v_add_u32_e32 v144, s39, v139
	s_add_i32 s40, 0, 0x1c000
	ds_read_b128 v[164:167], v144
	ds_read_b128 v[168:171], v144 offset:1024
	ds_read_b128 v[172:175], v144 offset:2048
	ds_read_b128 v[176:179], v144 offset:3072
	v_add_u32_e32 v144, s40, v139
	ds_read_b128 v[184:187], v144
	ds_read_b128 v[188:191], v144 offset:1024
	ds_read_b128 v[192:195], v144 offset:2048
	ds_read_b128 v[196:199], v144 offset:3072
	s_add_u32 s12, s18, 0x44000
	s_addc_u32 s13, s19, 0
	s_mov_b32 m0, s25
	v_lshl_add_u64 v[236:237], s[12:13], 0, v[154:155]
	ds_read_b128 v[200:203], v163 offset:32768
	ds_read_b128 v[204:207], v163 offset:33792
	ds_read_b128 v[208:211], v163 offset:34816
	ds_read_b128 v[212:215], v163 offset:35840
	ds_read_b128 v[216:219], v163 offset:36864
	ds_read_b128 v[220:223], v163 offset:37888
	ds_read_b128 v[224:227], v163 offset:38912
	ds_read_b128 v[228:231], v163 offset:39936
	global_load_lds_dwordx4 v[236:237], off
	s_mov_b32 m0, s26
	v_lshl_add_u64 v[236:237], s[12:13], 0, v[132:133]
	global_load_lds_dwordx4 v[236:237], off
	s_setprio 1
	s_waitcnt vmcnt(8) lgkmcnt(0)
	s_barrier
	v_mfma_f32_16x16x32_bf16 v[126:129], v[164:167], v[200:203], v[126:129]
	v_mfma_f32_16x16x32_bf16 v[118:121], v[172:175], v[200:203], v[118:121]
	v_mfma_f32_16x16x32_bf16 v[110:113], v[164:167], v[208:211], v[110:113]
	v_mfma_f32_16x16x32_bf16 v[102:105], v[172:175], v[208:211], v[102:105]
	v_mfma_f32_16x16x32_bf16 v[94:97], v[164:167], v[216:219], v[94:97]
	v_mfma_f32_16x16x32_bf16 v[86:89], v[172:175], v[216:219], v[86:89]
	v_mfma_f32_16x16x32_bf16 v[78:81], v[164:167], v[224:227], v[78:81]
	v_mfma_f32_16x16x32_bf16 v[70:73], v[172:175], v[224:227], v[70:73]
	v_mfma_f32_16x16x32_bf16 v[126:129], v[168:171], v[204:207], v[126:129]
	v_mfma_f32_16x16x32_bf16 v[118:121], v[176:179], v[204:207], v[118:121]
	v_mfma_f32_16x16x32_bf16 v[110:113], v[168:171], v[212:215], v[110:113]
	v_mfma_f32_16x16x32_bf16 v[102:105], v[176:179], v[212:215], v[102:105]
	v_mfma_f32_16x16x32_bf16 v[94:97], v[168:171], v[220:223], v[94:97]
	v_mfma_f32_16x16x32_bf16 v[86:89], v[176:179], v[220:223], v[86:89]
	v_mfma_f32_16x16x32_bf16 v[78:81], v[168:171], v[228:231], v[78:81]
	v_mfma_f32_16x16x32_bf16 v[70:73], v[176:179], v[228:231], v[70:73]
	v_mfma_f32_16x16x32_bf16 v[122:125], v[184:187], v[200:203], v[122:125]
	v_mfma_f32_16x16x32_bf16 v[114:117], v[192:195], v[200:203], v[114:117]
	v_mfma_f32_16x16x32_bf16 v[106:109], v[184:187], v[208:211], v[106:109]
	v_mfma_f32_16x16x32_bf16 v[98:101], v[192:195], v[208:211], v[98:101]
	v_mfma_f32_16x16x32_bf16 v[90:93], v[184:187], v[216:219], v[90:93]
	v_mfma_f32_16x16x32_bf16 v[82:85], v[192:195], v[216:219], v[82:85]
	v_mfma_f32_16x16x32_bf16 v[74:77], v[184:187], v[224:227], v[74:77]
	v_mfma_f32_16x16x32_bf16 v[66:69], v[192:195], v[224:227], v[66:69]
	v_mfma_f32_16x16x32_bf16 v[122:125], v[188:191], v[204:207], v[122:125]
	v_mfma_f32_16x16x32_bf16 v[114:117], v[196:199], v[204:207], v[114:117]
	v_mfma_f32_16x16x32_bf16 v[106:109], v[188:191], v[212:215], v[106:109]
	v_mfma_f32_16x16x32_bf16 v[98:101], v[196:199], v[212:215], v[98:101]
	v_mfma_f32_16x16x32_bf16 v[90:93], v[188:191], v[220:223], v[90:93]
	v_mfma_f32_16x16x32_bf16 v[82:85], v[196:199], v[220:223], v[82:85]
	v_mfma_f32_16x16x32_bf16 v[74:77], v[188:191], v[228:231], v[74:77]
	v_mfma_f32_16x16x32_bf16 v[66:69], v[196:199], v[228:231], v[66:69]
	s_barrier
; #define PG8_STAGE(bufoff, gbase, voff) do { _Pragma("unroll") for (int _i = 0; _i < 2; ++_i) \
;         __builtin_amdgcn_global_load_lds((const unsigned*)((const char*)(gbase) + (voff)[_i]), (LAS unsigned*)(lds + (bufoff) + ldsw + _i * 8192), 16, 0, 0); } while (0)
; #define PG8_LDA(dst, b, h) do { _Pragma("unroll") for (int m = 0; m < 4; ++m) _Pragma("unroll") for (int k = 0; k < 2; ++k) dst[m][k] = *(const LAS bf16x8*)(lds + PG8_SA(b, h) + aoff + m * 2048 + k * 1024); } while (0)
; #define PG8_LDB(dst, b, h) do { _Pragma("unroll") for (int n = 0; n < 2; ++n) _Pragma("unroll") for (int k = 0; k < 2; ++k) dst[n][k] = *(const LAS bf16x8*)(lds + PG8_SB(b, h) + boff + n * 2048 + k * 1024); } while (0)
; #define PG8_MMA(ai, bj, At, Bt) do { __builtin_amdgcn_s_setprio(1); _Pragma("unroll") for (int m = 0; m < 4; ++m) _Pragma("unroll") for (int n = 0; n < 2; ++n) _Pragma("unroll") for (int k = 0; k < 2; ++k) \
;         acc[ai][bj][m][n] = __builtin_amdgcn_mfma_f32_16x16x32_bf16(Bt[n][k], At[m][k], acc[ai][bj][m][n], 0, 0, 0); __builtin_amdgcn_s_setprio(0); } while (0)
; #define PG8_WAIT_V(n) asm volatile("s_waitcnt vmcnt(" #n ")" ::: "memory")
; template <class Epi, bool ALIGN_EPI = PG8_ALIGN, bool SP2 = PG8_SP2>
; __device__ __forceinline__ void gemm_phase(LAS uchar* lds, const Gemm g, const StaticOrder& S, const Epi& E) {
;     ...
;             PG8_LDB(B0, 0, 0); PG8_LDB(B1, 0, 1); PG8_SCHED; PG8_LDA(At, 0, 0); PG8_STAGE(PG8_SA(1, 1), a1 + hstepA, voffA);
;             PG8_WAIT_V(8); PG8_WAIT_L(0); PG8_BAR; PG8_MMA(0, 0, At, B0); PG8_MMA(0, 1, At, B1); PG8_BAR; PG8_SCHED;
;             PG8_LDA(At, 0, 1); PG8_STAGE(PG8_SB(0, 0), b2, voffB); PG8_STAGE(PG8_SB(0, 1), b2 + hstepB, voffB); PG8_STAGE(PG8_SA(0, 0), a2, voffA);
;             PG8_WAIT_V(8); PG8_WAIT_L(0); PG8_BAR; PG8_MMA(1, 0, At, B0); PG8_MMA(1, 1, At, B1); PG8_BAR; PG8_SCHED;
;             PG8_LDB(B0, 1, 0); PG8_LDB(B1, 1, 1); PG8_SCHED; PG8_LDA(At, 1, 0); PG8_STAGE(PG8_SA(0, 1), a2 + hstepA, voffA);
;             PG8_WAIT_V(8); PG8_WAIT_L(0); PG8_BAR; PG8_MMA(0, 0, At, B0); PG8_MMA(0, 1, At, B1); PG8_BAR; PG8_SCHED;
;             PG8_LDA(At, 1, 1); PG8_STAGE(PG8_SB(1, 0), b3, voffB); PG8_STAGE(PG8_SB(1, 1), b3 + hstepB, voffB); PG8_STAGE(PG8_SA(1, 0), a3, voffA);
;             PG8_WAIT_V(8); PG8_WAIT_L(0); PG8_BAR; PG8_MMA(1, 0, At, B0); PG8_MMA(1, 1, At, B1); PG8_BAR; PG8_SCHED;
	s_setprio 0
	s_add_i32 s12, s39, s21
	v_lshl_add_u64 v[160:161], v[160:161], 0, s[84:85]
	s_mov_b32 m0, s12
	ds_read_b128 v[200:203], v163 offset:49152
	ds_read_b128 v[204:207], v163 offset:50176
	ds_read_b128 v[208:211], v163 offset:51200
	ds_read_b128 v[212:215], v163 offset:52224
	ds_read_b128 v[216:219], v163 offset:53248
	ds_read_b128 v[220:223], v163 offset:54272
	ds_read_b128 v[224:227], v163 offset:55296
	ds_read_b128 v[228:231], v163 offset:56320
	global_load_lds_dwordx4 v[160:161], off
	s_add_i32 m0, s12, 0x2000
	s_add_u32 s12, s16, 0x44080
	v_lshl_add_u64 v[160:161], v[180:181], 0, s[84:85]
	s_addc_u32 s13, s17, 0
	s_add_i32 s16, s40, s21
	global_load_lds_dwordx4 v[160:161], off
	s_mov_b32 m0, s16
	v_lshl_add_u64 v[160:161], s[12:13], 0, v[134:135]
	global_load_lds_dwordx4 v[160:161], off
	s_add_i32 m0, s16, 0x2000
	v_lshl_add_u64 v[160:161], s[12:13], 0, v[130:131]
	global_load_lds_dwordx4 v[160:161], off
	s_mov_b32 m0, s27
	v_lshl_add_u64 v[160:161], v[232:233], 0, s[84:85]
	global_load_lds_dwordx4 v[160:161], off
	s_mov_b32 m0, s28
	v_lshl_add_u64 v[160:161], v[234:235], 0, s[84:85]
	global_load_lds_dwordx4 v[160:161], off
	s_setprio 1
	s_waitcnt vmcnt(8) lgkmcnt(0)
	s_barrier
	v_mfma_f32_16x16x32_bf16 v[62:65], v[164:167], v[200:203], v[62:65]
	v_mfma_f32_16x16x32_bf16 v[54:57], v[172:175], v[200:203], v[54:57]
	v_mfma_f32_16x16x32_bf16 v[46:49], v[164:167], v[208:211], v[46:49]
	v_mfma_f32_16x16x32_bf16 v[38:41], v[172:175], v[208:211], v[38:41]
	v_mfma_f32_16x16x32_bf16 v[30:33], v[164:167], v[216:219], v[30:33]
	v_mfma_f32_16x16x32_bf16 v[22:25], v[172:175], v[216:219], v[22:25]
	v_mfma_f32_16x16x32_bf16 v[14:17], v[164:167], v[224:227], v[14:17]
	v_mfma_f32_16x16x32_bf16 v[6:9], v[172:175], v[224:227], v[6:9]
	v_mfma_f32_16x16x32_bf16 v[62:65], v[168:171], v[204:207], v[62:65]
	v_mfma_f32_16x16x32_bf16 v[54:57], v[176:179], v[204:207], v[54:57]
	v_mfma_f32_16x16x32_bf16 v[46:49], v[168:171], v[212:215], v[46:49]
	v_mfma_f32_16x16x32_bf16 v[38:41], v[176:179], v[212:215], v[38:41]
	v_mfma_f32_16x16x32_bf16 v[30:33], v[168:171], v[220:223], v[30:33]
	v_mfma_f32_16x16x32_bf16 v[22:25], v[176:179], v[220:223], v[22:25]
	v_mfma_f32_16x16x32_bf16 v[14:17], v[168:171], v[228:231], v[14:17]
	v_mfma_f32_16x16x32_bf16 v[6:9], v[176:179], v[228:231], v[6:9]
	v_mfma_f32_16x16x32_bf16 v[58:61], v[184:187], v[200:203], v[58:61]
	v_mfma_f32_16x16x32_bf16 v[50:53], v[192:195], v[200:203], v[50:53]
	v_mfma_f32_16x16x32_bf16 v[42:45], v[184:187], v[208:211], v[42:45]
	v_mfma_f32_16x16x32_bf16 v[34:37], v[192:195], v[208:211], v[34:37]
	v_mfma_f32_16x16x32_bf16 v[26:29], v[184:187], v[216:219], v[26:29]
	v_mfma_f32_16x16x32_bf16 v[18:21], v[192:195], v[216:219], v[18:21]
	v_mfma_f32_16x16x32_bf16 v[10:13], v[184:187], v[224:227], v[10:13]
	v_mfma_f32_16x16x32_bf16 v[2:5], v[192:195], v[224:227], v[2:5]
	v_mfma_f32_16x16x32_bf16 v[58:61], v[188:191], v[204:207], v[58:61]
	v_mfma_f32_16x16x32_bf16 v[50:53], v[196:199], v[204:207], v[50:53]
	v_mfma_f32_16x16x32_bf16 v[42:45], v[188:191], v[212:215], v[42:45]
	v_mfma_f32_16x16x32_bf16 v[34:37], v[196:199], v[212:215], v[34:37]
	v_mfma_f32_16x16x32_bf16 v[26:29], v[188:191], v[220:223], v[26:29]
	v_mfma_f32_16x16x32_bf16 v[18:21], v[196:199], v[220:223], v[18:21]
	v_mfma_f32_16x16x32_bf16 v[10:13], v[188:191], v[228:231], v[10:13]
	v_mfma_f32_16x16x32_bf16 v[2:5], v[196:199], v[228:231], v[2:5]
	s_barrier
	s_setprio 0
	s_add_i32 s38, s38, 2
	s_add_u32 s36, s36, 0x100
	s_addc_u32 s37, s37, 0
	s_cmp_gt_u32 s38, 13
	s_mov_b64 s[12:13], s[14:15]
.LBB0_1050:
	s_add_u32 s14, s12, 0x100
	s_addc_u32 s15, s13, 0
	s_add_i32 s39, 0, 0x10000
	s_cmp_eq_u32 s38, 12
	s_cselect_b32 s19, s1, s15
	s_cselect_b32 s18, s0, s14
	v_add_u32_e32 v144, s39, v139
	s_cselect_b32 s17, s11, s37
	s_cselect_b32 s16, s10, s36
	s_add_i32 s40, 0, 0x14000
	ds_read_b128 v[164:167], v144
	ds_read_b128 v[168:171], v144 offset:1024
	ds_read_b128 v[172:175], v144 offset:2048
	ds_read_b128 v[176:179], v144 offset:3072
	v_add_u32_e32 v144, s40, v139
	ds_read_b128 v[184:187], v144
	ds_read_b128 v[188:191], v144 offset:1024
	ds_read_b128 v[192:195], v144 offset:2048
	ds_read_b128 v[196:199], v144 offset:3072
	v_lshl_add_u64 v[160:161], s[12:13], 0, v[156:157]
	s_add_i32 m0, s23, 0xc000
	ds_read_b128 v[200:203], v163
	ds_read_b128 v[204:207], v163 offset:1024
	ds_read_b128 v[208:211], v163 offset:2048
	ds_read_b128 v[212:215], v163 offset:3072
	ds_read_b128 v[216:219], v163 offset:4096
	ds_read_b128 v[220:223], v163 offset:5120
	ds_read_b128 v[224:227], v163 offset:6144
	ds_read_b128 v[228:231], v163 offset:7168
	global_load_lds_dwordx4 v[160:161], off
	s_add_i32 m0, s23, 0xe000
	v_lshl_add_u64 v[160:161], s[12:13], 0, v[158:159]
	global_load_lds_dwordx4 v[160:161], off
	s_nop 0
	s_setprio 1
	s_waitcnt vmcnt(8) lgkmcnt(0)
	s_barrier
; #define PG8_STAGE(bufoff, gbase, voff) do { _Pragma("unroll") for (int _i = 0; _i < 2; ++_i) \
;         __builtin_amdgcn_global_load_lds((const unsigned*)((const char*)(gbase) + (voff)[_i]), (LAS unsigned*)(lds + (bufoff) + ldsw + _i * 8192), 16, 0, 0); } while (0)
; #define PG8_LDA(dst, b, h) do { _Pragma("unroll") for (int m = 0; m < 4; ++m) _Pragma("unroll") for (int k = 0; k < 2; ++k) dst[m][k] = *(const LAS bf16x8*)(lds + PG8_SA(b, h) + aoff + m * 2048 + k * 1024); } while (0)
; #define PG8_LDB(dst, b, h) do { _Pragma("unroll") for (int n = 0; n < 2; ++n) _Pragma("unroll") for (int k = 0; k < 2; ++k) dst[n][k] = *(const LAS bf16x8*)(lds + PG8_SB(b, h) + boff + n * 2048 + k * 1024); } while (0)
; #define PG8_MMA(ai, bj, At, Bt) do { __builtin_amdgcn_s_setprio(1); _Pragma("unroll") for (int m = 0; m < 4; ++m) _Pragma("unroll") for (int n = 0; n < 2; ++n) _Pragma("unroll") for (int k = 0; k < 2; ++k) \
;         acc[ai][bj][m][n] = __builtin_amdgcn_mfma_f32_16x16x32_bf16(Bt[n][k], At[m][k], acc[ai][bj][m][n], 0, 0, 0); __builtin_amdgcn_s_setprio(0); } while (0)
; #define PG8_WAIT_V(n) asm volatile("s_waitcnt vmcnt(" #n ")" ::: "memory")
; template <class Epi, bool ALIGN_EPI = PG8_ALIGN, bool SP2 = PG8_SP2>
; __device__ __forceinline__ void gemm_phase(LAS uchar* lds, const Gemm g, const StaticOrder& S, const Epi& E) {
;     ...
;             PG8_LDB(B0, 0, 0); PG8_LDB(B1, 0, 1); PG8_SCHED; PG8_LDA(At, 0, 0); PG8_STAGE(PG8_SA(1, 1), a1 + hstepA, voffA);
;             PG8_WAIT_V(8); PG8_WAIT_L(0); PG8_BAR; PG8_MMA(0, 0, At, B0); PG8_MMA(0, 1, At, B1); PG8_BAR; PG8_SCHED;
;             PG8_LDA(At, 0, 1); PG8_STAGE(PG8_SB(0, 0), b2, voffB); PG8_STAGE(PG8_SB(0, 1), b2 + hstepB, voffB); PG8_STAGE(PG8_SA(0, 0), a2, voffA);
;             PG8_WAIT_V(8); PG8_WAIT_L(0); PG8_BAR; PG8_MMA(1, 0, At, B0); PG8_MMA(1, 1, At, B1); PG8_BAR; PG8_SCHED;
;             PG8_LDB(B0, 1, 0); PG8_LDB(B1, 1, 1); PG8_SCHED; PG8_LDA(At, 1, 0); PG8_STAGE(PG8_SA(0, 1), a2 + hstepA, voffA);
;             PG8_WAIT_V(8); PG8_WAIT_L(0); PG8_BAR; PG8_MMA(0, 0, At, B0); PG8_MMA(0, 1, At, B1); PG8_BAR; PG8_SCHED;
;             PG8_LDA(At, 1, 1); PG8_STAGE(PG8_SB(1, 0), b3, voffB); PG8_STAGE(PG8_SB(1, 1), b3 + hstepB, voffB); PG8_STAGE(PG8_SA(1, 0), a3, voffA);
;             PG8_WAIT_V(8); PG8_WAIT_L(0); PG8_BAR; PG8_MMA(1, 0, At, B0); PG8_MMA(1, 1, At, B1); PG8_BAR; PG8_SCHED;
	v_mfma_f32_16x16x32_bf16 v[126:129], v[164:167], v[200:203], v[126:129]
	v_mfma_f32_16x16x32_bf16 v[118:121], v[172:175], v[200:203], v[118:121]
	v_mfma_f32_16x16x32_bf16 v[110:113], v[164:167], v[208:211], v[110:113]
	v_mfma_f32_16x16x32_bf16 v[102:105], v[172:175], v[208:211], v[102:105]
	v_mfma_f32_16x16x32_bf16 v[94:97], v[164:167], v[216:219], v[94:97]
	v_mfma_f32_16x16x32_bf16 v[86:89], v[172:175], v[216:219], v[86:89]
	v_mfma_f32_16x16x32_bf16 v[78:81], v[164:167], v[224:227], v[78:81]
	v_mfma_f32_16x16x32_bf16 v[70:73], v[172:175], v[224:227], v[70:73]
	v_mfma_f32_16x16x32_bf16 v[126:129], v[168:171], v[204:207], v[126:129]
	v_mfma_f32_16x16x32_bf16 v[118:121], v[176:179], v[204:207], v[118:121]
	v_mfma_f32_16x16x32_bf16 v[110:113], v[168:171], v[212:215], v[110:113]
	v_mfma_f32_16x16x32_bf16 v[102:105], v[176:179], v[212:215], v[102:105]
	v_mfma_f32_16x16x32_bf16 v[94:97], v[168:171], v[220:223], v[94:97]
	v_mfma_f32_16x16x32_bf16 v[86:89], v[176:179], v[220:223], v[86:89]
	v_mfma_f32_16x16x32_bf16 v[78:81], v[168:171], v[228:231], v[78:81]
	v_mfma_f32_16x16x32_bf16 v[70:73], v[176:179], v[228:231], v[70:73]
	v_mfma_f32_16x16x32_bf16 v[122:125], v[184:187], v[200:203], v[122:125]
	v_mfma_f32_16x16x32_bf16 v[114:117], v[192:195], v[200:203], v[114:117]
	v_mfma_f32_16x16x32_bf16 v[106:109], v[184:187], v[208:211], v[106:109]
	v_mfma_f32_16x16x32_bf16 v[98:101], v[192:195], v[208:211], v[98:101]
	v_mfma_f32_16x16x32_bf16 v[90:93], v[184:187], v[216:219], v[90:93]
	v_mfma_f32_16x16x32_bf16 v[82:85], v[192:195], v[216:219], v[82:85]
	v_mfma_f32_16x16x32_bf16 v[74:77], v[184:187], v[224:227], v[74:77]
	v_mfma_f32_16x16x32_bf16 v[66:69], v[192:195], v[224:227], v[66:69]
	v_mfma_f32_16x16x32_bf16 v[122:125], v[188:191], v[204:207], v[122:125]
	v_mfma_f32_16x16x32_bf16 v[114:117], v[196:199], v[204:207], v[114:117]
	v_mfma_f32_16x16x32_bf16 v[106:109], v[188:191], v[212:215], v[106:109]
	v_mfma_f32_16x16x32_bf16 v[98:101], v[196:199], v[212:215], v[98:101]
	v_mfma_f32_16x16x32_bf16 v[90:93], v[188:191], v[220:223], v[90:93]
	v_mfma_f32_16x16x32_bf16 v[82:85], v[196:199], v[220:223], v[82:85]
	v_mfma_f32_16x16x32_bf16 v[74:77], v[188:191], v[228:231], v[74:77]
	v_mfma_f32_16x16x32_bf16 v[66:69], v[196:199], v[228:231], v[66:69]
	s_barrier
	s_setprio 0
	s_add_i32 s12, s39, s21
	v_lshl_add_u64 v[160:161], s[16:17], 0, v[134:135]
	s_mov_b32 m0, s12
	ds_read_b128 v[200:203], v163 offset:16384
	ds_read_b128 v[204:207], v163 offset:17408
	ds_read_b128 v[208:211], v163 offset:18432
	ds_read_b128 v[212:215], v163 offset:19456
	ds_read_b128 v[216:219], v163 offset:20480
	ds_read_b128 v[220:223], v163 offset:21504
	ds_read_b128 v[224:227], v163 offset:22528
	ds_read_b128 v[228:231], v163 offset:23552
	global_load_lds_dwordx4 v[160:161], off
	s_add_i32 m0, s12, 0x2000
	s_add_u32 s12, s16, 0x44000
	v_lshl_add_u64 v[180:181], s[16:17], 0, v[130:131]
	s_addc_u32 s13, s17, 0
	s_add_i32 s39, s40, s21
	global_load_lds_dwordx4 v[180:181], off
	v_lshl_add_u64 v[232:233], s[12:13], 0, v[134:135]
	s_mov_b32 m0, s39
	global_load_lds_dwordx4 v[232:233], off
	s_add_i32 m0, s39, 0x2000
	v_lshl_add_u64 v[232:233], s[12:13], 0, v[130:131]
	global_load_lds_dwordx4 v[232:233], off
	s_mov_b32 m0, s23
	v_lshl_add_u64 v[232:233], s[18:19], 0, v[154:155]
	global_load_lds_dwordx4 v[232:233], off
	s_mov_b32 m0, s24
	v_lshl_add_u64 v[234:235], s[18:19], 0, v[132:133]
	global_load_lds_dwordx4 v[234:235], off
	s_setprio 1
	s_waitcnt vmcnt(8) lgkmcnt(0)
	s_barrier
	v_mfma_f32_16x16x32_bf16 v[62:65], v[164:167], v[200:203], v[62:65]
	v_mfma_f32_16x16x32_bf16 v[54:57], v[172:175], v[200:203], v[54:57]
	v_mfma_f32_16x16x32_bf16 v[46:49], v[164:167], v[208:211], v[46:49]
	v_mfma_f32_16x16x32_bf16 v[38:41], v[172:175], v[208:211], v[38:41]
	v_mfma_f32_16x16x32_bf16 v[30:33], v[164:167], v[216:219], v[30:33]
	v_mfma_f32_16x16x32_bf16 v[22:25], v[172:175], v[216:219], v[22:25]
	v_mfma_f32_16x16x32_bf16 v[14:17], v[164:167], v[224:227], v[14:17]
	v_mfma_f32_16x16x32_bf16 v[6:9], v[172:175], v[224:227], v[6:9]
	v_mfma_f32_16x16x32_bf16 v[62:65], v[168:171], v[204:207], v[62:65]
	v_mfma_f32_16x16x32_bf16 v[54:57], v[176:179], v[204:207], v[54:57]
	v_mfma_f32_16x16x32_bf16 v[46:49], v[168:171], v[212:215], v[46:49]
	v_mfma_f32_16x16x32_bf16 v[38:41], v[176:179], v[212:215], v[38:41]
	v_mfma_f32_16x16x32_bf16 v[30:33], v[168:171], v[220:223], v[30:33]
	v_mfma_f32_16x16x32_bf16 v[22:25], v[176:179], v[220:223], v[22:25]
	v_mfma_f32_16x16x32_bf16 v[14:17], v[168:171], v[228:231], v[14:17]
	v_mfma_f32_16x16x32_bf16 v[6:9], v[176:179], v[228:231], v[6:9]
	v_mfma_f32_16x16x32_bf16 v[58:61], v[184:187], v[200:203], v[58:61]
	v_mfma_f32_16x16x32_bf16 v[50:53], v[192:195], v[200:203], v[50:53]
	v_mfma_f32_16x16x32_bf16 v[42:45], v[184:187], v[208:211], v[42:45]
	v_mfma_f32_16x16x32_bf16 v[34:37], v[192:195], v[208:211], v[34:37]
	v_mfma_f32_16x16x32_bf16 v[26:29], v[184:187], v[216:219], v[26:29]
	v_mfma_f32_16x16x32_bf16 v[18:21], v[192:195], v[216:219], v[18:21]
	v_mfma_f32_16x16x32_bf16 v[10:13], v[184:187], v[224:227], v[10:13]
	v_mfma_f32_16x16x32_bf16 v[2:5], v[192:195], v[224:227], v[2:5]
	v_mfma_f32_16x16x32_bf16 v[58:61], v[188:191], v[204:207], v[58:61]
	v_mfma_f32_16x16x32_bf16 v[50:53], v[196:199], v[204:207], v[50:53]
	v_mfma_f32_16x16x32_bf16 v[42:45], v[188:191], v[212:215], v[42:45]
	v_mfma_f32_16x16x32_bf16 v[34:37], v[196:199], v[212:215], v[34:37]
	v_mfma_f32_16x16x32_bf16 v[26:29], v[188:191], v[220:223], v[26:29]
	v_mfma_f32_16x16x32_bf16 v[18:21], v[196:199], v[220:223], v[18:21]
	v_mfma_f32_16x16x32_bf16 v[10:13], v[188:191], v[228:231], v[10:13]
	v_mfma_f32_16x16x32_bf16 v[2:5], v[196:199], v[228:231], v[2:5]
	s_barrier
; #define PG8_STAGE(bufoff, gbase, voff) do { _Pragma("unroll") for (int _i = 0; _i < 2; ++_i) \
;         __builtin_amdgcn_global_load_lds((const unsigned*)((const char*)(gbase) + (voff)[_i]), (LAS unsigned*)(lds + (bufoff) + ldsw + _i * 8192), 16, 0, 0); } while (0)
; #define PG8_LDA(dst, b, h) do { _Pragma("unroll") for (int m = 0; m < 4; ++m) _Pragma("unroll") for (int k = 0; k < 2; ++k) dst[m][k] = *(const LAS bf16x8*)(lds + PG8_SA(b, h) + aoff + m * 2048 + k * 1024); } while (0)
; #define PG8_LDB(dst, b, h) do { _Pragma("unroll") for (int n = 0; n < 2; ++n) _Pragma("unroll") for (int k = 0; k < 2; ++k) dst[n][k] = *(const LAS bf16x8*)(lds + PG8_SB(b, h) + boff + n * 2048 + k * 1024); } while (0)
; #define PG8_MMA(ai, bj, At, Bt) do { __builtin_amdgcn_s_setprio(1); _Pragma("unroll") for (int m = 0; m < 4; ++m) _Pragma("unroll") for (int n = 0; n < 2; ++n) _Pragma("unroll") for (int k = 0; k < 2; ++k) \
;         acc[ai][bj][m][n] = __builtin_amdgcn_mfma_f32_16x16x32_bf16(Bt[n][k], At[m][k], acc[ai][bj][m][n], 0, 0, 0); __builtin_amdgcn_s_setprio(0); } while (0)
; #define PG8_WAIT_V(n) asm volatile("s_waitcnt vmcnt(" #n ")" ::: "memory")
; template <class Epi, bool ALIGN_EPI = PG8_ALIGN, bool SP2 = PG8_SP2>
; __device__ __forceinline__ void gemm_phase(LAS uchar* lds, const Gemm g, const StaticOrder& S, const Epi& E) {
;     ...
;             PG8_LDB(B0, 0, 0); PG8_LDB(B1, 0, 1); PG8_SCHED; PG8_LDA(At, 0, 0); PG8_STAGE(PG8_SA(1, 1), a1 + hstepA, voffA);
;             PG8_WAIT_V(8); PG8_WAIT_L(0); PG8_BAR; PG8_MMA(0, 0, At, B0); PG8_MMA(0, 1, At, B1); PG8_BAR; PG8_SCHED;
;             PG8_LDA(At, 0, 1); PG8_STAGE(PG8_SB(0, 0), b2, voffB); PG8_STAGE(PG8_SB(0, 1), b2 + hstepB, voffB); PG8_STAGE(PG8_SA(0, 0), a2, voffA);
;             PG8_WAIT_V(8); PG8_WAIT_L(0); PG8_BAR; PG8_MMA(1, 0, At, B0); PG8_MMA(1, 1, At, B1); PG8_BAR; PG8_SCHED;
;             PG8_LDB(B0, 1, 0); PG8_LDB(B1, 1, 1); PG8_SCHED; PG8_LDA(At, 1, 0); PG8_STAGE(PG8_SA(0, 1), a2 + hstepA, voffA);
;             PG8_WAIT_V(8); PG8_WAIT_L(0); PG8_BAR; PG8_MMA(0, 0, At, B0); PG8_MMA(0, 1, At, B1); PG8_BAR; PG8_SCHED;
;             PG8_LDA(At, 1, 1); PG8_STAGE(PG8_SB(1, 0), b3, voffB); PG8_STAGE(PG8_SB(1, 1), b3 + hstepB, voffB); PG8_STAGE(PG8_SA(1, 0), a3, voffA);
;             PG8_WAIT_V(8); PG8_WAIT_L(0); PG8_BAR; PG8_MMA(1, 0, At, B0); PG8_MMA(1, 1, At, B1); PG8_BAR; PG8_SCHED;
	s_setprio 0
	s_add_i32 s39, 0, 0x18000
	v_add_u32_e32 v144, s39, v139
	s_add_i32 s40, 0, 0x1c000
	ds_read_b128 v[164:167], v144
	ds_read_b128 v[168:171], v144 offset:1024
	ds_read_b128 v[172:175], v144 offset:2048
	ds_read_b128 v[176:179], v144 offset:3072
	v_add_u32_e32 v144, s40, v139
	ds_read_b128 v[184:187], v144
	ds_read_b128 v[188:191], v144 offset:1024
	ds_read_b128 v[192:195], v144 offset:2048
	ds_read_b128 v[196:199], v144 offset:3072
	s_add_u32 s12, s18, 0x44000
	s_addc_u32 s13, s19, 0
	s_mov_b32 m0, s25
	v_lshl_add_u64 v[236:237], s[12:13], 0, v[154:155]
	ds_read_b128 v[200:203], v163 offset:32768
	ds_read_b128 v[204:207], v163 offset:33792
	ds_read_b128 v[208:211], v163 offset:34816
	ds_read_b128 v[212:215], v163 offset:35840
	ds_read_b128 v[216:219], v163 offset:36864
	ds_read_b128 v[220:223], v163 offset:37888
	ds_read_b128 v[224:227], v163 offset:38912
	ds_read_b128 v[228:231], v163 offset:39936
	global_load_lds_dwordx4 v[236:237], off
	s_mov_b32 m0, s26
	v_lshl_add_u64 v[236:237], s[12:13], 0, v[132:133]
	global_load_lds_dwordx4 v[236:237], off
	s_setprio 1
	s_waitcnt vmcnt(8) lgkmcnt(0)
	s_barrier
	v_mfma_f32_16x16x32_bf16 v[126:129], v[164:167], v[200:203], v[126:129]
	v_mfma_f32_16x16x32_bf16 v[118:121], v[172:175], v[200:203], v[118:121]
	v_mfma_f32_16x16x32_bf16 v[110:113], v[164:167], v[208:211], v[110:113]
	v_mfma_f32_16x16x32_bf16 v[102:105], v[172:175], v[208:211], v[102:105]
	v_mfma_f32_16x16x32_bf16 v[94:97], v[164:167], v[216:219], v[94:97]
	v_mfma_f32_16x16x32_bf16 v[86:89], v[172:175], v[216:219], v[86:89]
	v_mfma_f32_16x16x32_bf16 v[78:81], v[164:167], v[224:227], v[78:81]
	v_mfma_f32_16x16x32_bf16 v[70:73], v[172:175], v[224:227], v[70:73]
	v_mfma_f32_16x16x32_bf16 v[126:129], v[168:171], v[204:207], v[126:129]
	v_mfma_f32_16x16x32_bf16 v[118:121], v[176:179], v[204:207], v[118:121]
	v_mfma_f32_16x16x32_bf16 v[110:113], v[168:171], v[212:215], v[110:113]
	v_mfma_f32_16x16x32_bf16 v[102:105], v[176:179], v[212:215], v[102:105]
	v_mfma_f32_16x16x32_bf16 v[94:97], v[168:171], v[220:223], v[94:97]
	v_mfma_f32_16x16x32_bf16 v[86:89], v[176:179], v[220:223], v[86:89]
	v_mfma_f32_16x16x32_bf16 v[78:81], v[168:171], v[228:231], v[78:81]
	v_mfma_f32_16x16x32_bf16 v[70:73], v[176:179], v[228:231], v[70:73]
	v_mfma_f32_16x16x32_bf16 v[122:125], v[184:187], v[200:203], v[122:125]
	v_mfma_f32_16x16x32_bf16 v[114:117], v[192:195], v[200:203], v[114:117]
	v_mfma_f32_16x16x32_bf16 v[106:109], v[184:187], v[208:211], v[106:109]
	v_mfma_f32_16x16x32_bf16 v[98:101], v[192:195], v[208:211], v[98:101]
	v_mfma_f32_16x16x32_bf16 v[90:93], v[184:187], v[216:219], v[90:93]
	v_mfma_f32_16x16x32_bf16 v[82:85], v[192:195], v[216:219], v[82:85]
	v_mfma_f32_16x16x32_bf16 v[74:77], v[184:187], v[224:227], v[74:77]
	v_mfma_f32_16x16x32_bf16 v[66:69], v[192:195], v[224:227], v[66:69]
	v_mfma_f32_16x16x32_bf16 v[122:125], v[188:191], v[204:207], v[122:125]
	v_mfma_f32_16x16x32_bf16 v[114:117], v[196:199], v[204:207], v[114:117]
	v_mfma_f32_16x16x32_bf16 v[106:109], v[188:191], v[212:215], v[106:109]
	v_mfma_f32_16x16x32_bf16 v[98:101], v[196:199], v[212:215], v[98:101]
	v_mfma_f32_16x16x32_bf16 v[90:93], v[188:191], v[220:223], v[90:93]
	v_mfma_f32_16x16x32_bf16 v[82:85], v[196:199], v[220:223], v[82:85]
	v_mfma_f32_16x16x32_bf16 v[74:77], v[188:191], v[228:231], v[74:77]
	v_mfma_f32_16x16x32_bf16 v[66:69], v[196:199], v[228:231], v[66:69]
	s_barrier
; #define PG8_STAGE(bufoff, gbase, voff) do { _Pragma("unroll") for (int _i = 0; _i < 2; ++_i) \
;         __builtin_amdgcn_global_load_lds((const unsigned*)((const char*)(gbase) + (voff)[_i]), (LAS unsigned*)(lds + (bufoff) + ldsw + _i * 8192), 16, 0, 0); } while (0)
; #define PG8_LDA(dst, b, h) do { _Pragma("unroll") for (int m = 0; m < 4; ++m) _Pragma("unroll") for (int k = 0; k < 2; ++k) dst[m][k] = *(const LAS bf16x8*)(lds + PG8_SA(b, h) + aoff + m * 2048 + k * 1024); } while (0)
; #define PG8_LDB(dst, b, h) do { _Pragma("unroll") for (int n = 0; n < 2; ++n) _Pragma("unroll") for (int k = 0; k < 2; ++k) dst[n][k] = *(const LAS bf16x8*)(lds + PG8_SB(b, h) + boff + n * 2048 + k * 1024); } while (0)
; #define PG8_MMA(ai, bj, At, Bt) do { __builtin_amdgcn_s_setprio(1); _Pragma("unroll") for (int m = 0; m < 4; ++m) _Pragma("unroll") for (int n = 0; n < 2; ++n) _Pragma("unroll") for (int k = 0; k < 2; ++k) \
;         acc[ai][bj][m][n] = __builtin_amdgcn_mfma_f32_16x16x32_bf16(Bt[n][k], At[m][k], acc[ai][bj][m][n], 0, 0, 0); __builtin_amdgcn_s_setprio(0); } while (0)
; template <class Epi, bool ALIGN_EPI = PG8_ALIGN, bool SP2 = PG8_SP2>
; __device__ __forceinline__ void gemm_phase(LAS uchar* lds, const Gemm g, const StaticOrder& S, const Epi& E) {
;     ...
;             PG8_LDB(B0, 0, 0); PG8_LDB(B1, 0, 1); PG8_SCHED; PG8_LDA(At, 0, 0); PG8_STAGE(PG8_SA(1, 1), a1 + hstepA, voffA);
;             PG8_WAIT_V(8); PG8_WAIT_L(0); PG8_BAR; PG8_MMA(0, 0, At, B0); PG8_MMA(0, 1, At, B1); PG8_BAR; PG8_SCHED;
;             PG8_LDA(At, 0, 1); PG8_STAGE(PG8_SB(0, 0), b2, voffB); PG8_STAGE(PG8_SB(0, 1), b2 + hstepB, voffB); PG8_STAGE(PG8_SA(0, 0), a2, voffA);
;             PG8_WAIT_V(8); PG8_WAIT_L(0); PG8_BAR; PG8_MMA(1, 0, At, B0); PG8_MMA(1, 1, At, B1); PG8_BAR; PG8_SCHED;
;             PG8_LDB(B0, 1, 0); PG8_LDB(B1, 1, 1); PG8_SCHED; PG8_LDA(At, 1, 0); PG8_STAGE(PG8_SA(0, 1), a2 + hstepA, voffA);
;             PG8_WAIT_V(8); PG8_WAIT_L(0); PG8_BAR; PG8_MMA(0, 0, At, B0); PG8_MMA(0, 1, At, B1); PG8_BAR; PG8_SCHED;
;             PG8_LDA(At, 1, 1); PG8_STAGE(PG8_SB(1, 0), b3, voffB); PG8_STAGE(PG8_SB(1, 1), b3 + hstepB, voffB); PG8_STAGE(PG8_SA(1, 0), a3, voffA);
;             PG8_WAIT_V(8); PG8_WAIT_L(0); PG8_BAR; PG8_MMA(1, 0, At, B0); PG8_MMA(1, 1, At, B1); PG8_BAR; PG8_SCHED;
;     ...
;         if constexpr (ALIGN_EPI) { if (wr == 0) PG8_BAR; }
	s_setprio 0
	s_add_i32 s12, s39, s21
	v_lshl_add_u64 v[160:161], v[160:161], 0, s[84:85]
	s_mov_b32 m0, s12
	ds_read_b128 v[200:203], v163 offset:49152
	ds_read_b128 v[204:207], v163 offset:50176
	ds_read_b128 v[208:211], v163 offset:51200
	ds_read_b128 v[212:215], v163 offset:52224
	ds_read_b128 v[216:219], v163 offset:53248
	ds_read_b128 v[220:223], v163 offset:54272
	ds_read_b128 v[224:227], v163 offset:55296
	ds_read_b128 v[228:231], v163 offset:56320
	global_load_lds_dwordx4 v[160:161], off
	s_add_i32 m0, s12, 0x2000
	s_add_u32 s12, s16, 0x44080
	v_lshl_add_u64 v[160:161], v[180:181], 0, s[84:85]
	s_addc_u32 s13, s17, 0
	s_add_i32 s16, s40, s21
	global_load_lds_dwordx4 v[160:161], off
	s_mov_b32 m0, s16
	v_lshl_add_u64 v[160:161], s[12:13], 0, v[134:135]
	global_load_lds_dwordx4 v[160:161], off
	s_add_i32 m0, s16, 0x2000
	v_lshl_add_u64 v[160:161], s[12:13], 0, v[130:131]
	global_load_lds_dwordx4 v[160:161], off
	s_mov_b32 m0, s27
	v_lshl_add_u64 v[160:161], v[232:233], 0, s[84:85]
	global_load_lds_dwordx4 v[160:161], off
	s_mov_b32 m0, s28
	v_lshl_add_u64 v[160:161], v[234:235], 0, s[84:85]
	global_load_lds_dwordx4 v[160:161], off
	s_setprio 1
	s_waitcnt vmcnt(8) lgkmcnt(0)
	s_barrier
	v_mfma_f32_16x16x32_bf16 v[62:65], v[164:167], v[200:203], v[62:65]
	v_mfma_f32_16x16x32_bf16 v[54:57], v[172:175], v[200:203], v[54:57]
	v_mfma_f32_16x16x32_bf16 v[46:49], v[164:167], v[208:211], v[46:49]
	v_mfma_f32_16x16x32_bf16 v[38:41], v[172:175], v[208:211], v[38:41]
	v_mfma_f32_16x16x32_bf16 v[30:33], v[164:167], v[216:219], v[30:33]
	v_mfma_f32_16x16x32_bf16 v[22:25], v[172:175], v[216:219], v[22:25]
	v_mfma_f32_16x16x32_bf16 v[14:17], v[164:167], v[224:227], v[14:17]
	v_mfma_f32_16x16x32_bf16 v[6:9], v[172:175], v[224:227], v[6:9]
	v_mfma_f32_16x16x32_bf16 v[62:65], v[168:171], v[204:207], v[62:65]
	v_mfma_f32_16x16x32_bf16 v[54:57], v[176:179], v[204:207], v[54:57]
	v_mfma_f32_16x16x32_bf16 v[46:49], v[168:171], v[212:215], v[46:49]
	v_mfma_f32_16x16x32_bf16 v[38:41], v[176:179], v[212:215], v[38:41]
	v_mfma_f32_16x16x32_bf16 v[30:33], v[168:171], v[220:223], v[30:33]
	v_mfma_f32_16x16x32_bf16 v[22:25], v[176:179], v[220:223], v[22:25]
	v_mfma_f32_16x16x32_bf16 v[14:17], v[168:171], v[228:231], v[14:17]
	v_mfma_f32_16x16x32_bf16 v[6:9], v[176:179], v[228:231], v[6:9]
	v_mfma_f32_16x16x32_bf16 v[58:61], v[184:187], v[200:203], v[58:61]
	v_mfma_f32_16x16x32_bf16 v[50:53], v[192:195], v[200:203], v[50:53]
	v_mfma_f32_16x16x32_bf16 v[42:45], v[184:187], v[208:211], v[42:45]
	v_mfma_f32_16x16x32_bf16 v[34:37], v[192:195], v[208:211], v[34:37]
	v_mfma_f32_16x16x32_bf16 v[26:29], v[184:187], v[216:219], v[26:29]
	v_mfma_f32_16x16x32_bf16 v[18:21], v[192:195], v[216:219], v[18:21]
	v_mfma_f32_16x16x32_bf16 v[10:13], v[184:187], v[224:227], v[10:13]
	v_mfma_f32_16x16x32_bf16 v[2:5], v[192:195], v[224:227], v[2:5]
	v_mfma_f32_16x16x32_bf16 v[58:61], v[188:191], v[204:207], v[58:61]
	v_mfma_f32_16x16x32_bf16 v[50:53], v[196:199], v[204:207], v[50:53]
	v_mfma_f32_16x16x32_bf16 v[42:45], v[188:191], v[212:215], v[42:45]
	v_mfma_f32_16x16x32_bf16 v[34:37], v[196:199], v[212:215], v[34:37]
	v_mfma_f32_16x16x32_bf16 v[26:29], v[188:191], v[220:223], v[26:29]
	v_mfma_f32_16x16x32_bf16 v[18:21], v[196:199], v[220:223], v[18:21]
	v_mfma_f32_16x16x32_bf16 v[10:13], v[188:191], v[228:231], v[10:13]
	v_mfma_f32_16x16x32_bf16 v[2:5], v[196:199], v[228:231], v[2:5]
	s_barrier
	s_setprio 0
	s_add_i32 s38, s38, 2
	s_add_u32 s36, s36, 0x100
	s_addc_u32 s37, s37, 0
	s_cmp_gt_u32 s38, 13
	s_mov_b64 s[12:13], s[14:15]
	s_cbranch_scc0 .LBB0_1050
	s_and_b64 vcc, exec, s[8:9]
	s_cbranch_vccz .LBB0_1053
	s_barrier

; #define PG8_STAGE(bufoff, gbase, voff) do { _Pragma("unroll") for (int _i = 0; _i < 2; ++_i) \
;         __builtin_amdgcn_global_load_lds((const unsigned*)((const char*)(gbase) + (voff)[_i]), (LAS unsigned*)(lds + (bufoff) + ldsw + _i * 8192), 16, 0, 0); } while (0)
; #define PG8_LDA(dst, b, h) do { _Pragma("unroll") for (int m = 0; m < 4; ++m) _Pragma("unroll") for (int k = 0; k < 2; ++k) dst[m][k] = *(const LAS bf16x8*)(lds + PG8_SA(b, h) + aoff + m * 2048 + k * 1024); } while (0)
; #define PG8_LDB(dst, b, h) do { _Pragma("unroll") for (int n = 0; n < 2; ++n) _Pragma("unroll") for (int k = 0; k < 2; ++k) dst[n][k] = *(const LAS bf16x8*)(lds + PG8_SB(b, h) + boff + n * 2048 + k * 1024); } while (0)
; #define PG8_MMA(ai, bj, At, Bt) do { __builtin_amdgcn_s_setprio(1); _Pragma("unroll") for (int m = 0; m < 4; ++m) _Pragma("unroll") for (int n = 0; n < 2; ++n) _Pragma("unroll") for (int k = 0; k < 2; ++k) \
;         acc[ai][bj][m][n] = __builtin_amdgcn_mfma_f32_16x16x32_bf16(Bt[n][k], At[m][k], acc[ai][bj][m][n], 0, 0, 0); __builtin_amdgcn_s_setprio(0); } while (0)
; #define PG8_WAIT_V(n) asm volatile("s_waitcnt vmcnt(" #n ")" ::: "memory")
; template <class Epi, bool ALIGN_EPI = PG8_ALIGN, bool SP2 = PG8_SP2>
; __device__ __forceinline__ void gemm_phase(LAS uchar* lds, const Gemm g, const StaticOrder& S, const Epi& E) {
;     ...
;             PG8_LDB(B0, 0, 0); PG8_LDB(B1, 0, 1); PG8_SCHED; PG8_LDA(At, 0, 0); PG8_STAGE(PG8_SA(1, 1), a1 + hstepA, voffA);
;             PG8_WAIT_V(8); PG8_WAIT_L(0); PG8_BAR; PG8_MMA(0, 0, At, B0); PG8_MMA(0, 1, At, B1); PG8_BAR; PG8_SCHED;
;             PG8_LDA(At, 0, 1); PG8_STAGE(PG8_SB(0, 0), b2, voffB); PG8_STAGE(PG8_SB(0, 1), b2 + hstepB, voffB); PG8_STAGE(PG8_SA(0, 0), a2, voffA);
;             PG8_WAIT_V(8); PG8_WAIT_L(0); PG8_BAR; PG8_MMA(1, 0, At, B0); PG8_MMA(1, 1, At, B1); PG8_BAR; PG8_SCHED;
;             PG8_LDB(B0, 1, 0); PG8_LDB(B1, 1, 1); PG8_SCHED; PG8_LDA(At, 1, 0); PG8_STAGE(PG8_SA(0, 1), a2 + hstepA, voffA);
;             PG8_WAIT_V(8); PG8_WAIT_L(0); PG8_BAR; PG8_MMA(0, 0, At, B0); PG8_MMA(0, 1, At, B1); PG8_BAR; PG8_SCHED;
;             PG8_LDA(At, 1, 1); PG8_STAGE(PG8_SB(1, 0), b3, voffB); PG8_STAGE(PG8_SB(1, 1), b3 + hstepB, voffB); PG8_STAGE(PG8_SA(1, 0), a3, voffA);
;             PG8_WAIT_V(8); PG8_WAIT_L(0); PG8_BAR; PG8_MMA(1, 0, At, B0); PG8_MMA(1, 1, At, B1); PG8_BAR; PG8_SCHED;
.LBB0_1143:
	s_add_u32 s16, s14, 0x100
	s_addc_u32 s17, s15, 0
	s_add_i32 s41, 0, 0x10000
	s_cmp_eq_u32 s40, 40
	s_cselect_b32 s21, s5, s17
	s_cselect_b32 s20, s4, s16
	v_add_u32_e32 v144, s41, v139
	s_cselect_b32 s19, s13, s39
	s_cselect_b32 s18, s12, s38
	s_add_i32 s42, 0, 0x14000
	ds_read_b128 v[160:163], v144
	ds_read_b128 v[166:169], v144 offset:1024
	ds_read_b128 v[170:173], v144 offset:2048
	ds_read_b128 v[174:177], v144 offset:3072
	v_add_u32_e32 v144, s42, v139
	ds_read_b128 v[178:181], v144
	ds_read_b128 v[184:187], v144 offset:1024
	ds_read_b128 v[188:191], v144 offset:2048
	ds_read_b128 v[192:195], v144 offset:3072
	v_lshl_add_u64 v[228:229], s[14:15], 0, v[156:157]
	s_add_i32 m0, s25, 0xc000
	ds_read_b128 v[196:199], v165
	ds_read_b128 v[200:203], v165 offset:1024
	ds_read_b128 v[204:207], v165 offset:2048
	ds_read_b128 v[208:211], v165 offset:3072
	ds_read_b128 v[212:215], v165 offset:4096
	ds_read_b128 v[216:219], v165 offset:5120
	ds_read_b128 v[220:223], v165 offset:6144
	ds_read_b128 v[224:227], v165 offset:7168
	global_load_lds_dwordx4 v[228:229], off
	s_add_i32 m0, s25, 0xe000
	v_lshl_add_u64 v[228:229], s[14:15], 0, v[158:159]
	global_load_lds_dwordx4 v[228:229], off
	s_nop 0
	s_setprio 1
	s_waitcnt vmcnt(8) lgkmcnt(0)
	s_barrier
	v_mfma_f32_16x16x32_bf16 v[126:129], v[160:163], v[196:199], v[126:129]
	v_mfma_f32_16x16x32_bf16 v[122:125], v[170:173], v[196:199], v[122:125]
	v_mfma_f32_16x16x32_bf16 v[118:121], v[160:163], v[204:207], v[118:121]
	v_mfma_f32_16x16x32_bf16 v[110:113], v[170:173], v[204:207], v[110:113]
	v_mfma_f32_16x16x32_bf16 v[102:105], v[160:163], v[212:215], v[102:105]
	v_mfma_f32_16x16x32_bf16 v[94:97], v[170:173], v[212:215], v[94:97]
	v_mfma_f32_16x16x32_bf16 v[86:89], v[160:163], v[220:223], v[86:89]
	v_mfma_f32_16x16x32_bf16 v[78:81], v[170:173], v[220:223], v[78:81]
	v_mfma_f32_16x16x32_bf16 v[126:129], v[166:169], v[200:203], v[126:129]
	v_mfma_f32_16x16x32_bf16 v[122:125], v[174:177], v[200:203], v[122:125]
	v_mfma_f32_16x16x32_bf16 v[118:121], v[166:169], v[208:211], v[118:121]
	v_mfma_f32_16x16x32_bf16 v[110:113], v[174:177], v[208:211], v[110:113]
	v_mfma_f32_16x16x32_bf16 v[102:105], v[166:169], v[216:219], v[102:105]
	v_mfma_f32_16x16x32_bf16 v[94:97], v[174:177], v[216:219], v[94:97]
	v_mfma_f32_16x16x32_bf16 v[86:89], v[166:169], v[224:227], v[86:89]
	v_mfma_f32_16x16x32_bf16 v[78:81], v[174:177], v[224:227], v[78:81]
	v_mfma_f32_16x16x32_bf16 v[114:117], v[178:181], v[196:199], v[114:117]
	v_mfma_f32_16x16x32_bf16 v[106:109], v[188:191], v[196:199], v[106:109]
	v_mfma_f32_16x16x32_bf16 v[98:101], v[178:181], v[204:207], v[98:101]
	v_mfma_f32_16x16x32_bf16 v[90:93], v[188:191], v[204:207], v[90:93]
	v_mfma_f32_16x16x32_bf16 v[82:85], v[178:181], v[212:215], v[82:85]
	v_mfma_f32_16x16x32_bf16 v[74:77], v[188:191], v[212:215], v[74:77]
	v_mfma_f32_16x16x32_bf16 v[70:73], v[178:181], v[220:223], v[70:73]
	v_mfma_f32_16x16x32_bf16 v[66:69], v[188:191], v[220:223], v[66:69]
	v_mfma_f32_16x16x32_bf16 v[114:117], v[184:187], v[200:203], v[114:117]
	v_mfma_f32_16x16x32_bf16 v[106:109], v[192:195], v[200:203], v[106:109]
	v_mfma_f32_16x16x32_bf16 v[98:101], v[184:187], v[208:211], v[98:101]
	v_mfma_f32_16x16x32_bf16 v[90:93], v[192:195], v[208:211], v[90:93]
	v_mfma_f32_16x16x32_bf16 v[82:85], v[184:187], v[216:219], v[82:85]
	v_mfma_f32_16x16x32_bf16 v[74:77], v[192:195], v[216:219], v[74:77]
	v_mfma_f32_16x16x32_bf16 v[70:73], v[184:187], v[224:227], v[70:73]
	v_mfma_f32_16x16x32_bf16 v[66:69], v[192:195], v[224:227], v[66:69]
	s_barrier
	s_setprio 0
	s_add_i32 s14, s41, s24
	v_lshl_add_u64 v[228:229], s[18:19], 0, v[132:133]
	s_mov_b32 m0, s14
	ds_read_b128 v[196:199], v165 offset:16384
	ds_read_b128 v[200:203], v165 offset:17408
	ds_read_b128 v[204:207], v165 offset:18432
	ds_read_b128 v[208:211], v165 offset:19456
	ds_read_b128 v[212:215], v165 offset:20480
	ds_read_b128 v[216:219], v165 offset:21504
	ds_read_b128 v[220:223], v165 offset:22528
	ds_read_b128 v[224:227], v165 offset:23552
	global_load_lds_dwordx4 v[228:229], off
	s_add_i32 m0, s14, 0x2000
	s_add_u32 s14, s18, 0xb0000
	v_lshl_add_u64 v[230:231], s[18:19], 0, v[154:155]
	s_addc_u32 s15, s19, 0
	s_add_i32 s41, s42, s24
	global_load_lds_dwordx4 v[230:231], off
	v_lshl_add_u64 v[232:233], s[14:15], 0, v[132:133]
	s_mov_b32 m0, s41
	global_load_lds_dwordx4 v[232:233], off
	s_add_i32 m0, s41, 0x2000
	v_lshl_add_u64 v[232:233], s[14:15], 0, v[154:155]
	global_load_lds_dwordx4 v[232:233], off
	s_mov_b32 m0, s25
	v_lshl_add_u64 v[232:233], s[20:21], 0, v[130:131]
	global_load_lds_dwordx4 v[232:233], off
	s_mov_b32 m0, s26
	v_lshl_add_u64 v[234:235], s[20:21], 0, v[134:135]
	global_load_lds_dwordx4 v[234:235], off
	s_setprio 1
	s_waitcnt vmcnt(8) lgkmcnt(0)
	s_barrier
; #define PG8_STAGE(bufoff, gbase, voff) do { _Pragma("unroll") for (int _i = 0; _i < 2; ++_i) \
;         __builtin_amdgcn_global_load_lds((const unsigned*)((const char*)(gbase) + (voff)[_i]), (LAS unsigned*)(lds + (bufoff) + ldsw + _i * 8192), 16, 0, 0); } while (0)
; #define PG8_LDA(dst, b, h) do { _Pragma("unroll") for (int m = 0; m < 4; ++m) _Pragma("unroll") for (int k = 0; k < 2; ++k) dst[m][k] = *(const LAS bf16x8*)(lds + PG8_SA(b, h) + aoff + m * 2048 + k * 1024); } while (0)
; #define PG8_LDB(dst, b, h) do { _Pragma("unroll") for (int n = 0; n < 2; ++n) _Pragma("unroll") for (int k = 0; k < 2; ++k) dst[n][k] = *(const LAS bf16x8*)(lds + PG8_SB(b, h) + boff + n * 2048 + k * 1024); } while (0)
; #define PG8_MMA(ai, bj, At, Bt) do { __builtin_amdgcn_s_setprio(1); _Pragma("unroll") for (int m = 0; m < 4; ++m) _Pragma("unroll") for (int n = 0; n < 2; ++n) _Pragma("unroll") for (int k = 0; k < 2; ++k) \
;         acc[ai][bj][m][n] = __builtin_amdgcn_mfma_f32_16x16x32_bf16(Bt[n][k], At[m][k], acc[ai][bj][m][n], 0, 0, 0); __builtin_amdgcn_s_setprio(0); } while (0)
; #define PG8_WAIT_V(n) asm volatile("s_waitcnt vmcnt(" #n ")" ::: "memory")
; template <class Epi, bool ALIGN_EPI = PG8_ALIGN, bool SP2 = PG8_SP2>
; __device__ __forceinline__ void gemm_phase(LAS uchar* lds, const Gemm g, const StaticOrder& S, const Epi& E) {
;     ...
;             PG8_LDB(B0, 0, 0); PG8_LDB(B1, 0, 1); PG8_SCHED; PG8_LDA(At, 0, 0); PG8_STAGE(PG8_SA(1, 1), a1 + hstepA, voffA);
;             PG8_WAIT_V(8); PG8_WAIT_L(0); PG8_BAR; PG8_MMA(0, 0, At, B0); PG8_MMA(0, 1, At, B1); PG8_BAR; PG8_SCHED;
;             PG8_LDA(At, 0, 1); PG8_STAGE(PG8_SB(0, 0), b2, voffB); PG8_STAGE(PG8_SB(0, 1), b2 + hstepB, voffB); PG8_STAGE(PG8_SA(0, 0), a2, voffA);
;             PG8_WAIT_V(8); PG8_WAIT_L(0); PG8_BAR; PG8_MMA(1, 0, At, B0); PG8_MMA(1, 1, At, B1); PG8_BAR; PG8_SCHED;
;             PG8_LDB(B0, 1, 0); PG8_LDB(B1, 1, 1); PG8_SCHED; PG8_LDA(At, 1, 0); PG8_STAGE(PG8_SA(0, 1), a2 + hstepA, voffA);
;             PG8_WAIT_V(8); PG8_WAIT_L(0); PG8_BAR; PG8_MMA(0, 0, At, B0); PG8_MMA(0, 1, At, B1); PG8_BAR; PG8_SCHED;
;             PG8_LDA(At, 1, 1); PG8_STAGE(PG8_SB(1, 0), b3, voffB); PG8_STAGE(PG8_SB(1, 1), b3 + hstepB, voffB); PG8_STAGE(PG8_SA(1, 0), a3, voffA);
;             PG8_WAIT_V(8); PG8_WAIT_L(0); PG8_BAR; PG8_MMA(1, 0, At, B0); PG8_MMA(1, 1, At, B1); PG8_BAR; PG8_SCHED;
	v_mfma_f32_16x16x32_bf16 v[62:65], v[160:163], v[196:199], v[62:65]
	v_mfma_f32_16x16x32_bf16 v[58:61], v[170:173], v[196:199], v[58:61]
	v_mfma_f32_16x16x32_bf16 v[54:57], v[160:163], v[204:207], v[54:57]
	v_mfma_f32_16x16x32_bf16 v[46:49], v[170:173], v[204:207], v[46:49]
	v_mfma_f32_16x16x32_bf16 v[38:41], v[160:163], v[212:215], v[38:41]
	v_mfma_f32_16x16x32_bf16 v[30:33], v[170:173], v[212:215], v[30:33]
	v_mfma_f32_16x16x32_bf16 v[22:25], v[160:163], v[220:223], v[22:25]
	v_mfma_f32_16x16x32_bf16 v[14:17], v[170:173], v[220:223], v[14:17]
	v_mfma_f32_16x16x32_bf16 v[62:65], v[166:169], v[200:203], v[62:65]
	v_mfma_f32_16x16x32_bf16 v[58:61], v[174:177], v[200:203], v[58:61]
	v_mfma_f32_16x16x32_bf16 v[54:57], v[166:169], v[208:211], v[54:57]
	v_mfma_f32_16x16x32_bf16 v[46:49], v[174:177], v[208:211], v[46:49]
	v_mfma_f32_16x16x32_bf16 v[38:41], v[166:169], v[216:219], v[38:41]
	v_mfma_f32_16x16x32_bf16 v[30:33], v[174:177], v[216:219], v[30:33]
	v_mfma_f32_16x16x32_bf16 v[22:25], v[166:169], v[224:227], v[22:25]
	v_mfma_f32_16x16x32_bf16 v[14:17], v[174:177], v[224:227], v[14:17]
	v_mfma_f32_16x16x32_bf16 v[50:53], v[178:181], v[196:199], v[50:53]
	v_mfma_f32_16x16x32_bf16 v[42:45], v[188:191], v[196:199], v[42:45]
	v_mfma_f32_16x16x32_bf16 v[34:37], v[178:181], v[204:207], v[34:37]
	v_mfma_f32_16x16x32_bf16 v[26:29], v[188:191], v[204:207], v[26:29]
	v_mfma_f32_16x16x32_bf16 v[18:21], v[178:181], v[212:215], v[18:21]
	v_mfma_f32_16x16x32_bf16 v[10:13], v[188:191], v[212:215], v[10:13]
	v_mfma_f32_16x16x32_bf16 v[6:9], v[178:181], v[220:223], v[6:9]
	v_mfma_f32_16x16x32_bf16 v[2:5], v[188:191], v[220:223], v[2:5]
	v_mfma_f32_16x16x32_bf16 v[50:53], v[184:187], v[200:203], v[50:53]
	v_mfma_f32_16x16x32_bf16 v[42:45], v[192:195], v[200:203], v[42:45]
	v_mfma_f32_16x16x32_bf16 v[34:37], v[184:187], v[208:211], v[34:37]
	v_mfma_f32_16x16x32_bf16 v[26:29], v[192:195], v[208:211], v[26:29]
	v_mfma_f32_16x16x32_bf16 v[18:21], v[184:187], v[216:219], v[18:21]
	v_mfma_f32_16x16x32_bf16 v[10:13], v[192:195], v[216:219], v[10:13]
	v_mfma_f32_16x16x32_bf16 v[6:9], v[184:187], v[224:227], v[6:9]
	v_mfma_f32_16x16x32_bf16 v[2:5], v[192:195], v[224:227], v[2:5]
	s_barrier
	s_setprio 0
	s_add_i32 s41, 0, 0x18000
	v_add_u32_e32 v144, s41, v139
	s_add_i32 s42, 0, 0x1c000
	ds_read_b128 v[160:163], v144
	ds_read_b128 v[166:169], v144 offset:1024
	ds_read_b128 v[170:173], v144 offset:2048
	ds_read_b128 v[174:177], v144 offset:3072
	v_add_u32_e32 v144, s42, v139
	ds_read_b128 v[178:181], v144
	ds_read_b128 v[184:187], v144 offset:1024
	ds_read_b128 v[188:191], v144 offset:2048
	ds_read_b128 v[192:195], v144 offset:3072
	s_add_u32 s14, s20, 0xb0000
	s_addc_u32 s15, s21, 0
	s_mov_b32 m0, s27
	v_lshl_add_u64 v[236:237], s[14:15], 0, v[130:131]
	ds_read_b128 v[196:199], v165 offset:32768
	ds_read_b128 v[200:203], v165 offset:33792
	ds_read_b128 v[204:207], v165 offset:34816
	ds_read_b128 v[208:211], v165 offset:35840
	ds_read_b128 v[212:215], v165 offset:36864
	ds_read_b128 v[216:219], v165 offset:37888
	ds_read_b128 v[220:223], v165 offset:38912
	ds_read_b128 v[224:227], v165 offset:39936
	global_load_lds_dwordx4 v[236:237], off
	s_mov_b32 m0, s28
	v_lshl_add_u64 v[236:237], s[14:15], 0, v[134:135]
	global_load_lds_dwordx4 v[236:237], off
	s_setprio 1
	s_waitcnt vmcnt(8) lgkmcnt(0)
	s_barrier
	v_mfma_f32_16x16x32_bf16 v[126:129], v[160:163], v[196:199], v[126:129]
	v_mfma_f32_16x16x32_bf16 v[122:125], v[170:173], v[196:199], v[122:125]
	v_mfma_f32_16x16x32_bf16 v[118:121], v[160:163], v[204:207], v[118:121]
	v_mfma_f32_16x16x32_bf16 v[110:113], v[170:173], v[204:207], v[110:113]
	v_mfma_f32_16x16x32_bf16 v[102:105], v[160:163], v[212:215], v[102:105]
	v_mfma_f32_16x16x32_bf16 v[94:97], v[170:173], v[212:215], v[94:97]
	v_mfma_f32_16x16x32_bf16 v[86:89], v[160:163], v[220:223], v[86:89]
	v_mfma_f32_16x16x32_bf16 v[78:81], v[170:173], v[220:223], v[78:81]
	v_mfma_f32_16x16x32_bf16 v[126:129], v[166:169], v[200:203], v[126:129]
	v_mfma_f32_16x16x32_bf16 v[122:125], v[174:177], v[200:203], v[122:125]
	v_mfma_f32_16x16x32_bf16 v[118:121], v[166:169], v[208:211], v[118:121]
	v_mfma_f32_16x16x32_bf16 v[110:113], v[174:177], v[208:211], v[110:113]
	v_mfma_f32_16x16x32_bf16 v[102:105], v[166:169], v[216:219], v[102:105]
	v_mfma_f32_16x16x32_bf16 v[94:97], v[174:177], v[216:219], v[94:97]
	v_mfma_f32_16x16x32_bf16 v[86:89], v[166:169], v[224:227], v[86:89]
	v_mfma_f32_16x16x32_bf16 v[78:81], v[174:177], v[224:227], v[78:81]
	v_mfma_f32_16x16x32_bf16 v[114:117], v[178:181], v[196:199], v[114:117]
	v_mfma_f32_16x16x32_bf16 v[106:109], v[188:191], v[196:199], v[106:109]
	v_mfma_f32_16x16x32_bf16 v[98:101], v[178:181], v[204:207], v[98:101]
	v_mfma_f32_16x16x32_bf16 v[90:93], v[188:191], v[204:207], v[90:93]
	v_mfma_f32_16x16x32_bf16 v[82:85], v[178:181], v[212:215], v[82:85]
	v_mfma_f32_16x16x32_bf16 v[74:77], v[188:191], v[212:215], v[74:77]
	v_mfma_f32_16x16x32_bf16 v[70:73], v[178:181], v[220:223], v[70:73]
	v_mfma_f32_16x16x32_bf16 v[66:69], v[188:191], v[220:223], v[66:69]
	v_mfma_f32_16x16x32_bf16 v[114:117], v[184:187], v[200:203], v[114:117]
	v_mfma_f32_16x16x32_bf16 v[106:109], v[192:195], v[200:203], v[106:109]
	v_mfma_f32_16x16x32_bf16 v[98:101], v[184:187], v[208:211], v[98:101]
	v_mfma_f32_16x16x32_bf16 v[90:93], v[192:195], v[208:211], v[90:93]
	v_mfma_f32_16x16x32_bf16 v[82:85], v[184:187], v[216:219], v[82:85]
	v_mfma_f32_16x16x32_bf16 v[74:77], v[192:195], v[216:219], v[74:77]
	v_mfma_f32_16x16x32_bf16 v[70:73], v[184:187], v[224:227], v[70:73]
	v_mfma_f32_16x16x32_bf16 v[66:69], v[192:195], v[224:227], v[66:69]
	s_barrier
; #define PG8_STAGE(bufoff, gbase, voff) do { _Pragma("unroll") for (int _i = 0; _i < 2; ++_i) \
;         __builtin_amdgcn_global_load_lds((const unsigned*)((const char*)(gbase) + (voff)[_i]), (LAS unsigned*)(lds + (bufoff) + ldsw + _i * 8192), 16, 0, 0); } while (0)
; #define PG8_LDA(dst, b, h) do { _Pragma("unroll") for (int m = 0; m < 4; ++m) _Pragma("unroll") for (int k = 0; k < 2; ++k) dst[m][k] = *(const LAS bf16x8*)(lds + PG8_SA(b, h) + aoff + m * 2048 + k * 1024); } while (0)
; #define PG8_LDB(dst, b, h) do { _Pragma("unroll") for (int n = 0; n < 2; ++n) _Pragma("unroll") for (int k = 0; k < 2; ++k) dst[n][k] = *(const LAS bf16x8*)(lds + PG8_SB(b, h) + boff + n * 2048 + k * 1024); } while (0)
; #define PG8_MMA(ai, bj, At, Bt) do { __builtin_amdgcn_s_setprio(1); _Pragma("unroll") for (int m = 0; m < 4; ++m) _Pragma("unroll") for (int n = 0; n < 2; ++n) _Pragma("unroll") for (int k = 0; k < 2; ++k) \
;         acc[ai][bj][m][n] = __builtin_amdgcn_mfma_f32_16x16x32_bf16(Bt[n][k], At[m][k], acc[ai][bj][m][n], 0, 0, 0); __builtin_amdgcn_s_setprio(0); } while (0)
; template <class Epi, bool ALIGN_EPI = PG8_ALIGN, bool SP2 = PG8_SP2>
; __device__ __forceinline__ void gemm_phase(LAS uchar* lds, const Gemm g, const StaticOrder& S, const Epi& E) {
;     ...
;             PG8_LDB(B0, 0, 0); PG8_LDB(B1, 0, 1); PG8_SCHED; PG8_LDA(At, 0, 0); PG8_STAGE(PG8_SA(1, 1), a1 + hstepA, voffA);
;             PG8_WAIT_V(8); PG8_WAIT_L(0); PG8_BAR; PG8_MMA(0, 0, At, B0); PG8_MMA(0, 1, At, B1); PG8_BAR; PG8_SCHED;
;             PG8_LDA(At, 0, 1); PG8_STAGE(PG8_SB(0, 0), b2, voffB); PG8_STAGE(PG8_SB(0, 1), b2 + hstepB, voffB); PG8_STAGE(PG8_SA(0, 0), a2, voffA);
;             PG8_WAIT_V(8); PG8_WAIT_L(0); PG8_BAR; PG8_MMA(1, 0, At, B0); PG8_MMA(1, 1, At, B1); PG8_BAR; PG8_SCHED;
;             PG8_LDB(B0, 1, 0); PG8_LDB(B1, 1, 1); PG8_SCHED; PG8_LDA(At, 1, 0); PG8_STAGE(PG8_SA(0, 1), a2 + hstepA, voffA);
;             PG8_WAIT_V(8); PG8_WAIT_L(0); PG8_BAR; PG8_MMA(0, 0, At, B0); PG8_MMA(0, 1, At, B1); PG8_BAR; PG8_SCHED;
;             PG8_LDA(At, 1, 1); PG8_STAGE(PG8_SB(1, 0), b3, voffB); PG8_STAGE(PG8_SB(1, 1), b3 + hstepB, voffB); PG8_STAGE(PG8_SA(1, 0), a3, voffA);
;             PG8_WAIT_V(8); PG8_WAIT_L(0); PG8_BAR; PG8_MMA(1, 0, At, B0); PG8_MMA(1, 1, At, B1); PG8_BAR; PG8_SCHED;
;     ...
;         if constexpr (ALIGN_EPI) { if (wr == 0) PG8_BAR; }
	s_setprio 0
	s_add_i32 s14, s41, s24
	v_lshl_add_u64 v[228:229], v[228:229], 0, s[84:85]
	s_mov_b32 m0, s14
	ds_read_b128 v[196:199], v165 offset:49152
	ds_read_b128 v[200:203], v165 offset:50176
	ds_read_b128 v[204:207], v165 offset:51200
	ds_read_b128 v[208:211], v165 offset:52224
	ds_read_b128 v[212:215], v165 offset:53248
	ds_read_b128 v[216:219], v165 offset:54272
	ds_read_b128 v[220:223], v165 offset:55296
	ds_read_b128 v[224:227], v165 offset:56320
	global_load_lds_dwordx4 v[228:229], off
	s_add_i32 m0, s14, 0x2000
	s_add_u32 s14, s18, 0xb0080
	v_lshl_add_u64 v[228:229], v[230:231], 0, s[84:85]
	s_addc_u32 s15, s19, 0
	s_add_i32 s18, s42, s24
	global_load_lds_dwordx4 v[228:229], off
	s_mov_b32 m0, s18
	v_lshl_add_u64 v[228:229], s[14:15], 0, v[132:133]
	global_load_lds_dwordx4 v[228:229], off
	s_add_i32 m0, s18, 0x2000
	v_lshl_add_u64 v[228:229], s[14:15], 0, v[154:155]
	global_load_lds_dwordx4 v[228:229], off
	s_mov_b32 m0, s29
	v_lshl_add_u64 v[228:229], v[232:233], 0, s[84:85]
	global_load_lds_dwordx4 v[228:229], off
	s_mov_b32 m0, s30
	v_lshl_add_u64 v[228:229], v[234:235], 0, s[84:85]
	global_load_lds_dwordx4 v[228:229], off
	s_setprio 1
	s_waitcnt vmcnt(8) lgkmcnt(0)
	s_barrier
	v_mfma_f32_16x16x32_bf16 v[62:65], v[160:163], v[196:199], v[62:65]
	v_mfma_f32_16x16x32_bf16 v[58:61], v[170:173], v[196:199], v[58:61]
	v_mfma_f32_16x16x32_bf16 v[54:57], v[160:163], v[204:207], v[54:57]
	v_mfma_f32_16x16x32_bf16 v[46:49], v[170:173], v[204:207], v[46:49]
	v_mfma_f32_16x16x32_bf16 v[38:41], v[160:163], v[212:215], v[38:41]
	v_mfma_f32_16x16x32_bf16 v[30:33], v[170:173], v[212:215], v[30:33]
	v_mfma_f32_16x16x32_bf16 v[22:25], v[160:163], v[220:223], v[22:25]
	v_mfma_f32_16x16x32_bf16 v[14:17], v[170:173], v[220:223], v[14:17]
	v_mfma_f32_16x16x32_bf16 v[62:65], v[166:169], v[200:203], v[62:65]
	v_mfma_f32_16x16x32_bf16 v[58:61], v[174:177], v[200:203], v[58:61]
	v_mfma_f32_16x16x32_bf16 v[54:57], v[166:169], v[208:211], v[54:57]
	v_mfma_f32_16x16x32_bf16 v[46:49], v[174:177], v[208:211], v[46:49]
	v_mfma_f32_16x16x32_bf16 v[38:41], v[166:169], v[216:219], v[38:41]
	v_mfma_f32_16x16x32_bf16 v[30:33], v[174:177], v[216:219], v[30:33]
	v_mfma_f32_16x16x32_bf16 v[22:25], v[166:169], v[224:227], v[22:25]
	v_mfma_f32_16x16x32_bf16 v[14:17], v[174:177], v[224:227], v[14:17]
	v_mfma_f32_16x16x32_bf16 v[50:53], v[178:181], v[196:199], v[50:53]
	v_mfma_f32_16x16x32_bf16 v[42:45], v[188:191], v[196:199], v[42:45]
	v_mfma_f32_16x16x32_bf16 v[34:37], v[178:181], v[204:207], v[34:37]
	v_mfma_f32_16x16x32_bf16 v[26:29], v[188:191], v[204:207], v[26:29]
	v_mfma_f32_16x16x32_bf16 v[18:21], v[178:181], v[212:215], v[18:21]
	v_mfma_f32_16x16x32_bf16 v[10:13], v[188:191], v[212:215], v[10:13]
	v_mfma_f32_16x16x32_bf16 v[6:9], v[178:181], v[220:223], v[6:9]
	v_mfma_f32_16x16x32_bf16 v[2:5], v[188:191], v[220:223], v[2:5]
	v_mfma_f32_16x16x32_bf16 v[50:53], v[184:187], v[200:203], v[50:53]
	v_mfma_f32_16x16x32_bf16 v[42:45], v[192:195], v[200:203], v[42:45]
	v_mfma_f32_16x16x32_bf16 v[34:37], v[184:187], v[208:211], v[34:37]
	v_mfma_f32_16x16x32_bf16 v[26:29], v[192:195], v[208:211], v[26:29]
	v_mfma_f32_16x16x32_bf16 v[18:21], v[184:187], v[216:219], v[18:21]
	v_mfma_f32_16x16x32_bf16 v[10:13], v[192:195], v[216:219], v[10:13]
	v_mfma_f32_16x16x32_bf16 v[6:9], v[184:187], v[224:227], v[6:9]
	v_mfma_f32_16x16x32_bf16 v[2:5], v[192:195], v[224:227], v[2:5]
	s_barrier
	s_setprio 0
	s_add_i32 s40, s40, 2
	s_add_u32 s38, s38, 0x100
	s_addc_u32 s39, s39, 0
	s_cmp_gt_u32 s40, 41
	s_mov_b64 s[14:15], s[16:17]
	s_cbranch_scc0 .LBB0_1143
	s_and_b64 vcc, exec, s[10:11]
	s_cbranch_vccz .LBB0_1146
	s_barrier
